# all packed f32 VALU ops (v_pk_mul/add/fma_f32) split into their two single-lane ops, kernel-wide
# speedup vs baseline: 1.0039x; 1.0039x over previous
.LBB0_66:
	v_ashrrev_i32_e32 v1, 31, v0
	v_lshlrev_b64 v[20:21], 6, v[0:1]
	s_waitcnt vmcnt(12)
	v_lshl_add_u64 v[32:33], s[12:13], 0, v[20:21]
	global_load_dwordx4 v[20:23], v[32:33], off offset:48
	global_load_dwordx4 v[24:27], v[32:33], off offset:32
	global_load_dwordx4 v[28:31], v[32:33], off offset:16
	s_nop 0
	global_load_dwordx4 v[32:35], v[32:33], off
	v_add_u32_e32 v72, 1, v0
	v_ashrrev_i32_e32 v73, 31, v72
	v_lshlrev_b64 v[72:73], 6, v[72:73]
	v_lshl_add_u64 v[84:85], s[12:13], 0, v[72:73]
	global_load_dwordx4 v[72:75], v[84:85], off offset:48
	global_load_dwordx4 v[76:79], v[84:85], off offset:32
	global_load_dwordx4 v[80:83], v[84:85], off offset:16
	s_nop 0
	global_load_dwordx4 v[84:87], v[84:85], off
	s_mov_b32 s0, 0x3a800000
	v_mov_b32_e32 v53, v3
	v_mov_b32_e32 v55, v3
	v_mov_b32_e32 v57, v3
	v_lshlrev_b64 v[120:121], 12, v[0:1]
	v_lshl_add_u64 v[120:121], s[22:23], 0, v[120:121]
	v_lshl_add_u64 v[136:137], v[120:121], 0, s[10:11]
	v_lshl_add_u64 v[58:59], v[120:121], 0, v[2:3]
	v_lshl_add_u64 v[66:67], v[136:137], 0, v[2:3]
	v_lshl_add_u64 v[62:63], v[136:137], 0, v[52:53]
	v_lshl_add_u64 v[60:61], v[136:137], 0, v[54:55]
	global_load_dwordx4 v[148:151], v[58:59], off
	global_load_dwordx4 v[144:147], v[66:67], off
	global_load_dwordx4 v[140:143], v[58:59], off offset:1024
	global_load_dwordx4 v[132:135], v[62:63], off
	global_load_dwordx4 v[124:127], v[58:59], off offset:2048
	global_load_dwordx4 v[128:131], v[60:61], off
	global_load_dwordx4 v[120:123], v[58:59], off offset:3072
	v_lshl_add_u64 v[64:65], v[136:137], 0, v[56:57]
	global_load_dwordx4 v[136:139], v[64:65], off
	s_waitcnt vmcnt(14)
	v_add_f32_e32 v24, v24, v25
	v_add_f32_e32 v26, v26, v27
	s_waitcnt vmcnt(12)
	v_mov_b32_e32 v36, v33
	v_mov_b32_e32 v37, v34
	v_mov_b32_e32 v33, v35
	v_mov_b32_e32 v34, v29
	v_mov_b32_e32 v35, v30
	v_mov_b32_e32 v29, v31
	v_add_f32_e32 v32, v36, v32
	v_add_f32_e32 v33, v37, v33
	v_add_f32_e32 v28, v34, v28
	v_add_f32_e32 v29, v35, v29
	v_pk_add_f32 v[32:33], v[32:33], v[32:33] op_sel:[0,1] op_sel_hi:[1,0]
	v_pk_add_f32 v[28:29], v[28:29], v[28:29] op_sel:[0,1] op_sel_hi:[1,0]
	v_mov_b32_e32 v33, v20
	v_mov_b32_e32 v29, v21
	v_mov_b32_e32 v25, v22
	v_mov_b32_e32 v27, v23
	v_add_f32_e32 v20, v32, v28
	v_add_f32_e32 v21, v33, v29
	v_add_f32_e32 v22, v24, v26
	v_add_f32_e32 v23, v25, v27
	s_nop 0
	v_add_f32_e32 v36, v20, v22
	v_add_f32_e32 v37, v21, v23
	s_waitcnt vmcnt(10)
	v_add_f32_e32 v76, v76, v77
	v_add_f32_e32 v78, v78, v79
	s_waitcnt vmcnt(8)
	v_mov_b32_e32 v90, v85
	v_mov_b32_e32 v91, v86
	v_mov_b32_e32 v85, v87
	v_mov_b32_e32 v86, v81
	v_mov_b32_e32 v87, v82
	v_mov_b32_e32 v81, v83
	v_add_f32_e32 v84, v90, v84
	v_add_f32_e32 v85, v91, v85
	v_add_f32_e32 v80, v86, v80
	v_add_f32_e32 v81, v87, v81
	v_pk_add_f32 v[84:85], v[84:85], v[84:85] op_sel:[0,1] op_sel_hi:[1,0]
	v_pk_add_f32 v[80:81], v[80:81], v[80:81] op_sel:[0,1] op_sel_hi:[1,0]
	v_mov_b32_e32 v85, v72
	v_mov_b32_e32 v81, v73
	v_mov_b32_e32 v77, v74
	v_mov_b32_e32 v79, v75
	v_add_f32_e32 v72, v84, v80
	v_add_f32_e32 v73, v85, v81
	v_add_f32_e32 v74, v76, v78
	v_add_f32_e32 v75, v77, v79
	s_nop 0
	v_add_f32_e32 v72, v72, v74
	v_add_f32_e32 v73, v73, v75
	v_mov_b32_e32 v75, v36
	v_mov_b32_e32 v74, v72
	v_mov_b32_e32 v36, v73
	v_add_f32_e32 v72, v74, v36
	v_add_f32_e32 v73, v75, v37
	s_nop 0
	v_pk_fma_f32 v[72:73], v[72:73], s[0:1], v[172:173] op_sel_hi:[1,0,0]
	s_nop 0
	v_mul_f32_e32 v74, 0x4b800000, v73
	v_cmp_gt_f32_e64 s[0:1], s33, v73
	v_cmp_gt_f32_e32 vcc, s33, v72
	s_nop 0
	v_cndmask_b32_e64 v73, v73, v74, s[0:1]
	v_rsq_f32_e32 v68, v73
	v_mul_f32_e32 v73, 0x4b800000, v72
	v_cndmask_b32_e32 v72, v72, v73, vcc
	v_rsq_f32_e32 v70, v72
	v_mul_f32_e32 v69, 0x45800000, v68
	v_cndmask_b32_e64 v68, v68, v69, s[0:1]
	v_mul_f32_e32 v71, 0x45800000, v70
	v_cndmask_b32_e32 v70, v70, v71, vcc
	v_add_u32_e32 v0, s8, v0
	v_cmp_lt_i32_e32 vcc, s63, v0
	s_or_b64 s[6:7], vcc, s[6:7]
	s_waitcnt vmcnt(7)
	v_mul_f32_e32 v148, v148, v68
	v_mul_f32_e32 v149, v149, v68
	v_mul_f32_e32 v150, v150, v68
	v_mul_f32_e32 v151, v151, v68
	s_waitcnt vmcnt(3)
	v_mul_f32_e32 v124, v124, v68
	v_mul_f32_e32 v125, v125, v68
	v_mul_f32_e32 v126, v126, v68
	v_mul_f32_e32 v127, v127, v68
	s_waitcnt vmcnt(1)
	v_mul_f32_e32 v120, v120, v68
	v_mul_f32_e32 v121, v121, v68
	v_mul_f32_e32 v122, v122, v68
	v_mul_f32_e32 v123, v123, v68
	v_mul_f32_e32 v126, v14, v126
	v_mul_f32_e32 v127, v15, v127
	v_mul_f32_e32 v124, v12, v124
	v_mul_f32_e32 v125, v13, v125
	v_mul_f32_e32 v122, v18, v122
	v_mul_f32_e32 v123, v19, v123
	v_mul_f32_e32 v120, v16, v120
	v_mul_f32_e32 v121, v17, v121
	v_mul_f32_e32 v144, v144, v70
	v_mul_f32_e32 v145, v145, v70
	v_mul_f32_e32 v146, v146, v70
	v_mul_f32_e32 v147, v147, v70
	v_mul_f32_e32 v140, v140, v68
	v_mul_f32_e32 v141, v141, v68
	v_mul_f32_e32 v142, v142, v68
	v_mul_f32_e32 v143, v143, v68
	v_mul_f32_e32 v132, v132, v70
	v_mul_f32_e32 v133, v133, v70
	v_mul_f32_e32 v134, v134, v70
	v_mul_f32_e32 v135, v135, v70
	global_store_dwordx4 v[58:59], v[124:127], off offset:2048
	global_store_dwordx4 v[58:59], v[120:123], off offset:3072
	v_mul_f32_e32 v150, v6, v150
	v_mul_f32_e32 v151, v7, v151
	v_mul_f32_e32 v124, v128, v70
	v_mul_f32_e32 v125, v129, v70
	v_mul_f32_e32 v126, v130, v70
	v_mul_f32_e32 v127, v131, v70
	s_waitcnt vmcnt(2)
	v_mul_f32_e32 v120, v136, v70
	v_mul_f32_e32 v121, v137, v70
	v_mul_f32_e32 v122, v138, v70
	v_mul_f32_e32 v123, v139, v70
	v_mul_f32_e32 v148, v4, v148
	v_mul_f32_e32 v149, v5, v149
	v_mul_f32_e32 v146, v6, v146
	v_mul_f32_e32 v147, v7, v147
	v_mul_f32_e32 v144, v4, v144
	v_mul_f32_e32 v145, v5, v145
	v_mul_f32_e32 v142, v10, v142
	v_mul_f32_e32 v143, v11, v143
	v_mul_f32_e32 v140, v8, v140
	v_mul_f32_e32 v141, v9, v141
	v_mul_f32_e32 v134, v10, v134
	v_mul_f32_e32 v135, v11, v135
	v_mul_f32_e32 v132, v8, v132
	v_mul_f32_e32 v133, v9, v133
	v_mul_f32_e32 v126, v14, v126
	v_mul_f32_e32 v127, v15, v127
	v_mul_f32_e32 v124, v12, v124
	v_mul_f32_e32 v125, v13, v125
	v_mul_f32_e32 v122, v18, v122
	v_mul_f32_e32 v123, v19, v123
	v_mul_f32_e32 v120, v16, v120
	v_mul_f32_e32 v121, v17, v121
	global_store_dwordx4 v[58:59], v[148:151], off
	global_store_dwordx4 v[66:67], v[144:147], off
	global_store_dwordx4 v[58:59], v[140:143], off offset:1024
	global_store_dwordx4 v[62:63], v[132:135], off
	global_store_dwordx4 v[60:61], v[124:127], off
	global_store_dwordx4 v[64:65], v[120:123], off
	s_andn2_b64 exec, exec, s[6:7]
	s_cbranch_execnz .LBB0_66

.LBB0_76:
	v_lshl_add_u64 v[4:5], v[56:57], 0, s[16:17]
	v_mad_u64_u32 v[8:9], s[18:19], v4, s72, v[58:59]
	v_mov_b32_e32 v2, v9
	v_mad_u64_u32 v[10:11], s[18:19], v5, s72, v[2:3]
	v_mov_b32_e32 v9, v10
	v_add_co_u32_e32 v114, vcc, s20, v8
	s_nop 1
	v_addc_co_u32_e32 v115, vcc, 0, v10, vcc
	v_add_co_u32_e32 v116, vcc, s24, v8
	s_nop 1
	v_addc_co_u32_e32 v117, vcc, 0, v10, vcc
	v_add_co_u32_e32 v118, vcc, s25, v8
	s_nop 1
	v_addc_co_u32_e32 v119, vcc, 0, v10, vcc
	global_load_dwordx4 v[120:123], v[8:9], off
	global_load_dwordx4 v[124:127], v[114:115], off
	global_load_dwordx4 v[128:131], v[116:117], off
	global_load_dwordx4 v[132:135], v[118:119], off
	v_lshl_add_u64 v[98:99], v[60:61], 0, s[16:17]
	v_mad_u64_u32 v[70:71], s[16:17], v98, s72, v[66:67]
	v_mov_b32_e32 v2, v71
	v_lshlrev_b64 v[84:85], 11, v[98:99]
	v_add_u32_e32 v110, v43, v42
	v_mad_u64_u32 v[6:7], s[16:17], v99, s72, v[2:3]
	v_lshlrev_b64 v[98:99], 4, v[98:99]
	v_lshl_or_b32 v98, s13, 2, v98
	v_lshl_add_u64 v[4:5], v[62:63], 0, v[84:85]
	v_mov_b32_e32 v71, v6
	v_lshl_add_u64 v[100:101], s[6:7], 0, v[98:99]
	v_lshl_add_u64 v[98:99], s[0:1], 0, v[98:99]
	global_load_dwordx4 v[32:35], v[4:5], off
	global_load_dwordx2 v[86:87], v[70:71], off offset:3072
	global_load_dwordx4 v[28:31], v[4:5], off offset:64
	global_load_dwordx2 v[82:83], v[70:71], off offset:3104
	global_load_dwordx4 v[24:27], v[4:5], off offset:128
	global_load_dwordx2 v[80:81], v[70:71], off offset:3136
	global_load_dwordx4 v[20:23], v[4:5], off offset:192
	global_load_dwordx2 v[78:79], v[70:71], off offset:3168
	global_load_dwordx4 v[16:19], v[4:5], off offset:256
	global_load_dwordx2 v[76:77], v[70:71], off offset:3200
	global_load_dwordx4 v[12:15], v[4:5], off offset:320
	global_load_dwordx2 v[74:75], v[70:71], off offset:3232
	global_load_dwordx4 v[8:11], v[4:5], off offset:384
	global_load_dwordx2 v[72:73], v[70:71], off offset:3264
	s_nop 0
	global_load_dwordx4 v[4:7], v[4:5], off offset:448
	s_nop 0
	global_load_dwordx2 v[70:71], v[70:71], off offset:3296
	s_nop 0
	global_load_dword v2, v[100:101], off
	global_load_dword v97, v[98:99], off
	s_waitcnt lgkmcnt(0)
	s_barrier
	s_waitcnt vmcnt(21)
	ds_write_b128 v96, v[120:123] offset:34816
	s_waitcnt vmcnt(20)
	ds_write_b128 v96, v[124:127] offset:43520
	s_waitcnt vmcnt(19)
	ds_write_b128 v96, v[128:131] offset:52224
	s_waitcnt vmcnt(18)
	ds_write_b128 v96, v[132:135] offset:60928
	s_waitcnt lgkmcnt(0)
	s_barrier
	ds_read_b128 v[98:101], v110 offset:34816
	ds_read_b128 v[102:105], v110 offset:34880
	ds_read_b128 v[106:109], v110 offset:34944
	ds_read_b128 v[110:113], v110 offset:35008
	ds_read_b128 v[114:117], v93
	ds_read_b128 v[118:121], v93 offset:64
	ds_read_b128 v[122:125], v93 offset:4416
	s_waitcnt lgkmcnt(2)
	v_mfma_f32_16x16x32_bf16 v[114:117], v[114:117], v[98:101], 0
	ds_read_b128 v[126:129], v93 offset:8768
	ds_read_b128 v[130:133], v93 offset:13120
	ds_read_b128 v[134:137], v93 offset:17472
	s_waitcnt lgkmcnt(4)
	v_mfma_f32_16x16x32_bf16 v[114:117], v[118:121], v[102:105], v[114:117]
	ds_read_b128 v[118:121], v93 offset:128
	ds_read_b128 v[138:141], v93 offset:21824
	ds_read_b128 v[142:145], v93 offset:26176
	s_waitcnt lgkmcnt(2)
	v_mfma_f32_16x16x32_bf16 v[114:117], v[118:121], v[106:109], v[114:117]
	ds_read_b128 v[118:121], v93 offset:192
	s_waitcnt vmcnt(1)
	v_mul_f32_e32 v2, 0x3db504f3, v2
	s_waitcnt lgkmcnt(0)
	v_mfma_f32_16x16x32_bf16 v[114:117], v[118:121], v[110:113], v[114:117]
	ds_read_b128 v[118:121], v93 offset:4352
	s_waitcnt lgkmcnt(0)
	v_mfma_f32_16x16x32_bf16 v[118:121], v[118:121], v[98:101], 0
	s_nop 4
	v_fma_f32 v32, v2, v114, v32
	v_fma_f32 v33, v2, v115, v33
	v_fma_f32 v34, v2, v116, v34
	v_fma_f32 v35, v2, v117, v35
	v_mfma_f32_16x16x32_bf16 v[118:121], v[122:125], v[102:105], v[118:121]
	ds_read_b128 v[122:125], v93 offset:4480
	s_waitcnt lgkmcnt(0)
	v_mfma_f32_16x16x32_bf16 v[118:121], v[122:125], v[106:109], v[118:121]
	ds_read_b128 v[122:125], v93 offset:4544
	s_waitcnt lgkmcnt(0)
	v_mfma_f32_16x16x32_bf16 v[118:121], v[122:125], v[110:113], v[118:121]
	ds_read_b128 v[122:125], v93 offset:8704
	s_waitcnt lgkmcnt(0)
	v_mfma_f32_16x16x32_bf16 v[122:125], v[122:125], v[98:101], 0
	v_mfma_f32_16x16x32_bf16 v[122:125], v[126:129], v[102:105], v[122:125]
	ds_read_b128 v[126:129], v93 offset:8832
	s_waitcnt lgkmcnt(0)
	v_mfma_f32_16x16x32_bf16 v[122:125], v[126:129], v[106:109], v[122:125]
	ds_read_b128 v[126:129], v93 offset:8896
	s_waitcnt lgkmcnt(0)
	v_mfma_f32_16x16x32_bf16 v[122:125], v[126:129], v[110:113], v[122:125]
	ds_read_b128 v[126:129], v93 offset:13056
	s_nop 6
	v_fma_f32 v24, v2, v122, v24
	v_fma_f32 v25, v2, v123, v25
	s_waitcnt lgkmcnt(0)
	v_mfma_f32_16x16x32_bf16 v[126:129], v[126:129], v[98:101], 0
	v_mfma_f32_16x16x32_bf16 v[126:129], v[130:133], v[102:105], v[126:129]
	ds_read_b128 v[130:133], v93 offset:13184
	s_waitcnt lgkmcnt(0)
	v_mfma_f32_16x16x32_bf16 v[126:129], v[130:133], v[106:109], v[126:129]
	ds_read_b128 v[130:133], v93 offset:13248
	s_waitcnt lgkmcnt(0)
	v_mfma_f32_16x16x32_bf16 v[126:129], v[130:133], v[110:113], v[126:129]
	ds_read_b128 v[130:133], v93 offset:17408
	s_waitcnt lgkmcnt(0)
	v_mfma_f32_16x16x32_bf16 v[130:133], v[130:133], v[98:101], 0
	v_mfma_f32_16x16x32_bf16 v[130:133], v[134:137], v[102:105], v[130:133]
	ds_read_b128 v[134:137], v93 offset:17536
	s_waitcnt lgkmcnt(0)
	v_mfma_f32_16x16x32_bf16 v[130:133], v[134:137], v[106:109], v[130:133]
	ds_read_b128 v[134:137], v93 offset:17600
	s_waitcnt lgkmcnt(0)
	v_mfma_f32_16x16x32_bf16 v[130:133], v[134:137], v[110:113], v[130:133]
	ds_read_b128 v[134:137], v93 offset:21760
	s_waitcnt lgkmcnt(0)
	v_mfma_f32_16x16x32_bf16 v[134:137], v[134:137], v[98:101], 0
	v_mfma_f32_16x16x32_bf16 v[134:137], v[138:141], v[102:105], v[134:137]
	ds_read_b128 v[138:141], v93 offset:21888
	s_waitcnt lgkmcnt(0)
	v_mfma_f32_16x16x32_bf16 v[134:137], v[138:141], v[106:109], v[134:137]
	ds_read_b128 v[138:141], v93 offset:21952
	s_waitcnt lgkmcnt(0)
	v_mfma_f32_16x16x32_bf16 v[134:137], v[138:141], v[110:113], v[134:137]
	ds_read_b128 v[138:141], v93 offset:26112
	s_nop 6
	v_fma_f32 v12, v2, v134, v12
	v_fma_f32 v13, v2, v135, v13
	s_waitcnt lgkmcnt(0)
	v_mfma_f32_16x16x32_bf16 v[138:141], v[138:141], v[98:101], 0
	v_mfma_f32_16x16x32_bf16 v[138:141], v[142:145], v[102:105], v[138:141]
	ds_read_b128 v[142:145], v93 offset:26240
	s_waitcnt lgkmcnt(0)
	v_mfma_f32_16x16x32_bf16 v[138:141], v[142:145], v[106:109], v[138:141]
	ds_read_b128 v[142:145], v93 offset:26304
	s_waitcnt lgkmcnt(0)
	v_mfma_f32_16x16x32_bf16 v[138:141], v[142:145], v[110:113], v[138:141]
	ds_read_b128 v[142:145], v93 offset:30464
	s_waitcnt lgkmcnt(0)
	v_mfma_f32_16x16x32_bf16 v[98:101], v[142:145], v[98:101], 0
	ds_read_b128 v[142:145], v93 offset:30528
	s_waitcnt lgkmcnt(0)
	v_mfma_f32_16x16x32_bf16 v[98:101], v[142:145], v[102:105], v[98:101]
	ds_read_b128 v[102:105], v93 offset:30592
	s_waitcnt lgkmcnt(0)
	v_mfma_f32_16x16x32_bf16 v[98:101], v[102:105], v[106:109], v[98:101]
	ds_read_b128 v[102:105], v93 offset:30656
	s_waitcnt lgkmcnt(0)
	v_mfma_f32_16x16x32_bf16 v[98:101], v[102:105], v[110:113], v[98:101]
	ds_read_b128 v[102:105], v94 offset:34816
	ds_read_b128 v[106:109], v94 offset:34832
	ds_read_b128 v[110:113], v94 offset:34848
	ds_read_b128 v[142:145], v94 offset:34864
	ds_read_b128 v[146:149], v95
	ds_read_b128 v[150:153], v95 offset:16
	ds_read_b128 v[154:157], v95 offset:32
	ds_read_b128 v[158:161], v95 offset:48
	s_waitcnt lgkmcnt(7)
	v_and_b32_e32 v166, 0xffff0000, v102
	s_waitcnt lgkmcnt(6)
	v_and_b32_e32 v167, 0xffff0000, v106
	v_lshlrev_b32_e32 v163, 16, v106
	s_waitcnt lgkmcnt(1)
	v_mov_b32_e32 v165, v154
	v_mov_b32_e32 v154, v147
	v_lshlrev_b32_e32 v162, 16, v102
	v_mov_b32_e32 v164, v146
	v_mul_f32_e32 v146, v154, v166
	v_mul_f32_e32 v147, v155, v167
	v_lshlrev_b32_e32 v155, 16, v107
	v_fma_f32 v146, v164, v162, v146
	v_fma_f32 v147, v165, v163, v147
	v_lshlrev_b32_e32 v154, 16, v103
	v_mov_b32_e32 v162, v148
	v_mov_b32_e32 v163, v156
	v_fma_f32 v146, v162, v154, v146
	v_fma_f32 v147, v163, v155, v147
	v_and_b32_e32 v107, 0xffff0000, v107
	v_and_b32_e32 v106, 0xffff0000, v103
	v_mov_b32_e32 v156, v149
	v_fma_f32 v102, v156, v106, v146
	v_fma_f32 v103, v157, v107, v147
	v_lshlrev_b32_e32 v107, 16, v108
	v_lshlrev_b32_e32 v106, 16, v104
	v_mov_b32_e32 v146, v150
	s_waitcnt lgkmcnt(0)
	v_mov_b32_e32 v147, v158
	v_fma_f32 v102, v146, v106, v102
	v_fma_f32 v103, v147, v107, v103
	v_and_b32_e32 v107, 0xffff0000, v108
	v_and_b32_e32 v106, 0xffff0000, v104
	v_mov_b32_e32 v158, v151
	v_fma_f32 v102, v158, v106, v102
	v_fma_f32 v103, v159, v107, v103
	v_lshlrev_b32_e32 v107, 16, v109
	v_lshlrev_b32_e32 v106, 16, v105
	v_mov_b32_e32 v146, v152
	v_mov_b32_e32 v147, v160
	v_fma_f32 v102, v146, v106, v102
	v_fma_f32 v103, v147, v107, v103
	v_and_b32_e32 v107, 0xffff0000, v109
	v_and_b32_e32 v106, 0xffff0000, v105
	v_mov_b32_e32 v160, v153
	v_fma_f32 v102, v160, v106, v102
	v_fma_f32 v103, v161, v107, v103
	v_and_b32_e32 v159, 0xffff0000, v142
	v_add_f32_e32 v102, 0, v102
	v_add_f32_e32 v160, v102, v103
	ds_read_b128 v[102:105], v95 offset:80
	ds_read_b128 v[106:109], v95 offset:112
	ds_read_b128 v[146:149], v95 offset:64
	ds_read_b128 v[150:153], v95 offset:96
	v_and_b32_e32 v158, 0xffff0000, v110
	v_lshlrev_b32_e32 v155, 16, v142
	v_lshlrev_b32_e32 v154, 16, v110
	s_waitcnt lgkmcnt(1)
	v_mov_b32_e32 v156, v146
	s_waitcnt lgkmcnt(0)
	v_mov_b32_e32 v157, v150
	v_mov_b32_e32 v150, v147
	v_mul_f32_e32 v146, v150, v158
	v_mul_f32_e32 v147, v151, v159
	v_lshlrev_b32_e32 v151, 16, v143
	v_fma_f32 v146, v156, v154, v146
	v_fma_f32 v147, v157, v155, v147
	v_lshlrev_b32_e32 v150, 16, v111
	v_mov_b32_e32 v154, v148
	v_mov_b32_e32 v155, v152
	v_fma_f32 v146, v154, v150, v146
	v_fma_f32 v147, v155, v151, v147
	v_and_b32_e32 v143, 0xffff0000, v143
	v_and_b32_e32 v142, 0xffff0000, v111
	v_mov_b32_e32 v152, v149
	v_fma_f32 v110, v152, v142, v146
	v_fma_f32 v111, v153, v143, v147
	v_lshlrev_b32_e32 v143, 16, v144
	v_lshlrev_b32_e32 v142, 16, v112
	v_mov_b32_e32 v146, v102
	v_mov_b32_e32 v147, v106
	v_fma_f32 v110, v146, v142, v110
	v_fma_f32 v111, v147, v143, v111
	v_and_b32_e32 v143, 0xffff0000, v144
	v_and_b32_e32 v142, 0xffff0000, v112
	v_mov_b32_e32 v106, v103
	v_fma_f32 v102, v106, v142, v110
	v_fma_f32 v103, v107, v143, v111
	v_lshlrev_b32_e32 v107, 16, v145
	v_lshlrev_b32_e32 v106, 16, v113
	v_mov_b32_e32 v110, v104
	v_mov_b32_e32 v111, v108
	v_fma_f32 v102, v110, v106, v102
	v_fma_f32 v103, v111, v107, v103
	v_and_b32_e32 v107, 0xffff0000, v145
	v_and_b32_e32 v106, 0xffff0000, v113
	v_mov_b32_e32 v108, v105
	v_fma_f32 v102, v108, v106, v102
	v_fma_f32 v103, v109, v107, v103
	v_fma_f32 v112, v2, v130, v16
	v_fma_f32 v113, v2, v131, v17
	v_add_f32_e32 v102, v160, v102
	v_add_f32_e32 v102, v102, v103
	ds_bpermute_b32 v103, v91, v102
	v_fma_f32 v16, v2, v132, v18
	v_fma_f32 v17, v2, v133, v19
	v_fma_f32 v98, v2, v98, v4
	v_fma_f32 v99, v2, v99, v5
	v_fma_f32 v4, v2, v100, v6
	v_fma_f32 v5, v2, v101, v7
	s_waitcnt lgkmcnt(0)
	v_add_f32_e32 v102, v102, v103
	ds_bpermute_b32 v103, v92, v102
	s_waitcnt lgkmcnt(0)
	v_add_f32_e32 v102, v102, v103
	s_waitcnt vmcnt(0)
	v_fmac_f32_e32 v97, v2, v102
	v_max_f32_e64 v97, |v97|, 1.0
	v_div_scale_f32 v102, s[16:17], v97, v97, 1.0
	v_rcp_f32_e32 v103, v102
	s_mov_b64 s[16:17], 0x80
	v_fma_f32 v104, -v102, v103, 1.0
	v_fmac_f32_e32 v103, v104, v103
	v_div_scale_f32 v104, vcc, 1.0, v97, 1.0
	v_mul_f32_e32 v105, v104, v103
	v_fma_f32 v106, -v102, v105, v104
	v_fmac_f32_e32 v105, v106, v103
	v_fma_f32 v102, -v102, v105, v104
	v_div_fmas_f32 v102, v102, v103, v105
	v_div_fixup_f32 v102, v102, v97, 1.0
	v_mul_f32_e32 v106, v32, v102
	v_mul_f32_e32 v107, v33, v102
	v_fma_f32 v32, v2, v118, v28
	v_fma_f32 v33, v2, v119, v29
	v_fma_f32 v28, v2, v120, v30
	v_fma_f32 v29, v2, v121, v31
	v_mul_f32_e32 v30, v32, v102
	v_mul_f32_e32 v31, v33, v102
	v_mul_f32_e32 v104, v34, v102
	v_mul_f32_e32 v105, v35, v102
	v_mul_f32_e32 v28, v28, v102
	v_mul_f32_e32 v29, v29, v102
	v_mov_b32_e32 v34, v107
	v_mov_b32_e32 v35, v31
	v_mov_b32_e32 v32, v106
	v_mov_b32_e32 v33, v30
	v_mul_f32_e32 v34, v34, v34
	v_mul_f32_e32 v35, v35, v35
	v_mov_b32_e32 v108, v105
	v_mov_b32_e32 v109, v29
	v_fma_f32 v32, v32, v32, v34
	v_fma_f32 v33, v33, v33, v35
	v_mov_b32_e32 v34, v104
	v_mov_b32_e32 v35, v28
	v_mul_f32_e32 v108, v108, v108
	v_mul_f32_e32 v109, v109, v109
	v_mul_f32_e32 v16, v16, v102
	v_mul_f32_e32 v17, v17, v102
	v_fma_f32 v34, v34, v34, v108
	v_fma_f32 v35, v35, v35, v109
	v_mul_f32_e32 v18, v112, v102
	v_mul_f32_e32 v19, v113, v102
	v_add_f32_e32 v32, v32, v34
	v_add_f32_e32 v33, v33, v35
	v_fma_f32 v34, v2, v124, v26
	v_fma_f32 v35, v2, v125, v27
	v_mul_f32_e32 v26, v24, v102
	v_mul_f32_e32 v27, v25, v102
	v_mul_f32_e32 v24, v34, v102
	v_mul_f32_e32 v25, v35, v102
	v_mul_f32_e32 v108, v26, v26
	v_mul_f32_e32 v109, v27, v27
	v_mul_f32_e32 v34, v24, v24
	v_mul_f32_e32 v35, v25, v25
	v_add_f32_e32 v33, v32, v33
	v_add_f32_e32 v32, v32, v32
	v_pk_mov_b32 v[110:111], v[108:109], v[34:35] op_sel:[1,0]
	v_mov_b32_e32 v109, v35
	v_add_f32_e32 v34, v110, v108
	v_add_f32_e32 v35, v111, v109
	v_fma_f32 v108, v2, v126, v20
	v_fma_f32 v109, v2, v127, v21
	v_fma_f32 v20, v2, v128, v22
	v_fma_f32 v21, v2, v129, v23
	v_mul_f32_e32 v22, v108, v102
	v_mul_f32_e32 v23, v109, v102
	v_mul_f32_e32 v20, v20, v102
	v_mul_f32_e32 v21, v21, v102
	v_mul_f32_e32 v32, v22, v22
	v_add_f32_e32 v35, v34, v35
	v_add_f32_e32 v34, v34, v34
	v_fma_f32 v108, v22, v22, v32
	v_fma_f32 v109, v23, v23, v32
	v_mul_f32_e32 v32, v20, v20
	v_fma_f32 v110, v20, v20, v32
	v_fma_f32 v111, v21, v21, v32
	v_mul_f32_e32 v34, v16, v16
	v_mul_f32_e32 v32, v17, v17
	v_mul_f32_e32 v108, v18, v18
	v_mul_f32_e32 v110, v19, v19
	v_add_f32_e32 v32, v34, v32
	v_add_f32_e32 v33, v35, v33
	v_fma_f32 v34, v2, v136, v14
	v_fma_f32 v35, v2, v137, v15
	v_add_f32_e32 v108, v108, v110
	v_add_f32_e32 v109, v109, v111
	v_mul_f32_e32 v14, v12, v102
	v_mul_f32_e32 v15, v13, v102
	v_mul_f32_e32 v12, v34, v102
	v_mul_f32_e32 v13, v35, v102
	v_add_f32_e32 v32, v108, v32
	v_add_f32_e32 v33, v109, v33
	v_mul_f32_e32 v34, v12, v12
	v_mul_f32_e32 v35, v13, v13
	v_mul_f32_e32 v108, v14, v14
	v_mul_f32_e32 v109, v15, v15
	v_add_f32_e32 v33, v32, v33
	v_add_f32_e32 v32, v32, v32
	v_pk_mov_b32 v[110:111], v[108:109], v[34:35] op_sel:[1,0]
	v_mov_b32_e32 v109, v35
	v_add_f32_e32 v34, v110, v108
	v_add_f32_e32 v35, v111, v109
	v_fma_f32 v108, v2, v138, v8
	v_fma_f32 v109, v2, v139, v9
	v_fma_f32 v8, v2, v140, v10
	v_fma_f32 v9, v2, v141, v11
	v_mul_f32_e32 v10, v108, v102
	v_mul_f32_e32 v11, v109, v102
	v_mul_f32_e32 v8, v8, v102
	v_mul_f32_e32 v9, v9, v102
	v_mul_f32_e32 v32, v10, v10
	v_fma_f32 v108, v10, v10, v32
	v_fma_f32 v109, v11, v11, v32
	v_mul_f32_e32 v32, v8, v8
	v_add_f32_e32 v35, v34, v35
	v_add_f32_e32 v34, v34, v34
	v_fma_f32 v110, v8, v8, v32
	v_fma_f32 v111, v9, v9, v32
	v_mul_f32_e32 v4, v4, v102
	v_mul_f32_e32 v5, v5, v102
	v_mul_f32_e32 v6, v98, v102
	v_mul_f32_e32 v7, v99, v102
	v_mul_f32_e32 v34, v4, v4
	v_mul_f32_e32 v108, v6, v6
	v_mul_f32_e32 v110, v7, v7
	v_mul_f32_e32 v32, v5, v5
	v_add_f32_e32 v98, v108, v110
	v_add_f32_e32 v99, v109, v111
	v_add_f32_e32 v32, v34, v32
	v_add_f32_e32 v33, v35, v33
	v_lshlrev_b32_e32 v97, 16, v86
	v_add_f32_e32 v32, v98, v32
	v_add_f32_e32 v33, v99, v33
	v_and_b32_e32 v86, 0xffff0000, v86
	v_add_f32_e32 v2, v32, v33
	ds_bpermute_b32 v32, v91, v2
	v_mul_f32_e32 v86, 0xbfb8aa3b, v86
	v_exp_f32_e32 v86, v86
	v_mul_f32_e32 v97, 0xbfb8aa3b, v97
	v_exp_f32_e32 v97, v97
	s_waitcnt lgkmcnt(0)
	v_add_f32_e32 v2, v2, v32
	ds_bpermute_b32 v32, v92, v2
	v_add_f32_e32 v86, 1.0, v86
	v_rcp_f32_e32 v99, v86
	v_lshlrev_b32_e32 v86, 16, v87
	v_and_b32_e32 v87, 0xffff0000, v87
	s_waitcnt lgkmcnt(0)
	v_add_f32_e32 v2, v2, v32
	v_fmamk_f32 v2, v2, 0x3c000000, v172
	v_cmp_gt_f32_e32 vcc, s33, v2
	v_mul_f32_e32 v32, 0x4b800000, v2
	v_mul_f32_e32 v86, 0xbfb8aa3b, v86
	v_cndmask_b32_e32 v2, v2, v32, vcc
	v_rsq_f32_e32 v2, v2
	v_mul_f32_e32 v87, 0xbfb8aa3b, v87
	v_exp_f32_e32 v86, v86
	v_exp_f32_e32 v87, v87
	v_mul_f32_e32 v32, 0x45800000, v2
	v_cndmask_b32_e32 v2, v2, v32, vcc
	v_add_f32_e32 v97, 1.0, v97
	v_rcp_f32_e32 v98, v97
	v_add_f32_e32 v86, 1.0, v86
	v_add_f32_e32 v87, 1.0, v87
	v_mul_f32_e32 v100, v106, v2
	v_mul_f32_e32 v101, v107, v2
	v_rcp_f32_e32 v86, v86
	v_rcp_f32_e32 v87, v87
	v_mul_f32_e32 v30, v30, v2
	v_mul_f32_e32 v31, v31, v2
	v_mul_f32_e32 v28, v28, v2
	v_mul_f32_e32 v29, v29, v2
	v_mul_f32_e32 v26, v26, v2
	v_mul_f32_e32 v27, v27, v2
	v_mul_f32_e32 v24, v24, v2
	v_mul_f32_e32 v25, v25, v2
	v_mul_f32_e32 v22, v22, v2
	v_mul_f32_e32 v23, v23, v2
	v_mul_f32_e32 v20, v20, v2
	v_mul_f32_e32 v21, v21, v2
	v_mul_f32_e32 v18, v18, v2
	v_mul_f32_e32 v19, v19, v2
	v_mul_f32_e32 v16, v16, v2
	v_mul_f32_e32 v17, v17, v2
	v_mul_f32_e32 v14, v14, v2
	v_mul_f32_e32 v15, v15, v2
	v_mul_f32_e32 v12, v12, v2
	v_mul_f32_e32 v13, v13, v2
	v_mul_f32_e32 v10, v10, v2
	v_mul_f32_e32 v11, v11, v2
	v_mul_f32_e32 v8, v8, v2
	v_mul_f32_e32 v9, v9, v2
	v_mul_f32_e32 v6, v6, v2
	v_mul_f32_e32 v7, v7, v2
	v_mul_f32_e32 v4, v4, v2
	v_mul_f32_e32 v5, v5, v2
	s_andn2_b64 vcc, exec, s[14:15]
	s_mov_b64 s[14:15], 0
	s_waitcnt vmcnt(0)
	v_mov_b64_e32 v[32:33], v[184:185]
	v_mov_b64_e32 v[34:35], v[186:187]
	v_mul_f32_e32 v32, v32, v100
	v_mul_f32_e32 v33, v33, v101
	s_nop 0
	v_mul_f32_e32 v32, v98, v32
	v_mul_f32_e32 v33, v99, v33
	v_mul_f32_e32 v98, v104, v2
	v_mul_f32_e32 v99, v105, v2
	v_cvt_pk_bf16_f32 v32, v32, v33
	v_mul_f32_e32 v34, v34, v98
	v_mul_f32_e32 v35, v35, v99
	s_nop 0
	v_mul_f32_e32 v34, v86, v34
	v_mul_f32_e32 v35, v87, v35
	s_nop 0
	v_cvt_pk_bf16_f32 v33, v34, v35
	v_lshl_add_u64 v[34:35], v[68:69], 0, v[84:85]
	global_store_dwordx2 v[34:35], v[32:33], off
	v_lshlrev_b32_e32 v32, 16, v82
	v_and_b32_e32 v33, 0xffff0000, v82
	v_mul_f32_e32 v32, 0xbfb8aa3b, v32
	v_mul_f32_e32 v33, 0xbfb8aa3b, v33
	v_exp_f32_e32 v32, v32
	v_exp_f32_e32 v33, v33
	v_add_f32_e32 v32, 1.0, v32
	v_add_f32_e32 v33, 1.0, v33
	v_rcp_f32_e32 v32, v32
	v_rcp_f32_e32 v33, v33
	v_mov_b64_e32 v[84:85], v[188:189]
	v_mov_b64_e32 v[86:87], v[190:191]
	v_mul_f32_e32 v30, v84, v30
	v_mul_f32_e32 v31, v85, v31
	s_nop 0
	v_mul_f32_e32 v30, v32, v30
	v_mul_f32_e32 v31, v33, v31
	v_lshlrev_b32_e32 v32, 16, v83
	v_and_b32_e32 v33, 0xffff0000, v83
	v_mul_f32_e32 v32, 0xbfb8aa3b, v32
	v_mul_f32_e32 v33, 0xbfb8aa3b, v33
	v_exp_f32_e32 v32, v32
	v_exp_f32_e32 v33, v33
	v_mul_f32_e32 v28, v86, v28
	v_mul_f32_e32 v29, v87, v29
	v_cvt_pk_bf16_f32 v30, v30, v31
	v_add_f32_e32 v32, 1.0, v32
	v_add_f32_e32 v33, 1.0, v33
	v_rcp_f32_e32 v32, v32
	v_rcp_f32_e32 v33, v33
	s_nop 0
	v_mul_f32_e32 v28, v32, v28
	v_mul_f32_e32 v29, v33, v29
	s_nop 0
	v_cvt_pk_bf16_f32 v31, v28, v29
	global_store_dwordx2 v[34:35], v[30:31], off offset:32
	v_lshlrev_b32_e32 v32, 16, v80
	v_and_b32_e32 v33, 0xffff0000, v80
	v_mul_f32_e32 v32, 0xbfb8aa3b, v32
	v_mul_f32_e32 v33, 0xbfb8aa3b, v33
	v_exp_f32_e32 v32, v32
	v_exp_f32_e32 v33, v33
	v_add_f32_e32 v32, 1.0, v32
	v_add_f32_e32 v33, 1.0, v33
	v_rcp_f32_e32 v32, v32
	v_rcp_f32_e32 v33, v33
	v_mov_b64_e32 v[28:29], v[192:193]
	v_mov_b64_e32 v[30:31], v[194:195]
	v_mul_f32_e32 v26, v28, v26
	v_mul_f32_e32 v27, v29, v27
	v_lshlrev_b32_e32 v28, 16, v81
	v_and_b32_e32 v29, 0xffff0000, v81
	v_mul_f32_e32 v28, 0xbfb8aa3b, v28
	v_mul_f32_e32 v29, 0xbfb8aa3b, v29
	v_exp_f32_e32 v28, v28
	v_exp_f32_e32 v29, v29
	v_mul_f32_e32 v24, v30, v24
	v_mul_f32_e32 v25, v31, v25
	v_mul_f32_e32 v26, v32, v26
	v_mul_f32_e32 v27, v33, v27
	v_add_f32_e32 v28, 1.0, v28
	v_add_f32_e32 v29, 1.0, v29
	v_rcp_f32_e32 v28, v28
	v_rcp_f32_e32 v29, v29
	v_cvt_pk_bf16_f32 v26, v26, v27
	v_mul_f32_e32 v24, v28, v24
	v_mul_f32_e32 v25, v29, v25
	s_nop 0
	v_cvt_pk_bf16_f32 v27, v24, v25
	global_store_dwordx2 v[34:35], v[26:27], off offset:64
	v_lshlrev_b32_e32 v28, 16, v78
	v_and_b32_e32 v29, 0xffff0000, v78
	v_mul_f32_e32 v28, 0xbfb8aa3b, v28
	v_mul_f32_e32 v29, 0xbfb8aa3b, v29
	v_exp_f32_e32 v28, v28
	v_exp_f32_e32 v29, v29
	v_add_f32_e32 v28, 1.0, v28
	v_add_f32_e32 v29, 1.0, v29
	v_rcp_f32_e32 v28, v28
	v_rcp_f32_e32 v29, v29
	v_mov_b64_e32 v[24:25], v[196:197]
	v_mov_b64_e32 v[26:27], v[198:199]
	v_mul_f32_e32 v22, v24, v22
	v_mul_f32_e32 v23, v25, v23
	v_lshlrev_b32_e32 v24, 16, v79
	v_and_b32_e32 v25, 0xffff0000, v79
	v_mul_f32_e32 v24, 0xbfb8aa3b, v24
	v_mul_f32_e32 v25, 0xbfb8aa3b, v25
	v_exp_f32_e32 v24, v24
	v_exp_f32_e32 v25, v25
	v_mul_f32_e32 v20, v26, v20
	v_mul_f32_e32 v21, v27, v21
	v_mul_f32_e32 v22, v28, v22
	v_mul_f32_e32 v23, v29, v23
	v_add_f32_e32 v24, 1.0, v24
	v_add_f32_e32 v25, 1.0, v25
	v_rcp_f32_e32 v24, v24
	v_rcp_f32_e32 v25, v25
	v_cvt_pk_bf16_f32 v22, v22, v23
	v_mul_f32_e32 v20, v24, v20
	v_mul_f32_e32 v21, v25, v21
	s_nop 0
	v_cvt_pk_bf16_f32 v23, v20, v21
	global_store_dwordx2 v[34:35], v[22:23], off offset:96
	v_lshlrev_b32_e32 v24, 16, v76
	v_and_b32_e32 v25, 0xffff0000, v76
	v_mul_f32_e32 v24, 0xbfb8aa3b, v24
	v_mul_f32_e32 v25, 0xbfb8aa3b, v25
	v_exp_f32_e32 v24, v24
	v_exp_f32_e32 v25, v25
	v_add_f32_e32 v24, 1.0, v24
	v_add_f32_e32 v25, 1.0, v25
	v_rcp_f32_e32 v24, v24
	v_rcp_f32_e32 v25, v25
	v_mov_b64_e32 v[20:21], v[200:201]
	v_mov_b64_e32 v[22:23], v[202:203]
	v_mul_f32_e32 v18, v20, v18
	v_mul_f32_e32 v19, v21, v19
	v_lshlrev_b32_e32 v20, 16, v77
	v_and_b32_e32 v21, 0xffff0000, v77
	v_mul_f32_e32 v20, 0xbfb8aa3b, v20
	v_mul_f32_e32 v21, 0xbfb8aa3b, v21
	v_exp_f32_e32 v20, v20
	v_exp_f32_e32 v21, v21
	v_mul_f32_e32 v16, v22, v16
	v_mul_f32_e32 v17, v23, v17
	v_mul_f32_e32 v18, v24, v18
	v_mul_f32_e32 v19, v25, v19
	v_add_f32_e32 v20, 1.0, v20
	v_add_f32_e32 v21, 1.0, v21
	v_rcp_f32_e32 v20, v20
	v_rcp_f32_e32 v21, v21
	v_cvt_pk_bf16_f32 v18, v18, v19
	v_mul_f32_e32 v16, v20, v16
	v_mul_f32_e32 v17, v21, v17
	s_nop 0
	v_cvt_pk_bf16_f32 v19, v16, v17
	global_store_dwordx2 v[34:35], v[18:19], off offset:128
	v_lshlrev_b32_e32 v20, 16, v74
	v_and_b32_e32 v21, 0xffff0000, v74
	v_mul_f32_e32 v20, 0xbfb8aa3b, v20
	v_mul_f32_e32 v21, 0xbfb8aa3b, v21
	v_exp_f32_e32 v20, v20
	v_exp_f32_e32 v21, v21
	v_add_f32_e32 v20, 1.0, v20
	v_add_f32_e32 v21, 1.0, v21
	v_rcp_f32_e32 v20, v20
	v_rcp_f32_e32 v21, v21
	v_mov_b64_e32 v[16:17], v[204:205]
	v_mov_b64_e32 v[18:19], v[206:207]
	v_mul_f32_e32 v14, v16, v14
	v_mul_f32_e32 v15, v17, v15
	v_lshlrev_b32_e32 v16, 16, v75
	v_and_b32_e32 v17, 0xffff0000, v75
	v_mul_f32_e32 v16, 0xbfb8aa3b, v16
	v_mul_f32_e32 v17, 0xbfb8aa3b, v17
	v_exp_f32_e32 v16, v16
	v_exp_f32_e32 v17, v17
	v_mul_f32_e32 v12, v18, v12
	v_mul_f32_e32 v13, v19, v13
	v_mul_f32_e32 v14, v20, v14
	v_mul_f32_e32 v15, v21, v15
	v_add_f32_e32 v16, 1.0, v16
	v_add_f32_e32 v17, 1.0, v17
	v_rcp_f32_e32 v16, v16
	v_rcp_f32_e32 v17, v17
	v_cvt_pk_bf16_f32 v14, v14, v15
	v_mul_f32_e32 v12, v16, v12
	v_mul_f32_e32 v13, v17, v13
	s_nop 0
	v_cvt_pk_bf16_f32 v15, v12, v13
	global_store_dwordx2 v[34:35], v[14:15], off offset:160
	v_lshlrev_b32_e32 v16, 16, v72
	v_and_b32_e32 v17, 0xffff0000, v72
	v_mul_f32_e32 v16, 0xbfb8aa3b, v16
	v_mul_f32_e32 v17, 0xbfb8aa3b, v17
	v_exp_f32_e32 v16, v16
	v_exp_f32_e32 v17, v17
	v_add_f32_e32 v16, 1.0, v16
	v_add_f32_e32 v17, 1.0, v17
	v_rcp_f32_e32 v16, v16
	v_rcp_f32_e32 v17, v17
	v_mov_b64_e32 v[12:13], v[230:231]
	v_mov_b64_e32 v[14:15], v[232:233]
	v_mul_f32_e32 v10, v12, v10
	v_mul_f32_e32 v11, v13, v11
	v_lshlrev_b32_e32 v12, 16, v73
	v_and_b32_e32 v13, 0xffff0000, v73
	v_mul_f32_e32 v12, 0xbfb8aa3b, v12
	v_mul_f32_e32 v13, 0xbfb8aa3b, v13
	v_exp_f32_e32 v12, v12
	v_exp_f32_e32 v13, v13
	v_mul_f32_e32 v8, v14, v8
	v_mul_f32_e32 v9, v15, v9
	v_mul_f32_e32 v10, v16, v10
	v_mul_f32_e32 v11, v17, v11
	v_add_f32_e32 v12, 1.0, v12
	v_add_f32_e32 v13, 1.0, v13
	v_rcp_f32_e32 v12, v12
	v_rcp_f32_e32 v13, v13
	v_cvt_pk_bf16_f32 v10, v10, v11
	v_mul_f32_e32 v8, v12, v8
	v_mul_f32_e32 v9, v13, v9
	s_nop 0
	v_cvt_pk_bf16_f32 v11, v8, v9
	global_store_dwordx2 v[34:35], v[10:11], off offset:192
	v_lshlrev_b32_e32 v12, 16, v70
	v_and_b32_e32 v13, 0xffff0000, v70
	v_mul_f32_e32 v12, 0xbfb8aa3b, v12
	v_mul_f32_e32 v13, 0xbfb8aa3b, v13
	v_exp_f32_e32 v12, v12
	v_exp_f32_e32 v13, v13
	v_add_f32_e32 v12, 1.0, v12
	v_add_f32_e32 v13, 1.0, v13
	v_rcp_f32_e32 v12, v12
	v_rcp_f32_e32 v13, v13
	v_mov_b64_e32 v[8:9], v[234:235]
	v_mov_b64_e32 v[10:11], v[236:237]
	v_mul_f32_e32 v6, v8, v6
	v_mul_f32_e32 v7, v9, v7
	v_lshlrev_b32_e32 v8, 16, v71
	v_and_b32_e32 v9, 0xffff0000, v71
	v_mul_f32_e32 v8, 0xbfb8aa3b, v8
	v_mul_f32_e32 v9, 0xbfb8aa3b, v9
	v_exp_f32_e32 v8, v8
	v_exp_f32_e32 v9, v9
	v_mul_f32_e32 v4, v10, v4
	v_mul_f32_e32 v5, v11, v5
	v_mul_f32_e32 v6, v12, v6
	v_mul_f32_e32 v7, v13, v7
	v_add_f32_e32 v8, 1.0, v8
	v_add_f32_e32 v9, 1.0, v9
	v_rcp_f32_e32 v8, v8
	v_rcp_f32_e32 v9, v9
	v_cvt_pk_bf16_f32 v6, v6, v7
	v_mul_f32_e32 v4, v8, v4
	v_mul_f32_e32 v5, v9, v5
	s_nop 0
	v_cvt_pk_bf16_f32 v7, v4, v5
	global_store_dwordx2 v[34:35], v[6:7], off offset:224
	s_cbranch_vccz .LBB0_76
	v_readlane_b32 s14, v252, 7
	v_readlane_b32 s15, v252, 8
	s_load_dword s13, s[14:15], 0x0
	s_waitcnt lgkmcnt(0)
	s_add_i32 s12, s12, s13
	s_cmpk_gt_i32 s12, 0xff
	s_cbranch_scc0 .LBB0_73

.LBB0_92:
	v_div_scale_f32 v36, s[0:1], v194, v194, 1.0
	v_rcp_f32_e32 v37, v36
	v_div_scale_f32 v38, vcc, 1.0, v194, 1.0
	v_ashrrev_i32_e32 v155, 31, v154
	v_fma_f32 v39, -v36, v37, 1.0
	v_fmac_f32_e32 v37, v39, v37
	v_mul_f32_e32 v39, v38, v37
	v_fma_f32 v40, -v36, v39, v38
	v_fmac_f32_e32 v39, v40, v37
	v_fma_f32 v36, -v36, v39, v38
	v_div_fmas_f32 v36, v36, v37, v39
	v_lshl_add_u64 v[38:39], v[154:155], 0, s[6:7]
	v_readlane_b32 s0, v254, 48
	v_lshlrev_b64 v[38:39], 11, v[38:39]
	v_readlane_b32 s1, v254, 49
	v_mov_b32_e32 v139, v3
	v_div_fixup_f32 v36, v36, v194, 1.0
	v_lshl_add_u64 v[38:39], s[0:1], 0, v[38:39]
	v_lshl_add_u64 v[38:39], v[38:39], 0, s[20:21]
	v_lshl_add_u64 v[38:39], v[38:39], 0, v[138:139]
	s_mov_b64 s[0:1], 0xee00400
	v_lshl_add_u64 v[40:41], v[38:39], 0, s[0:1]
	s_mov_b32 s0, 0xee00000
	v_mul_f32_e32 v42, v80, v36
	v_mul_f32_e32 v43, v81, v36
	v_mul_f32_e32 v44, v82, v36
	v_mul_f32_e32 v45, v83, v36
	v_add_co_u32_e32 v38, vcc, s0, v38
	v_cvt_pk_bf16_f32 v42, v42, v43
	v_cvt_pk_bf16_f32 v43, v44, v45
	v_addc_co_u32_e32 v39, vcc, 0, v39, vcc
	global_store_dwordx2 v[38:39], v[42:43], off offset:1024
	v_mul_f32_e32 v38, v76, v36
	v_mul_f32_e32 v39, v77, v36
	v_mul_f32_e32 v42, v78, v36
	v_mul_f32_e32 v43, v79, v36
	v_cvt_pk_bf16_f32 v38, v38, v39
	v_cvt_pk_bf16_f32 v39, v42, v43
	global_store_dwordx2 v[40:41], v[38:39], off offset:32
	v_mul_f32_e32 v38, v72, v36
	v_mul_f32_e32 v39, v73, v36
	v_mul_f32_e32 v42, v74, v36
	v_mul_f32_e32 v43, v75, v36
	v_cvt_pk_bf16_f32 v38, v38, v39
	v_cvt_pk_bf16_f32 v39, v42, v43
	global_store_dwordx2 v[40:41], v[38:39], off offset:64
	v_mul_f32_e32 v38, v68, v36
	v_mul_f32_e32 v39, v69, v36
	v_mul_f32_e32 v42, v70, v36
	v_mul_f32_e32 v43, v71, v36
	v_cvt_pk_bf16_f32 v38, v38, v39
	v_cvt_pk_bf16_f32 v39, v42, v43
	global_store_dwordx2 v[40:41], v[38:39], off offset:96
	v_mul_f32_e32 v38, v64, v36
	v_mul_f32_e32 v39, v65, v36
	v_mul_f32_e32 v42, v66, v36
	v_mul_f32_e32 v43, v67, v36
	v_cvt_pk_bf16_f32 v38, v38, v39
	v_cvt_pk_bf16_f32 v39, v42, v43
	global_store_dwordx2 v[40:41], v[38:39], off offset:128
	v_mul_f32_e32 v38, v60, v36
	v_mul_f32_e32 v39, v61, v36
	v_mul_f32_e32 v42, v62, v36
	v_mul_f32_e32 v43, v63, v36
	v_cvt_pk_bf16_f32 v38, v38, v39
	v_cvt_pk_bf16_f32 v39, v42, v43
	global_store_dwordx2 v[40:41], v[38:39], off offset:160
	v_mul_f32_e32 v38, v56, v36
	v_mul_f32_e32 v39, v57, v36
	v_mul_f32_e32 v42, v58, v36
	v_mul_f32_e32 v43, v59, v36
	v_cvt_pk_bf16_f32 v38, v38, v39
	v_cvt_pk_bf16_f32 v39, v42, v43
	global_store_dwordx2 v[40:41], v[38:39], off offset:192
	v_mul_f32_e32 v38, v52, v36
	v_mul_f32_e32 v39, v53, v36
	v_mul_f32_e32 v37, v55, v36
	v_mul_f32_e32 v36, v54, v36
	v_cvt_pk_bf16_f32 v38, v38, v39
	v_cvt_pk_bf16_f32 v39, v36, v37
	s_mov_b64 s[0:1], 0
	s_and_b64 vcc, exec, s[56:57]
	global_store_dwordx2 v[40:41], v[38:39], off offset:224
	s_cbranch_vccnz .LBB0_89

.LBB0_94:
	s_waitcnt lgkmcnt(8)
	v_lshlrev_b32_e32 v64, 16, v4
	v_and_b32_e32 v65, 0xffff0000, v4
	v_lshlrev_b32_e32 v66, 16, v5
	v_and_b32_e32 v67, 0xffff0000, v5
	v_lshlrev_b32_e32 v68, 16, v6
	v_and_b32_e32 v69, 0xffff0000, v6
	v_lshlrev_b32_e32 v70, 16, v7
	v_and_b32_e32 v71, 0xffff0000, v7
	v_mul_f32_e32 v46, v10, v65
	v_mul_f32_e32 v47, v11, v65
	v_mul_f32_e32 v48, v14, v67
	v_mul_f32_e32 v49, v15, v67
	v_mul_f32_e32 v50, v18, v69
	v_mul_f32_e32 v51, v19, v69
	v_mul_f32_e32 v52, v22, v71
	v_mul_f32_e32 v53, v23, v71
	v_mul_f32_e32 v54, v26, v65
	v_mul_f32_e32 v55, v27, v65
	v_mul_f32_e32 v56, v30, v67
	v_mul_f32_e32 v57, v31, v67
	v_mul_f32_e32 v58, v34, v69
	v_mul_f32_e32 v59, v35, v69
	v_mul_f32_e32 v60, v90, v71
	v_mul_f32_e32 v61, v91, v71
	v_fma_f32 v46, v8, v64, v46
	v_fma_f32 v47, v9, v64, v47
	v_fma_f32 v48, v12, v66, v48
	v_fma_f32 v49, v13, v66, v49
	v_fma_f32 v50, v16, v68, v50
	v_fma_f32 v51, v17, v68, v51
	v_fma_f32 v52, v20, v70, v52
	v_fma_f32 v53, v21, v70, v53
	v_fma_f32 v54, v24, v64, v54
	v_fma_f32 v55, v25, v64, v55
	v_fma_f32 v56, v28, v66, v56
	v_fma_f32 v57, v29, v66, v57
	v_fma_f32 v58, v32, v68, v58
	v_fma_f32 v59, v33, v68, v59
	v_fma_f32 v60, v88, v70, v60
	v_fma_f32 v61, v89, v70, v61
	v_add_f32_e32 v46, v46, v48
	v_add_f32_e32 v47, v47, v49
	v_add_f32_e32 v54, v54, v56
	v_add_f32_e32 v55, v55, v57
	v_add_f32_e32 v46, v46, v50
	v_add_f32_e32 v47, v47, v51
	v_add_f32_e32 v54, v54, v58
	v_add_f32_e32 v55, v55, v59
	v_add_f32_e32 v46, v46, v52
	v_add_f32_e32 v47, v47, v53
	v_add_f32_e32 v54, v54, v60
	v_add_f32_e32 v55, v55, v61
	v_add_f32_e32 v40, v40, v46
	v_add_f32_e32 v41, v41, v47
	v_add_f32_e32 v42, v42, v54
	v_add_f32_e32 v43, v43, v55
	v_add_u32_e32 v202, 16, v202
	v_add_u32_e32 v203, 64, v203
	s_waitcnt lgkmcnt(0)
	ds_read_b128 v[4:7], v202
	ds_read_b128 v[8:11], v203
	ds_read_b128 v[12:15], v203 offset:16
	ds_read_b128 v[16:19], v203 offset:32
	ds_read_b128 v[20:23], v203 offset:48
	ds_read_b128 v[24:27], v203 offset:1024
	ds_read_b128 v[28:31], v203 offset:1040
	ds_read_b128 v[32:35], v203 offset:1056
	ds_read_b128 v[88:91], v203 offset:1072
	v_mul_f32_e32 v46, v94, v65
	v_mul_f32_e32 v47, v95, v65
	v_mul_f32_e32 v48, v98, v67
	v_mul_f32_e32 v49, v99, v67
	v_mul_f32_e32 v50, v102, v69
	v_mul_f32_e32 v51, v103, v69
	v_mul_f32_e32 v52, v106, v71
	v_mul_f32_e32 v53, v107, v71
	v_mul_f32_e32 v54, v110, v65
	v_mul_f32_e32 v55, v111, v65
	v_mul_f32_e32 v56, v114, v67
	v_mul_f32_e32 v57, v115, v67
	v_mul_f32_e32 v58, v196, v69
	v_mul_f32_e32 v59, v197, v69
	v_mul_f32_e32 v60, v200, v71
	v_mul_f32_e32 v61, v201, v71
	v_fma_f32 v46, v92, v64, v46
	v_fma_f32 v47, v93, v64, v47
	v_fma_f32 v48, v96, v66, v48
	v_fma_f32 v49, v97, v66, v49
	v_fma_f32 v50, v100, v68, v50
	v_fma_f32 v51, v101, v68, v51
	v_fma_f32 v52, v104, v70, v52
	v_fma_f32 v53, v105, v70, v53
	v_fma_f32 v54, v108, v64, v54
	v_fma_f32 v55, v109, v64, v55
	v_fma_f32 v56, v112, v66, v56
	v_fma_f32 v57, v113, v66, v57
	v_fma_f32 v58, v194, v68, v58
	v_fma_f32 v59, v195, v68, v59
	v_fma_f32 v60, v198, v70, v60
	v_fma_f32 v61, v199, v70, v61
	v_add_f32_e32 v46, v46, v48
	v_add_f32_e32 v47, v47, v49
	v_add_f32_e32 v54, v54, v56
	v_add_f32_e32 v55, v55, v57
	v_add_f32_e32 v46, v46, v50
	v_add_f32_e32 v47, v47, v51
	v_add_f32_e32 v54, v54, v58
	v_add_f32_e32 v55, v55, v59
	v_add_f32_e32 v46, v46, v52
	v_add_f32_e32 v47, v47, v53
	v_add_f32_e32 v54, v54, v60
	v_add_f32_e32 v55, v55, v61
	v_add_f32_e32 v38, v38, v46
	v_add_f32_e32 v39, v39, v47
	v_add_f32_e32 v36, v36, v54
	v_add_f32_e32 v37, v37, v55
	s_waitcnt lgkmcnt(7)
	ds_read_b128 v[92:95], v203 offset:2048
	ds_read_b128 v[96:99], v203 offset:2064
	ds_read_b128 v[100:103], v203 offset:2080
	ds_read_b128 v[104:107], v203 offset:2096
	ds_read_b128 v[108:111], v203 offset:3072
	ds_read_b128 v[112:115], v203 offset:3088
	ds_read_b128 v[194:197], v203 offset:3104
	ds_read_b128 v[198:201], v203 offset:3120
	s_add_i32 s0, s0, -1
	s_cmp_lg_u32 s0, 0
	s_cbranch_scc1 .LBB0_94
	v_swap_b32 v40, v41

.LBB0_156:
	s_and_b64 vcc, exec, s[8:9]
	s_cbranch_vccz .Lms_inter
	v_mov_b32_e32 v198, v197
	s_nop 1
	v_permlane16_swap_b32_e32 v197, v198
	v_max_f32_e32 v197, v197, v198
	v_mov_b32_e32 v198, v197
	s_nop 1
	v_permlane32_swap_b32_e32 v197, v198
	v_max3_f32 v197, v196, v197, v198
	v_cmp_neq_f32_e32 vcc, s73, v197
	s_nop 1
	v_cndmask_b32_e32 v198, 0, v197, vcc
	v_sub_f32_e32 v196, v196, v198
	v_mul_f32_e32 v199, 0x3e0293ee, v196
	v_mul_f32_e32 v196, 0xbe0293ee, v198
	v_cndmask_b32_e64 v198, v196, v215, s[0:1]
	v_fmamk_f32 v112, v112, 0x3e0293ee, v198
	v_exp_f32_e32 v112, v112
	v_fmamk_f32 v113, v113, 0x3e0293ee, v198
	v_exp_f32_e32 v113, v113
	v_fmamk_f32 v114, v114, 0x3e0293ee, v198
	v_exp_f32_e32 v114, v114
	v_fmamk_f32 v115, v115, 0x3e0293ee, v198
	v_exp_f32_e32 v115, v115
	v_fmamk_f32 v108, v108, 0x3e0293ee, v198
	v_add_f32_e32 v196, 0, v112
	v_exp_f32_e32 v108, v108
	v_fmamk_f32 v109, v109, 0x3e0293ee, v198
	v_add_f32_e32 v196, v113, v196
	v_exp_f32_e32 v109, v109
	v_fmamk_f32 v110, v110, 0x3e0293ee, v198
	v_add_f32_e32 v196, v114, v196
	v_exp_f32_e32 v110, v110
	v_fmamk_f32 v111, v111, 0x3e0293ee, v198
	v_add_f32_e32 v196, v115, v196
	v_exp_f32_e32 v111, v111
	v_fmamk_f32 v104, v104, 0x3e0293ee, v198
	v_add_f32_e32 v196, v108, v196
	v_exp_f32_e32 v104, v104
	v_fmamk_f32 v105, v105, 0x3e0293ee, v198
	v_add_f32_e32 v196, v109, v196
	v_exp_f32_e32 v105, v105
	v_fmamk_f32 v106, v106, 0x3e0293ee, v198
	v_add_f32_e32 v196, v110, v196
	v_exp_f32_e32 v106, v106
	v_fmamk_f32 v107, v107, 0x3e0293ee, v198
	v_add_f32_e32 v196, v111, v196
	v_exp_f32_e32 v107, v107
	v_fmamk_f32 v100, v100, 0x3e0293ee, v198
	v_add_f32_e32 v196, v104, v196
	v_exp_f32_e32 v100, v100
	v_fmamk_f32 v101, v101, 0x3e0293ee, v198
	v_add_f32_e32 v196, v105, v196
	v_exp_f32_e32 v101, v101
	v_fmamk_f32 v102, v102, 0x3e0293ee, v198
	v_add_f32_e32 v196, v106, v196
	v_exp_f32_e32 v102, v102
	v_fmamk_f32 v103, v103, 0x3e0293ee, v198
	v_add_f32_e32 v196, v107, v196
	v_exp_f32_e32 v103, v103
	v_fmamk_f32 v96, v96, 0x3e0293ee, v198
	v_add_f32_e32 v196, v100, v196
	v_exp_f32_e32 v96, v96
	v_fmamk_f32 v97, v97, 0x3e0293ee, v198
	v_add_f32_e32 v196, v101, v196
	v_exp_f32_e32 v97, v97
	v_fmamk_f32 v98, v98, 0x3e0293ee, v198
	v_add_f32_e32 v196, v102, v196
	v_exp_f32_e32 v98, v98
	v_fmamk_f32 v99, v99, 0x3e0293ee, v198
	v_add_f32_e32 v196, v103, v196
	v_exp_f32_e32 v99, v99
	v_fmamk_f32 v92, v92, 0x3e0293ee, v198
	v_add_f32_e32 v196, v96, v196
	v_exp_f32_e32 v92, v92
	v_fmamk_f32 v93, v93, 0x3e0293ee, v198
	v_add_f32_e32 v196, v97, v196
	v_exp_f32_e32 v93, v93
	v_fmamk_f32 v94, v94, 0x3e0293ee, v198
	v_add_f32_e32 v196, v98, v196
	v_exp_f32_e32 v94, v94
	v_fmamk_f32 v95, v95, 0x3e0293ee, v198
	v_add_f32_e32 v196, v99, v196
	v_exp_f32_e32 v95, v95
	v_fmamk_f32 v88, v88, 0x3e0293ee, v198
	v_add_f32_e32 v196, v92, v196
	v_exp_f32_e32 v88, v88
	v_fmamk_f32 v89, v89, 0x3e0293ee, v198
	v_add_f32_e32 v196, v93, v196
	v_exp_f32_e32 v89, v89
	v_fmamk_f32 v90, v90, 0x3e0293ee, v198
	v_add_f32_e32 v196, v94, v196
	v_exp_f32_e32 v90, v90
	v_fmamk_f32 v91, v91, 0x3e0293ee, v198
	v_add_f32_e32 v196, v95, v196
	v_exp_f32_e32 v91, v91
	v_add_f32_e32 v196, v88, v196
	v_add_f32_e32 v196, v89, v196
	v_add_f32_e32 v196, v90, v196
	v_fmamk_f32 v84, v84, 0x3e0293ee, v198
	v_add_f32_e32 v200, v91, v196
	v_exp_f32_e32 v196, v84
	v_fmamk_f32 v85, v85, 0x3e0293ee, v198
	v_exp_f32_e32 v85, v85
	v_fmamk_f32 v86, v86, 0x3e0293ee, v198
	v_exp_f32_e32 v86, v86
	v_fmac_f32_e32 v198, 0x3e0293ee, v87
	v_exp_f32_e32 v87, v198
	v_add_f32_e32 v84, v196, v200
	v_add_f32_e32 v84, v85, v84
	v_add_f32_e32 v84, v86, v84
	v_add_f32_e32 v198, v87, v84
	v_exp_f32_e32 v84, v199
	v_mov_b32_e32 v199, v198
	s_nop 1
	v_permlane16_swap_b32_e32 v198, v199
	v_add_f32_e32 v198, v198, v199
	v_mov_b32_e32 v199, v198
	v_cmp_neq_f32_e32 vcc, 1.0, v84
	s_nop 0
	v_permlane32_swap_b32_e32 v198, v199
	s_cbranch_vccz .LBB0_158

	v_mul_f32_e32 v82, v82, v84
	v_mul_f32_e32 v83, v83, v84
	v_mul_f32_e32 v80, v80, v84
	v_mul_f32_e32 v81, v81, v84
	v_mul_f32_e32 v78, v78, v84
	v_mul_f32_e32 v79, v79, v84
	v_mul_f32_e32 v76, v76, v84
	v_mul_f32_e32 v77, v77, v84
	v_mul_f32_e32 v74, v74, v84
	v_mul_f32_e32 v75, v75, v84
	v_mul_f32_e32 v72, v72, v84
	v_mul_f32_e32 v73, v73, v84
	v_mul_f32_e32 v70, v70, v84
	v_mul_f32_e32 v71, v71, v84
	v_mul_f32_e32 v68, v68, v84
	v_mul_f32_e32 v69, v69, v84
	v_mul_f32_e32 v66, v66, v84
	v_mul_f32_e32 v67, v67, v84
	v_mul_f32_e32 v64, v64, v84
	v_mul_f32_e32 v65, v65, v84
	v_mul_f32_e32 v62, v62, v84
	v_mul_f32_e32 v63, v63, v84
	v_mul_f32_e32 v60, v60, v84
	v_mul_f32_e32 v61, v61, v84
	v_mul_f32_e32 v58, v58, v84
	v_mul_f32_e32 v59, v59, v84
	v_mul_f32_e32 v56, v56, v84
	v_mul_f32_e32 v57, v57, v84
	v_mul_f32_e32 v54, v54, v84
	v_mul_f32_e32 v55, v55, v84
	v_mul_f32_e32 v52, v52, v84
	v_mul_f32_e32 v53, v53, v84
	s_branch .LBB0_158

.Lms_join:
	v_exp_f32_e32 v84, v199
	v_mov_b32_e32 v199, v198
	s_nop 1
	v_permlane16_swap_b32_e32 v198, v199
	v_add_f32_e32 v198, v198, v199
	v_mov_b32_e32 v199, v198
	v_cmp_neq_f32_e32 vcc, 1.0, v84
	s_nop 0
	v_permlane32_swap_b32_e32 v198, v199
	s_cbranch_vccz .LBB0_158

	v_mul_f32_e32 v82, v82, v84
	v_mul_f32_e32 v83, v83, v84
	v_mul_f32_e32 v80, v80, v84
	v_mul_f32_e32 v81, v81, v84
	v_mul_f32_e32 v78, v78, v84
	v_mul_f32_e32 v79, v79, v84
	v_mul_f32_e32 v76, v76, v84
	v_mul_f32_e32 v77, v77, v84
	v_mul_f32_e32 v74, v74, v84
	v_mul_f32_e32 v75, v75, v84
	v_mul_f32_e32 v72, v72, v84
	v_mul_f32_e32 v73, v73, v84
	v_mul_f32_e32 v70, v70, v84
	v_mul_f32_e32 v71, v71, v84
	v_mul_f32_e32 v68, v68, v84
	v_mul_f32_e32 v69, v69, v84
	v_mul_f32_e32 v66, v66, v84
	v_mul_f32_e32 v67, v67, v84
	v_mul_f32_e32 v64, v64, v84
	v_mul_f32_e32 v65, v65, v84
	v_mul_f32_e32 v62, v62, v84
	v_mul_f32_e32 v63, v63, v84
	v_mul_f32_e32 v60, v60, v84
	v_mul_f32_e32 v61, v61, v84
	v_mul_f32_e32 v58, v58, v84
	v_mul_f32_e32 v59, v59, v84
	v_mul_f32_e32 v56, v56, v84
	v_mul_f32_e32 v57, v57, v84
	v_mul_f32_e32 v54, v54, v84
	v_mul_f32_e32 v55, v55, v84
	v_mul_f32_e32 v52, v52, v84
	v_mul_f32_e32 v53, v53, v84

.LBB0_164:
	s_mov_b32 s0, 0x7601400
	s_mov_b32 s1, 0
	v_lshl_add_u64 v[16:17], v[14:15], 0, s[0:1]
	s_add_u32 s0, s0, 0x1e00
	global_load_ushort v108, v[16:17], off
	v_lshl_add_u64 v[18:19], v[14:15], 0, s[0:1]
	s_add_u32 s0, s0, 0x1e00
	global_load_ushort v109, v[18:19], off
	v_lshl_add_u64 v[16:17], v[14:15], 0, s[0:1]
	s_add_u32 s0, s0, 0x1e00
	global_load_ushort v110, v[16:17], off
	v_lshl_add_u64 v[18:19], v[14:15], 0, s[0:1]
	s_add_u32 s0, s0, 0x1e00
	global_load_ushort v111, v[18:19], off
	v_lshl_add_u64 v[16:17], v[14:15], 0, s[0:1]
	s_add_u32 s0, s0, 0x1e00
	global_load_ushort v112, v[16:17], off
	v_lshl_add_u64 v[18:19], v[14:15], 0, s[0:1]
	s_add_u32 s0, s0, 0x1e00
	global_load_ushort v113, v[18:19], off
	v_lshl_add_u64 v[16:17], v[14:15], 0, s[0:1]
	s_add_u32 s0, s0, 0x1e00
	global_load_ushort v114, v[16:17], off
	v_lshl_add_u64 v[18:19], v[14:15], 0, s[0:1]
	s_add_u32 s0, s0, 0x1e00
	global_load_ushort v115, v[18:19], off
	v_lshl_add_u64 v[16:17], v[14:15], 0, s[0:1]
	s_add_u32 s0, s0, 0x1e00
	global_load_ushort v116, v[16:17], off
	v_lshl_add_u64 v[18:19], v[14:15], 0, s[0:1]
	s_add_u32 s0, s0, 0x1e00
	global_load_ushort v117, v[18:19], off
	v_lshl_add_u64 v[16:17], v[14:15], 0, s[0:1]
	s_add_u32 s0, s0, 0x1e00
	global_load_ushort v118, v[16:17], off
	v_lshl_add_u64 v[18:19], v[14:15], 0, s[0:1]
	s_add_u32 s0, s0, 0x1e00
	global_load_ushort v119, v[18:19], off
	v_lshl_add_u64 v[16:17], v[14:15], 0, s[0:1]
	s_add_u32 s0, s0, 0x1e00
	global_load_ushort v120, v[16:17], off
	v_lshl_add_u64 v[18:19], v[14:15], 0, s[0:1]
	s_add_u32 s0, s0, 0x1e00
	global_load_ushort v121, v[18:19], off
	v_lshl_add_u64 v[16:17], v[14:15], 0, s[0:1]
	s_add_u32 s0, s0, 0x1e00
	global_load_ushort v122, v[16:17], off
	v_lshl_add_u64 v[18:19], v[14:15], 0, s[0:1]
	s_add_u32 s0, s0, 0x1e00
	global_load_ushort v123, v[18:19], off
	v_lshl_add_u64 v[16:17], v[14:15], 0, s[0:1]
	s_add_u32 s0, s0, 0x1e00
	global_load_ushort v124, v[16:17], off
	v_lshl_add_u64 v[18:19], v[14:15], 0, s[0:1]
	s_add_u32 s0, s0, 0x1e00
	global_load_ushort v125, v[18:19], off
	v_lshl_add_u64 v[16:17], v[14:15], 0, s[0:1]
	s_add_u32 s0, s0, 0x1e00
	global_load_ushort v126, v[16:17], off
	v_lshl_add_u64 v[18:19], v[14:15], 0, s[0:1]
	s_add_u32 s0, s0, 0x1e00
	global_load_ushort v127, v[18:19], off
	v_lshl_add_u64 v[16:17], v[14:15], 0, s[0:1]
	s_add_u32 s0, s0, 0x1e00
	global_load_ushort v128, v[16:17], off
	v_lshl_add_u64 v[18:19], v[14:15], 0, s[0:1]
	s_add_u32 s0, s0, 0x1e00
	global_load_ushort v129, v[18:19], off
	v_lshl_add_u64 v[16:17], v[14:15], 0, s[0:1]
	s_add_u32 s0, s0, 0x1e00
	global_load_ushort v130, v[16:17], off
	v_lshl_add_u64 v[18:19], v[14:15], 0, s[0:1]
	s_add_u32 s0, s0, 0x1e00
	global_load_ushort v131, v[18:19], off
	v_lshl_add_u64 v[16:17], v[14:15], 0, s[0:1]
	s_add_u32 s0, s0, 0x1e00
	global_load_ushort v132, v[16:17], off
	v_lshl_add_u64 v[18:19], v[14:15], 0, s[0:1]
	s_add_u32 s0, s0, 0x1e00
	global_load_ushort v133, v[18:19], off
	v_lshl_add_u64 v[16:17], v[14:15], 0, s[0:1]
	s_add_u32 s0, s0, 0x1e00
	global_load_ushort v134, v[16:17], off
	v_lshl_add_u64 v[18:19], v[14:15], 0, s[0:1]
	s_add_u32 s0, s0, 0x1e00
	global_load_ushort v135, v[18:19], off
	v_lshl_add_u64 v[16:17], v[14:15], 0, s[0:1]
	s_add_u32 s0, s0, 0x1e00
	global_load_ushort v136, v[16:17], off
	v_lshl_add_u64 v[18:19], v[14:15], 0, s[0:1]
	s_add_u32 s0, s0, 0x1e00
	global_load_ushort v137, v[18:19], off
	v_lshl_add_u64 v[16:17], v[14:15], 0, s[0:1]
	s_add_u32 s0, s0, 0x1e00
	global_load_ushort v138, v[16:17], off
	v_lshl_add_u64 v[18:19], v[14:15], 0, s[0:1]
	s_add_u32 s0, s0, 0x1e00
	global_load_ushort v139, v[18:19], off
	s_waitcnt vmcnt(31)
	v_lshlrev_b32_e32 v108, 16, v108
	v_add_f32_e32 v13, v13, v108
	s_waitcnt vmcnt(30)
	v_lshlrev_b32_e32 v109, 16, v109
	v_add_f32_e32 v13, v13, v109
	s_waitcnt vmcnt(29)
	v_lshlrev_b32_e32 v110, 16, v110
	v_add_f32_e32 v13, v13, v110
	s_waitcnt vmcnt(28)
	v_lshlrev_b32_e32 v111, 16, v111
	v_add_f32_e32 v13, v13, v111
	s_waitcnt vmcnt(27)
	v_lshlrev_b32_e32 v112, 16, v112
	v_add_f32_e32 v13, v13, v112
	s_waitcnt vmcnt(26)
	v_lshlrev_b32_e32 v113, 16, v113
	v_add_f32_e32 v13, v13, v113
	s_waitcnt vmcnt(25)
	v_lshlrev_b32_e32 v114, 16, v114
	v_add_f32_e32 v13, v13, v114
	s_waitcnt vmcnt(24)
	v_lshlrev_b32_e32 v115, 16, v115
	v_add_f32_e32 v13, v13, v115
	s_waitcnt vmcnt(23)
	v_lshlrev_b32_e32 v116, 16, v116
	v_add_f32_e32 v13, v13, v116
	s_waitcnt vmcnt(22)
	v_lshlrev_b32_e32 v117, 16, v117
	v_add_f32_e32 v13, v13, v117
	s_waitcnt vmcnt(21)
	v_lshlrev_b32_e32 v118, 16, v118
	v_add_f32_e32 v13, v13, v118
	s_waitcnt vmcnt(20)
	v_lshlrev_b32_e32 v119, 16, v119
	v_add_f32_e32 v13, v13, v119
	s_waitcnt vmcnt(19)
	v_lshlrev_b32_e32 v120, 16, v120
	v_add_f32_e32 v13, v13, v120
	s_waitcnt vmcnt(18)
	v_lshlrev_b32_e32 v121, 16, v121
	v_add_f32_e32 v13, v13, v121
	s_waitcnt vmcnt(17)
	v_lshlrev_b32_e32 v122, 16, v122
	v_add_f32_e32 v13, v13, v122
	s_waitcnt vmcnt(16)
	v_lshlrev_b32_e32 v123, 16, v123
	v_add_f32_e32 v13, v13, v123
	s_waitcnt vmcnt(15)
	v_lshlrev_b32_e32 v124, 16, v124
	v_add_f32_e32 v13, v13, v124
	s_waitcnt vmcnt(14)
	v_lshlrev_b32_e32 v125, 16, v125
	v_add_f32_e32 v13, v13, v125
	s_waitcnt vmcnt(13)
	v_lshlrev_b32_e32 v126, 16, v126
	v_add_f32_e32 v13, v13, v126
	s_waitcnt vmcnt(12)
	v_lshlrev_b32_e32 v127, 16, v127
	v_add_f32_e32 v13, v13, v127
	s_waitcnt vmcnt(11)
	v_lshlrev_b32_e32 v128, 16, v128
	v_add_f32_e32 v13, v13, v128
	s_waitcnt vmcnt(10)
	v_lshlrev_b32_e32 v129, 16, v129
	v_add_f32_e32 v13, v13, v129
	s_waitcnt vmcnt(9)
	v_lshlrev_b32_e32 v130, 16, v130
	v_add_f32_e32 v13, v13, v130
	s_waitcnt vmcnt(8)
	v_lshlrev_b32_e32 v131, 16, v131
	v_add_f32_e32 v13, v13, v131
	s_waitcnt vmcnt(7)
	v_lshlrev_b32_e32 v132, 16, v132
	v_add_f32_e32 v13, v13, v132
	s_waitcnt vmcnt(6)
	v_lshlrev_b32_e32 v133, 16, v133
	v_add_f32_e32 v13, v13, v133
	s_waitcnt vmcnt(5)
	v_lshlrev_b32_e32 v134, 16, v134
	v_add_f32_e32 v13, v13, v134
	s_waitcnt vmcnt(4)
	v_lshlrev_b32_e32 v135, 16, v135
	v_add_f32_e32 v13, v13, v135
	s_waitcnt vmcnt(3)
	v_lshlrev_b32_e32 v136, 16, v136
	v_add_f32_e32 v13, v13, v136
	s_waitcnt vmcnt(2)
	v_lshlrev_b32_e32 v137, 16, v137
	v_add_f32_e32 v13, v13, v137
	s_waitcnt vmcnt(1)
	v_lshlrev_b32_e32 v138, 16, v138
	v_add_f32_e32 v13, v13, v138
	s_waitcnt vmcnt(0)
	v_lshlrev_b32_e32 v139, 16, v139
	v_add_f32_e32 v13, v13, v139
	v_lshl_add_u64 v[16:17], v[14:15], 0, s[0:1]
	s_add_u32 s0, s0, 0x1e00
	global_load_ushort v108, v[16:17], off
	v_lshl_add_u64 v[18:19], v[14:15], 0, s[0:1]
	s_add_u32 s0, s0, 0x1e00
	global_load_ushort v109, v[18:19], off
	v_lshl_add_u64 v[16:17], v[14:15], 0, s[0:1]
	s_add_u32 s0, s0, 0x1e00
	global_load_ushort v110, v[16:17], off
	v_lshl_add_u64 v[18:19], v[14:15], 0, s[0:1]
	s_add_u32 s0, s0, 0x1e00
	global_load_ushort v111, v[18:19], off
	v_lshl_add_u64 v[16:17], v[14:15], 0, s[0:1]
	s_add_u32 s0, s0, 0x1e00
	global_load_ushort v112, v[16:17], off
	v_lshl_add_u64 v[18:19], v[14:15], 0, s[0:1]
	s_add_u32 s0, s0, 0x1e00
	global_load_ushort v113, v[18:19], off
	v_lshl_add_u64 v[16:17], v[14:15], 0, s[0:1]
	s_add_u32 s0, s0, 0x1e00
	global_load_ushort v114, v[16:17], off
	v_lshl_add_u64 v[18:19], v[14:15], 0, s[0:1]
	s_add_u32 s0, s0, 0x1e00
	global_load_ushort v115, v[18:19], off
	v_lshl_add_u64 v[16:17], v[14:15], 0, s[0:1]
	s_add_u32 s0, s0, 0x1e00
	global_load_ushort v116, v[16:17], off
	v_lshl_add_u64 v[18:19], v[14:15], 0, s[0:1]
	s_add_u32 s0, s0, 0x1e00
	global_load_ushort v117, v[18:19], off
	v_lshl_add_u64 v[16:17], v[14:15], 0, s[0:1]
	s_add_u32 s0, s0, 0x1e00
	global_load_ushort v118, v[16:17], off
	v_lshl_add_u64 v[18:19], v[14:15], 0, s[0:1]
	s_add_u32 s0, s0, 0x1e00
	global_load_ushort v119, v[18:19], off
	v_lshl_add_u64 v[16:17], v[14:15], 0, s[0:1]
	s_add_u32 s0, s0, 0x1e00
	global_load_ushort v120, v[16:17], off
	v_lshl_add_u64 v[18:19], v[14:15], 0, s[0:1]
	s_add_u32 s0, s0, 0x1e00
	global_load_ushort v121, v[18:19], off
	v_lshl_add_u64 v[16:17], v[14:15], 0, s[0:1]
	s_add_u32 s0, s0, 0x1e00
	global_load_ushort v122, v[16:17], off
	v_lshl_add_u64 v[18:19], v[14:15], 0, s[0:1]
	s_add_u32 s0, s0, 0x1e00
	global_load_ushort v123, v[18:19], off
	v_lshl_add_u64 v[16:17], v[14:15], 0, s[0:1]
	s_add_u32 s0, s0, 0x1e00
	global_load_ushort v124, v[16:17], off
	v_lshl_add_u64 v[18:19], v[14:15], 0, s[0:1]
	s_add_u32 s0, s0, 0x1e00
	global_load_ushort v125, v[18:19], off
	v_lshl_add_u64 v[16:17], v[14:15], 0, s[0:1]
	s_add_u32 s0, s0, 0x1e00
	global_load_ushort v126, v[16:17], off
	v_lshl_add_u64 v[18:19], v[14:15], 0, s[0:1]
	s_add_u32 s0, s0, 0x1e00
	global_load_ushort v127, v[18:19], off
	v_lshl_add_u64 v[16:17], v[14:15], 0, s[0:1]
	s_add_u32 s0, s0, 0x1e00
	global_load_ushort v128, v[16:17], off
	v_lshl_add_u64 v[18:19], v[14:15], 0, s[0:1]
	s_add_u32 s0, s0, 0x1e00
	global_load_ushort v129, v[18:19], off
	v_lshl_add_u64 v[16:17], v[14:15], 0, s[0:1]
	s_add_u32 s0, s0, 0x1e00
	global_load_ushort v130, v[16:17], off
	v_lshl_add_u64 v[18:19], v[14:15], 0, s[0:1]
	s_add_u32 s0, s0, 0x1e00
	global_load_ushort v131, v[18:19], off
	v_lshl_add_u64 v[16:17], v[14:15], 0, s[0:1]
	s_add_u32 s0, s0, 0x1e00
	global_load_ushort v132, v[16:17], off
	v_lshl_add_u64 v[18:19], v[14:15], 0, s[0:1]
	s_add_u32 s0, s0, 0x1e00
	global_load_ushort v133, v[18:19], off
	v_lshl_add_u64 v[16:17], v[14:15], 0, s[0:1]
	s_add_u32 s0, s0, 0x1e00
	global_load_ushort v134, v[16:17], off
	v_lshl_add_u64 v[18:19], v[14:15], 0, s[0:1]
	s_add_u32 s0, s0, 0x1e00
	global_load_ushort v135, v[18:19], off
	v_lshl_add_u64 v[16:17], v[14:15], 0, s[0:1]
	s_add_u32 s0, s0, 0x1e00
	global_load_ushort v136, v[16:17], off
	v_lshl_add_u64 v[18:19], v[14:15], 0, s[0:1]
	s_add_u32 s0, s0, 0x1e00
	global_load_ushort v137, v[18:19], off
	v_lshl_add_u64 v[16:17], v[14:15], 0, s[0:1]
	s_add_u32 s0, s0, 0x1e00
	global_load_ushort v138, v[16:17], off
	v_lshl_add_u64 v[18:19], v[14:15], 0, s[0:1]
	s_add_u32 s0, s0, 0x1e00
	global_load_ushort v139, v[18:19], off
	s_waitcnt vmcnt(31)
	v_lshlrev_b32_e32 v108, 16, v108
	v_add_f32_e32 v13, v13, v108
	s_waitcnt vmcnt(30)
	v_lshlrev_b32_e32 v109, 16, v109
	v_add_f32_e32 v13, v13, v109
	s_waitcnt vmcnt(29)
	v_lshlrev_b32_e32 v110, 16, v110
	v_add_f32_e32 v13, v13, v110
	s_waitcnt vmcnt(28)
	v_lshlrev_b32_e32 v111, 16, v111
	v_add_f32_e32 v13, v13, v111
	s_waitcnt vmcnt(27)
	v_lshlrev_b32_e32 v112, 16, v112
	v_add_f32_e32 v13, v13, v112
	s_waitcnt vmcnt(26)
	v_lshlrev_b32_e32 v113, 16, v113
	v_add_f32_e32 v13, v13, v113
	s_waitcnt vmcnt(25)
	v_lshlrev_b32_e32 v114, 16, v114
	v_add_f32_e32 v13, v13, v114
	s_waitcnt vmcnt(24)
	v_lshlrev_b32_e32 v115, 16, v115
	v_add_f32_e32 v13, v13, v115
	s_waitcnt vmcnt(23)
	v_lshlrev_b32_e32 v116, 16, v116
	v_add_f32_e32 v13, v13, v116
	s_waitcnt vmcnt(22)
	v_lshlrev_b32_e32 v117, 16, v117
	v_add_f32_e32 v13, v13, v117
	s_waitcnt vmcnt(21)
	v_lshlrev_b32_e32 v118, 16, v118
	v_add_f32_e32 v13, v13, v118
	s_waitcnt vmcnt(20)
	v_lshlrev_b32_e32 v119, 16, v119
	v_add_f32_e32 v13, v13, v119
	s_waitcnt vmcnt(19)
	v_lshlrev_b32_e32 v120, 16, v120
	v_add_f32_e32 v13, v13, v120
	s_waitcnt vmcnt(18)
	v_lshlrev_b32_e32 v121, 16, v121
	v_add_f32_e32 v13, v13, v121
	s_waitcnt vmcnt(17)
	v_lshlrev_b32_e32 v122, 16, v122
	v_add_f32_e32 v13, v13, v122
	s_waitcnt vmcnt(16)
	v_lshlrev_b32_e32 v123, 16, v123
	v_add_f32_e32 v13, v13, v123
	s_waitcnt vmcnt(15)
	v_lshlrev_b32_e32 v124, 16, v124
	v_add_f32_e32 v13, v13, v124
	s_waitcnt vmcnt(14)
	v_lshlrev_b32_e32 v125, 16, v125
	v_add_f32_e32 v13, v13, v125
	s_waitcnt vmcnt(13)
	v_lshlrev_b32_e32 v126, 16, v126
	v_add_f32_e32 v13, v13, v126
	s_waitcnt vmcnt(12)
	v_lshlrev_b32_e32 v127, 16, v127
	v_add_f32_e32 v13, v13, v127
	s_waitcnt vmcnt(11)
	v_lshlrev_b32_e32 v128, 16, v128
	v_add_f32_e32 v13, v13, v128
	s_waitcnt vmcnt(10)
	v_lshlrev_b32_e32 v129, 16, v129
	v_add_f32_e32 v13, v13, v129
	s_waitcnt vmcnt(9)
	v_lshlrev_b32_e32 v130, 16, v130
	v_add_f32_e32 v13, v13, v130
	s_waitcnt vmcnt(8)
	v_lshlrev_b32_e32 v131, 16, v131
	v_add_f32_e32 v13, v13, v131
	s_waitcnt vmcnt(7)
	v_lshlrev_b32_e32 v132, 16, v132
	v_add_f32_e32 v13, v13, v132
	s_waitcnt vmcnt(6)
	v_lshlrev_b32_e32 v133, 16, v133
	v_add_f32_e32 v13, v13, v133
	s_waitcnt vmcnt(5)
	v_lshlrev_b32_e32 v134, 16, v134
	v_add_f32_e32 v13, v13, v134
	s_waitcnt vmcnt(4)
	v_lshlrev_b32_e32 v135, 16, v135
	v_add_f32_e32 v13, v13, v135
	s_waitcnt vmcnt(3)
	v_lshlrev_b32_e32 v136, 16, v136
	v_add_f32_e32 v13, v13, v136
	s_waitcnt vmcnt(2)
	v_lshlrev_b32_e32 v137, 16, v137
	v_add_f32_e32 v13, v13, v137
	s_waitcnt vmcnt(1)
	v_lshlrev_b32_e32 v138, 16, v138
	v_add_f32_e32 v13, v13, v138
	s_waitcnt vmcnt(0)
	v_lshlrev_b32_e32 v139, 16, v139
	v_add_f32_e32 v13, v13, v139
	ds_write_b32 v59, v13
	s_waitcnt lgkmcnt(0)
	s_barrier
	s_and_saveexec_b64 s[0:1], s[6:7]
	s_cbranch_execz .LBB0_167
	ds_read2st64_b32 v[14:15], v59 offset1:2
	ds_read2st64_b32 v[16:17], v59 offset0:4 offset1:6
	s_and_b32 s17, s10, 0xffffff80
	s_lshl_b32 s15, s15, 5
	s_or_b32 s15, s15, s17
	s_waitcnt lgkmcnt(1)
	v_mov_b32_e32 v18, v14
	s_waitcnt lgkmcnt(0)
	v_mov_b32_e32 v19, v16
	v_mov_b32_e32 v16, v15
	s_or_b32 s14, s15, s14
	v_add_f32_e32 v14, v18, v16
	v_add_f32_e32 v15, v19, v17
	s_ashr_i32 s15, s14, 31
	v_add_f32_e32 v13, v14, v15
	s_lshl_b64 s[14:15], s[14:15], 9
	v_mul_f32_e32 v13, 0x3b800000, v13
	v_lshl_add_u64 v[14:15], v[4:5], 0, s[14:15]
	global_store_dword v[14:15], v13, off

.LBB0_175:
	s_ashr_i32 s0, s62, 7
	s_ashr_i32 s1, s0, 31
	s_lshl_b64 s[64:65], s[0:1], 13
	s_lshl_b32 s0, s62, 8
	s_and_b32 s0, s0, 0x1f00
	s_bfe_u32 s4, s62, 0x20005
	s_or_b32 s64, s64, s0
	s_barrier
	s_mov_b64 s[6:7], exec
	v_readlane_b32 s0, v255, 0
	v_readlane_b32 s1, v255, 1
	s_and_b64 s[0:1], s[6:7], s[0:1]
	s_mov_b64 exec, s[0:1]
	s_cbranch_execz .LBB0_194
	v_mov_b32_e32 v5, s65
	v_or_b32_e32 v4, s64, v118
	v_readlane_b32 s0, v254, 52
	v_lshlrev_b64 v[6:7], 5, v[4:5]
	v_readlane_b32 s1, v254, 53
	s_lshl_b32 s20, s4, 2
	v_mov_b32_e32 v10, s20
	v_lshl_add_u64 v[6:7], s[0:1], 0, v[6:7]
	v_lshl_add_u64 v[8:9], v[6:7], 0, s[20:21]
	global_load_dword v6, v[8:9], off offset:16
	v_readlane_b32 s0, v254, 62
	v_readlane_b32 s1, v254, 63
	s_nop 4
	global_load_dword v14, v10, s[0:1] offset:16
	global_load_dword v7, v10, s[0:1]
	global_load_dword v16, v[8:9], off
	s_waitcnt vmcnt(2)
	v_add_f32_e32 v8, v14, v6
	v_cmp_le_f32_e32 vcc, 0, v8
	s_and_saveexec_b64 s[0:1], vcc
	s_xor_b64 s[0:1], exec, s[0:1]
	s_cbranch_execz .LBB0_178
	v_mul_f32_e32 v6, 0xbfb8aa3b, v8
	v_exp_f32_e32 v6, v6
	s_mov_b32 s5, 0x3f2aaaab
	v_add_f32_e32 v10, 1.0, v6
	v_frexp_mant_f32_e32 v12, v10
	v_cvt_f64_f32_e32 v[8:9], v10
	v_frexp_exp_i32_f64_e32 v8, v[8:9]
	v_cmp_gt_f32_e32 vcc, s5, v12
	v_add_f32_e32 v11, -1.0, v10
	v_sub_f32_e32 v13, v11, v10
	v_subbrev_co_u32_e32 v15, vcc, 0, v8, vcc
	v_sub_u32_e32 v8, 0, v15
	v_sub_f32_e32 v11, v6, v11
	v_add_f32_e32 v13, 1.0, v13
	v_ldexp_f32 v9, v10, v8
	v_add_f32_e32 v11, v11, v13
	v_add_f32_e32 v10, -1.0, v9
	v_add_f32_e32 v12, 1.0, v9
	v_ldexp_f32 v8, v11, v8
	v_add_f32_e32 v11, 1.0, v10
	v_add_f32_e32 v13, -1.0, v12
	v_sub_f32_e32 v11, v9, v11
	v_sub_f32_e32 v9, v9, v13
	v_add_f32_e32 v11, v8, v11
	v_add_f32_e32 v8, v8, v9
	v_add_f32_e32 v17, v12, v8
	v_rcp_f32_e32 v21, v17
	v_sub_f32_e32 v9, v17, v12
	v_sub_f32_e32 v20, v8, v9
	v_add_f32_e32 v9, v10, v11
	v_mul_f32_e32 v23, v9, v21
	v_sub_f32_e32 v8, v9, v10
	v_mul_f32_e32 v10, v17, v23
	v_fma_f32 v12, v23, v17, -v10
	v_fmac_f32_e32 v12, v23, v20
	v_sub_f32_e32 v22, v11, v8
	v_add_f32_e32 v8, v10, v12
	v_sub_f32_e32 v11, v9, v8
	v_add_f32_e64 v18, v8, -v10
	v_add_f32_e64 v19, v9, -v11
	v_mov_b32_e32 v13, v8
	v_add_f32_e64 v8, v18, -v12
	v_add_f32_e64 v9, v19, -v13
	s_mov_b32 s5, 0x3f317218
	v_add_f32_e32 v9, v22, v9
	v_add_f32_e32 v8, v8, v9
	v_add_f32_e32 v9, v11, v8
	v_mul_f32_e32 v22, v21, v9
	v_mul_f32_e32 v10, v17, v22
	v_fma_f32 v12, v22, v17, -v10
	v_fmac_f32_e32 v12, v22, v20
	v_sub_f32_e32 v11, v11, v9
	v_add_f32_e32 v17, v8, v11
	v_add_f32_e32 v8, v10, v12
	v_sub_f32_e32 v11, v9, v8
	v_add_f32_e64 v18, v8, -v10
	v_add_f32_e64 v19, v9, -v11
	v_mov_b32_e32 v13, v8
	v_add_f32_e64 v8, v18, -v12
	v_add_f32_e64 v9, v19, -v13
	v_cmp_neq_f32_e32 vcc, s2, v6
	v_add_f32_e32 v9, v17, v9
	v_add_f32_e32 v8, v8, v9
	v_add_f32_e32 v9, v23, v22
	v_add_f32_e32 v8, v11, v8
	v_sub_f32_e32 v10, v9, v23
	v_mul_f32_e32 v8, v21, v8
	v_sub_f32_e32 v10, v22, v10
	v_add_f32_e32 v10, v10, v8
	v_add_f32_e32 v12, v9, v10
	v_mul_f32_e32 v13, v12, v12
	v_fmamk_f32 v8, v13, 0x3e9b6dac, v210
	v_fmaak_f32 v175, v13, v8, 0x3f2aaada
	v_cvt_f32_i32_e32 v8, v15
	v_sub_f32_e32 v9, v12, v9
	v_sub_f32_e32 v9, v10, v9
	v_ldexp_f32 v15, v9, 1
	v_mul_f32_e32 v9, v12, v13
	v_ldexp_f32 v11, v12, 1
	v_mul_f32_e32 v12, v8, v174
	v_mul_f32_e32 v13, v9, v175
	s_nop 0
	v_fma_f32 v10, v8, s5, -v12
	v_fmac_f32_e32 v10, 0xb102e308, v8
	v_add_f32_e32 v8, v12, v10
	v_add_f32_e32 v9, v13, v11
	v_mov_b32_e32 v18, v12
	v_sub_f32_e32 v11, v9, v11
	v_sub_f32_e32 v11, v13, v11
	v_add_f32_e32 v19, v15, v11
	v_add_f32_e64 v12, v8, -v12
	v_add_f32_e64 v13, v9, -v13
	v_add_f32_e32 v20, v8, v18
	v_add_f32_e32 v21, v9, v19
	v_mov_b32_e32 v11, v8
	v_mov_b32_e32 v13, v21
	v_add_f32_e64 v22, v10, -v12
	v_add_f32_e64 v23, v11, -v13
	v_add_f32_e32 v10, v10, v12
	v_add_f32_e32 v11, v11, v13
	v_mov_b32_e32 v18, v19
	v_add_f32_e64 v12, v11, -v8
	v_add_f32_e64 v13, v10, -v9
	v_add_f32_e64 v24, v20, -v12
	v_add_f32_e64 v25, v21, -v12
	v_mov_b32_e32 v20, v21
	v_mov_b32_e32 v21, v11
	v_pk_mov_b32 v[12:13], v[8:9], v[12:13] op_sel:[1,0]
	v_mov_b32_e32 v19, v8
	v_add_f32_e64 v12, v20, -v12
	v_add_f32_e64 v13, v21, -v13
	v_mov_b32_e32 v24, v22
	v_add_f32_e64 v8, v18, -v12
	v_add_f32_e64 v9, v19, -v13
	v_mov_b32_e32 v23, v11
	v_add_f32_e32 v12, v24, v8
	v_add_f32_e32 v13, v25, v9
	s_mov_b32 s5, 0x33800000
	v_add_f32_e32 v18, v12, v13
	v_add_f32_e32 v19, v13, v12
	s_nop 0
	v_pk_add_f32 v[10:11], v[10:11], v[18:19] op_sel:[1,0] op_sel_hi:[0,1]
	v_mov_b32_e32 v13, v10
	v_add_f32_e64 v20, v12, -v22
	v_add_f32_e64 v21, v13, -v23
	v_mov_b32_e32 v9, v18
	v_sub_f32_e32 v11, v12, v20
	v_add_f32_e64 v8, v8, -v20
	v_add_f32_e64 v9, v9, -v21
	v_sub_f32_e32 v11, v22, v11
	v_add_f32_e32 v8, v8, v11
	v_add_f32_e32 v8, v8, v9
	v_add_f32_e32 v8, v10, v8
	v_cndmask_b32_e32 v8, v219, v8, vcc
	v_cmp_ngt_f32_e32 vcc, -1.0, v6
	s_nop 1
	v_cndmask_b32_e32 v8, v220, v8, vcc
	v_cmp_neq_f32_e32 vcc, -1.0, v6
	s_nop 1
	v_cndmask_b32_e32 v8, v215, v8, vcc
	v_cmp_lt_f32_e64 vcc, |v6|, s5
	s_nop 1
	v_cndmask_b32_e32 v6, v8, v6, vcc
	v_xor_b32_e32 v6, 0x80000000, v6
.LBB0_178:
	s_andn2_saveexec_b64 s[0:1], s[0:1]
	s_cbranch_execz .LBB0_180
	v_mul_f32_e32 v6, 0x3fb8aa3b, v8
	v_exp_f32_e32 v6, v6
	s_mov_b32 s5, 0x3f2aaaab
	v_add_f32_e32 v9, 1.0, v6
	v_add_f32_e32 v12, -1.0, v9
	v_frexp_mant_f32_e32 v13, v9
	v_cvt_f64_f32_e32 v[10:11], v9
	v_sub_f32_e32 v15, v12, v9
	v_sub_f32_e32 v12, v6, v12
	v_add_f32_e32 v15, 1.0, v15
	v_frexp_exp_i32_f64_e32 v10, v[10:11]
	v_cmp_gt_f32_e32 vcc, s5, v13
	v_add_f32_e32 v12, v12, v15
	s_mov_b32 s5, 0x3f317218
	v_subbrev_co_u32_e32 v15, vcc, 0, v10, vcc
	v_sub_u32_e32 v10, 0, v15
	v_ldexp_f32 v9, v9, v10
	v_ldexp_f32 v10, v12, v10
	v_add_f32_e32 v12, -1.0, v9
	v_add_f32_e32 v11, 1.0, v12
	v_sub_f32_e32 v11, v9, v11
	v_add_f32_e32 v13, v10, v11
	v_add_f32_e32 v11, 1.0, v9
	v_add_f32_e32 v17, -1.0, v11
	v_sub_f32_e32 v9, v9, v17
	v_add_f32_e32 v9, v10, v9
	v_add_f32_e32 v17, v11, v9
	v_rcp_f32_e32 v22, v17
	v_sub_f32_e32 v10, v17, v11
	v_add_f32_e32 v11, v12, v13
	v_sub_f32_e32 v9, v9, v10
	v_mul_f32_e32 v24, v11, v22
	v_sub_f32_e32 v10, v11, v12
	v_mul_f32_e32 v12, v17, v24
	v_fma_f32 v18, v24, v17, -v12
	v_fmac_f32_e32 v18, v24, v9
	v_sub_f32_e32 v23, v13, v10
	v_add_f32_e32 v10, v12, v18
	v_sub_f32_e32 v13, v11, v10
	v_add_f32_e64 v20, v10, -v12
	v_add_f32_e64 v21, v11, -v13
	v_mov_b32_e32 v19, v10
	v_add_f32_e64 v10, v20, -v18
	v_add_f32_e64 v11, v21, -v19
	v_cmp_neq_f32_e32 vcc, s2, v6
	v_add_f32_e32 v11, v23, v11
	v_add_f32_e32 v10, v10, v11
	v_add_f32_e32 v11, v13, v10
	v_mul_f32_e32 v23, v22, v11
	v_mul_f32_e32 v12, v17, v23
	v_fma_f32 v18, v23, v17, -v12
	v_fmac_f32_e32 v18, v23, v9
	v_sub_f32_e32 v9, v13, v11
	v_add_f32_e32 v9, v10, v9
	v_add_f32_e32 v10, v12, v18
	v_sub_f32_e32 v13, v11, v10
	v_add_f32_e64 v20, v10, -v12
	v_add_f32_e64 v21, v11, -v13
	v_mov_b32_e32 v19, v10
	v_add_f32_e64 v10, v20, -v18
	v_add_f32_e64 v11, v21, -v19
	s_nop 0
	v_add_f32_e32 v9, v9, v11
	v_add_f32_e32 v9, v10, v9
	v_add_f32_e32 v11, v24, v23
	v_add_f32_e32 v9, v13, v9
	v_sub_f32_e32 v10, v11, v24
	v_mul_f32_e32 v9, v22, v9
	v_sub_f32_e32 v10, v23, v10
	v_add_f32_e32 v9, v10, v9
	v_add_f32_e32 v12, v11, v9
	v_mul_f32_e32 v17, v12, v12
	v_fmamk_f32 v10, v17, 0x3e9b6dac, v210
	v_fmaak_f32 v175, v17, v10, 0x3f2aaada
	v_cvt_f32_i32_e32 v10, v15
	v_sub_f32_e32 v11, v12, v11
	v_sub_f32_e32 v9, v9, v11
	v_mul_f32_e32 v11, v12, v17
	v_mul_f32_e32 v18, v10, v174
	v_mul_f32_e32 v19, v11, v175
	v_ldexp_f32 v13, v12, 1
	v_fma_f32 v12, v10, s5, -v18
	v_fmac_f32_e32 v12, 0xb102e308, v10
	v_add_f32_e32 v10, v18, v12
	v_add_f32_e32 v11, v19, v13
	v_ldexp_f32 v9, v9, 1
	v_sub_f32_e32 v13, v11, v13
	v_sub_f32_e32 v13, v19, v13
	v_add_f32_e32 v21, v9, v13
	v_mov_b32_e32 v20, v18
	v_add_f32_e64 v18, v10, -v18
	v_add_f32_e64 v19, v11, -v19
	v_add_f32_e32 v22, v10, v20
	v_add_f32_e32 v23, v11, v21
	v_mov_b32_e32 v13, v10
	v_mov_b32_e32 v19, v23
	v_add_f32_e64 v24, v12, -v18
	v_add_f32_e64 v25, v13, -v19
	v_add_f32_e32 v12, v12, v18
	v_add_f32_e32 v13, v13, v19
	v_mov_b32_e32 v20, v21
	v_add_f32_e64 v18, v13, -v10
	v_add_f32_e64 v19, v12, -v11
	v_add_f32_e64 v26, v22, -v18
	v_add_f32_e64 v27, v23, -v18
	v_mov_b32_e32 v22, v23
	v_mov_b32_e32 v23, v13
	v_pk_mov_b32 v[18:19], v[10:11], v[18:19] op_sel:[1,0]
	v_mov_b32_e32 v21, v10
	v_add_f32_e64 v18, v22, -v18
	v_add_f32_e64 v19, v23, -v19
	v_mov_b32_e32 v26, v24
	v_add_f32_e64 v10, v20, -v18
	v_add_f32_e64 v11, v21, -v19
	v_mov_b32_e32 v25, v13
	v_add_f32_e32 v18, v26, v10
	v_add_f32_e32 v19, v27, v11
	s_mov_b32 s5, 0x33800000
	v_add_f32_e32 v20, v18, v19
	v_add_f32_e32 v21, v19, v18
	s_nop 0
	v_pk_add_f32 v[12:13], v[12:13], v[20:21] op_sel:[1,0] op_sel_hi:[0,1]
	v_mov_b32_e32 v19, v12
	v_add_f32_e64 v22, v18, -v24
	v_add_f32_e64 v23, v19, -v25
	v_mov_b32_e32 v11, v20
	v_sub_f32_e32 v9, v18, v22
	v_add_f32_e64 v10, v10, -v22
	v_add_f32_e64 v11, v11, -v23
	v_sub_f32_e32 v9, v24, v9
	v_add_f32_e32 v9, v10, v9
	v_add_f32_e32 v9, v9, v11
	v_add_f32_e32 v9, v12, v9
	v_cndmask_b32_e32 v9, v219, v9, vcc
	v_cmp_ngt_f32_e32 vcc, -1.0, v6
	s_nop 1
	v_cndmask_b32_e32 v9, v220, v9, vcc
	v_cmp_neq_f32_e32 vcc, -1.0, v6
	s_nop 1
	v_cndmask_b32_e32 v9, v215, v9, vcc
	v_cmp_lt_f32_e64 vcc, |v6|, s5
	s_nop 1
	v_cndmask_b32_e32 v6, v9, v6, vcc
	v_sub_f32_e32 v6, v8, v6
.LBB0_180:
	s_or_b64 exec, exec, s[0:1]
	v_mov_b32_e32 v9, s65
	v_or_b32_e32 v8, s64, v126
	v_readlane_b32 s0, v254, 52
	v_lshlrev_b64 v[10:11], 5, v[8:9]
	v_readlane_b32 s1, v254, 53
	s_nop 1
	v_lshl_add_u64 v[10:11], s[0:1], 0, v[10:11]
	v_lshl_add_u64 v[10:11], v[10:11], 0, s[20:21]
	global_load_dword v12, v[10:11], off offset:16
	global_load_dword v17, v[10:11], off
	s_waitcnt vmcnt(1)
	v_add_f32_e32 v10, v14, v12
	v_cmp_le_f32_e32 vcc, 0, v10
	s_and_saveexec_b64 s[0:1], vcc
	s_xor_b64 s[0:1], exec, s[0:1]
	s_cbranch_execz .LBB0_182
	v_mul_f32_e32 v10, 0xbfb8aa3b, v10
	v_exp_f32_e32 v15, v10
	s_mov_b32 s5, 0x3f2aaaab
	v_add_f32_e32 v12, 1.0, v15
	v_frexp_mant_f32_e32 v18, v12
	v_cvt_f64_f32_e32 v[10:11], v12
	v_frexp_exp_i32_f64_e32 v10, v[10:11]
	v_cmp_gt_f32_e32 vcc, s5, v18
	v_add_f32_e32 v13, -1.0, v12
	v_sub_f32_e32 v19, v13, v12
	v_subbrev_co_u32_e32 v22, vcc, 0, v10, vcc
	v_sub_u32_e32 v10, 0, v22
	v_sub_f32_e32 v13, v15, v13
	v_add_f32_e32 v19, 1.0, v19
	v_ldexp_f32 v11, v12, v10
	v_add_f32_e32 v13, v13, v19
	v_add_f32_e32 v12, -1.0, v11
	v_add_f32_e32 v18, 1.0, v11
	v_ldexp_f32 v10, v13, v10
	v_add_f32_e32 v13, 1.0, v12
	v_add_f32_e32 v19, -1.0, v18
	v_sub_f32_e32 v13, v11, v13
	v_sub_f32_e32 v11, v11, v19
	v_add_f32_e32 v13, v10, v13
	v_add_f32_e32 v10, v10, v11
	v_add_f32_e32 v23, v18, v10
	v_rcp_f32_e32 v25, v23
	v_sub_f32_e32 v11, v23, v18
	v_sub_f32_e32 v24, v10, v11
	v_add_f32_e32 v11, v12, v13
	v_mul_f32_e32 v27, v11, v25
	v_sub_f32_e32 v10, v11, v12
	v_mul_f32_e32 v12, v23, v27
	v_fma_f32 v18, v27, v23, -v12
	v_fmac_f32_e32 v18, v27, v24
	v_sub_f32_e32 v26, v13, v10
	v_add_f32_e32 v10, v12, v18
	v_sub_f32_e32 v13, v11, v10
	v_add_f32_e64 v20, v10, -v12
	v_add_f32_e64 v21, v11, -v13
	v_mov_b32_e32 v19, v10
	v_add_f32_e64 v10, v20, -v18
	v_add_f32_e64 v11, v21, -v19
	s_mov_b32 s5, 0x3f317218
	v_add_f32_e32 v11, v26, v11
	v_add_f32_e32 v10, v10, v11
	v_add_f32_e32 v11, v13, v10
	v_mul_f32_e32 v26, v25, v11
	v_mul_f32_e32 v12, v23, v26
	v_fma_f32 v18, v26, v23, -v12
	v_fmac_f32_e32 v18, v26, v24
	v_sub_f32_e32 v13, v13, v11
	v_add_f32_e32 v23, v10, v13
	v_add_f32_e32 v10, v12, v18
	v_sub_f32_e32 v13, v11, v10
	v_add_f32_e64 v20, v10, -v12
	v_add_f32_e64 v21, v11, -v13
	v_mov_b32_e32 v19, v10
	v_add_f32_e64 v10, v20, -v18
	v_add_f32_e64 v11, v21, -v19
	v_cmp_neq_f32_e32 vcc, s2, v15
	v_add_f32_e32 v11, v23, v11
	v_add_f32_e32 v10, v10, v11
	v_add_f32_e32 v11, v27, v26
	v_add_f32_e32 v10, v13, v10
	v_sub_f32_e32 v12, v11, v27
	v_mul_f32_e32 v10, v25, v10
	v_sub_f32_e32 v12, v26, v12
	v_add_f32_e32 v12, v12, v10
	v_add_f32_e32 v18, v11, v12
	v_mul_f32_e32 v19, v18, v18
	v_fmamk_f32 v10, v19, 0x3e9b6dac, v210
	v_fmaak_f32 v175, v19, v10, 0x3f2aaada
	v_cvt_f32_i32_e32 v10, v22
	v_sub_f32_e32 v11, v18, v11
	v_sub_f32_e32 v11, v12, v11
	v_ldexp_f32 v20, v11, 1
	v_mul_f32_e32 v11, v18, v19
	v_ldexp_f32 v13, v18, 1
	v_mul_f32_e32 v18, v10, v174
	v_mul_f32_e32 v19, v11, v175
	s_nop 0
	v_fma_f32 v12, v10, s5, -v18
	v_fmac_f32_e32 v12, 0xb102e308, v10
	v_add_f32_e32 v10, v18, v12
	v_add_f32_e32 v11, v19, v13
	s_mov_b32 s5, 0x33800000
	v_sub_f32_e32 v13, v11, v13
	v_sub_f32_e32 v13, v19, v13
	v_add_f32_e32 v21, v20, v13
	v_mov_b32_e32 v20, v18
	v_add_f32_e64 v18, v10, -v18
	v_add_f32_e64 v19, v11, -v19
	v_add_f32_e32 v22, v10, v20
	v_add_f32_e32 v23, v11, v21
	v_mov_b32_e32 v13, v10
	v_mov_b32_e32 v19, v23
	v_add_f32_e64 v24, v12, -v18
	v_add_f32_e64 v25, v13, -v19
	v_add_f32_e32 v12, v12, v18
	v_add_f32_e32 v13, v13, v19
	v_mov_b32_e32 v20, v21
	v_add_f32_e64 v18, v13, -v10
	v_add_f32_e64 v19, v12, -v11
	v_add_f32_e64 v26, v22, -v18
	v_add_f32_e64 v27, v23, -v18
	v_mov_b32_e32 v22, v23
	v_mov_b32_e32 v23, v13
	v_pk_mov_b32 v[18:19], v[10:11], v[18:19] op_sel:[1,0]
	v_mov_b32_e32 v21, v10
	v_add_f32_e64 v18, v22, -v18
	v_add_f32_e64 v19, v23, -v19
	v_mov_b32_e32 v26, v24
	v_add_f32_e64 v10, v20, -v18
	v_add_f32_e64 v11, v21, -v19
	v_mov_b32_e32 v25, v13
	v_add_f32_e32 v18, v26, v10
	v_add_f32_e32 v19, v27, v11
	s_nop 0
	v_add_f32_e32 v20, v18, v19
	v_add_f32_e32 v21, v19, v18
	s_nop 0
	v_pk_add_f32 v[12:13], v[12:13], v[20:21] op_sel:[1,0] op_sel_hi:[0,1]
	v_mov_b32_e32 v19, v12
	v_add_f32_e64 v22, v18, -v24
	v_add_f32_e64 v23, v19, -v25
	v_mov_b32_e32 v11, v20
	v_sub_f32_e32 v13, v18, v22
	v_add_f32_e64 v10, v10, -v22
	v_add_f32_e64 v11, v11, -v23
	v_sub_f32_e32 v13, v24, v13
	v_add_f32_e32 v10, v10, v13
	v_add_f32_e32 v10, v10, v11
	v_add_f32_e32 v10, v12, v10
	v_cndmask_b32_e32 v10, v219, v10, vcc
	v_cmp_ngt_f32_e32 vcc, -1.0, v15
	s_nop 1
	v_cndmask_b32_e32 v10, v220, v10, vcc
	v_cmp_neq_f32_e32 vcc, -1.0, v15
	s_nop 1
	v_cndmask_b32_e32 v10, v215, v10, vcc
	v_cmp_lt_f32_e64 vcc, |v15|, s5
	s_nop 1
	v_cndmask_b32_e32 v10, v10, v15, vcc
	v_xor_b32_e32 v18, 0x80000000, v10
.LBB0_182:
	s_andn2_saveexec_b64 s[0:1], s[0:1]
	s_cbranch_execz .LBB0_184
	v_mul_f32_e32 v11, 0x3fb8aa3b, v10
	v_exp_f32_e32 v11, v11
	s_mov_b32 s5, 0x3f2aaaab
	v_add_f32_e32 v15, 1.0, v11
	v_frexp_mant_f32_e32 v19, v15
	v_cvt_f64_f32_e32 v[12:13], v15
	v_frexp_exp_i32_f64_e32 v12, v[12:13]
	v_cmp_gt_f32_e32 vcc, s5, v19
	v_add_f32_e32 v18, -1.0, v15
	v_sub_f32_e32 v20, v18, v15
	v_subbrev_co_u32_e32 v24, vcc, 0, v12, vcc
	v_sub_u32_e32 v12, 0, v24
	v_sub_f32_e32 v18, v11, v18
	v_add_f32_e32 v20, 1.0, v20
	v_ldexp_f32 v13, v15, v12
	v_add_f32_e32 v18, v18, v20
	v_add_f32_e32 v15, -1.0, v13
	v_add_f32_e32 v19, 1.0, v13
	v_ldexp_f32 v12, v18, v12
	v_add_f32_e32 v18, 1.0, v15
	v_add_f32_e32 v20, -1.0, v19
	v_sub_f32_e32 v18, v13, v18
	v_sub_f32_e32 v13, v13, v20
	v_add_f32_e32 v18, v12, v18
	v_add_f32_e32 v12, v12, v13
	v_add_f32_e32 v25, v19, v12
	v_rcp_f32_e32 v27, v25
	v_sub_f32_e32 v13, v25, v19
	v_sub_f32_e32 v26, v12, v13
	v_add_f32_e32 v13, v15, v18
	v_sub_f32_e32 v12, v13, v15
	v_mul_f32_e32 v28, v13, v27
	v_sub_f32_e32 v15, v18, v12
	v_mul_f32_e32 v18, v25, v28
	v_fma_f32 v20, v28, v25, -v18
	v_fmac_f32_e32 v20, v28, v26
	v_add_f32_e32 v12, v18, v20
	v_sub_f32_e32 v19, v13, v12
	v_add_f32_e64 v22, v12, -v18
	v_add_f32_e64 v23, v13, -v19
	v_mov_b32_e32 v21, v12
	v_add_f32_e64 v12, v22, -v20
	v_add_f32_e64 v13, v23, -v21
	s_mov_b32 s5, 0x3f317218
	v_add_f32_e32 v13, v15, v13
	v_add_f32_e32 v12, v12, v13
	v_add_f32_e32 v13, v19, v12
	v_mul_f32_e32 v15, v27, v13
	v_mul_f32_e32 v18, v25, v15
	v_fma_f32 v20, v15, v25, -v18
	v_fmac_f32_e32 v20, v15, v26
	v_sub_f32_e32 v19, v19, v13
	v_add_f32_e32 v25, v12, v19
	v_add_f32_e32 v12, v18, v20
	v_sub_f32_e32 v19, v13, v12
	v_add_f32_e64 v22, v12, -v18
	v_add_f32_e64 v23, v13, -v19
	v_mov_b32_e32 v21, v12
	v_add_f32_e64 v12, v22, -v20
	v_add_f32_e64 v13, v23, -v21
	v_cmp_neq_f32_e32 vcc, s2, v11
	v_add_f32_e32 v13, v25, v13
	v_add_f32_e32 v12, v12, v13
	v_add_f32_e32 v13, v28, v15
	v_add_f32_e32 v12, v19, v12
	v_sub_f32_e32 v18, v13, v28
	v_mul_f32_e32 v12, v27, v12
	v_sub_f32_e32 v15, v15, v18
	v_add_f32_e32 v15, v15, v12
	v_add_f32_e32 v18, v13, v15
	v_mul_f32_e32 v20, v18, v18
	v_fmamk_f32 v12, v20, 0x3e9b6dac, v210
	v_fmaak_f32 v175, v20, v12, 0x3f2aaada
	v_cvt_f32_i32_e32 v12, v24
	v_sub_f32_e32 v13, v18, v13
	v_sub_f32_e32 v13, v15, v13
	v_ldexp_f32 v15, v13, 1
	v_mul_f32_e32 v13, v18, v20
	v_mul_f32_e32 v20, v12, v174
	v_mul_f32_e32 v21, v13, v175
	v_ldexp_f32 v19, v18, 1
	v_fma_f32 v18, v12, s5, -v20
	v_fmac_f32_e32 v18, 0xb102e308, v12
	v_add_f32_e32 v12, v20, v18
	v_add_f32_e32 v13, v21, v19
	v_mov_b32_e32 v22, v20
	v_sub_f32_e32 v19, v13, v19
	v_sub_f32_e32 v19, v21, v19
	v_add_f32_e32 v23, v15, v19
	v_add_f32_e64 v20, v12, -v20
	v_add_f32_e64 v21, v13, -v21
	v_add_f32_e32 v24, v12, v22
	v_add_f32_e32 v25, v13, v23
	v_mov_b32_e32 v19, v12
	v_mov_b32_e32 v21, v25
	v_add_f32_e64 v26, v18, -v20
	v_add_f32_e64 v27, v19, -v21
	v_add_f32_e32 v18, v18, v20
	v_add_f32_e32 v19, v19, v21
	v_mov_b32_e32 v22, v23
	v_add_f32_e64 v20, v19, -v12
	v_add_f32_e64 v21, v18, -v13
	v_add_f32_e64 v28, v24, -v20
	v_add_f32_e64 v29, v25, -v20
	v_mov_b32_e32 v24, v25
	v_mov_b32_e32 v25, v19
	v_pk_mov_b32 v[20:21], v[12:13], v[20:21] op_sel:[1,0]
	v_mov_b32_e32 v23, v12
	v_add_f32_e64 v20, v24, -v20
	v_add_f32_e64 v21, v25, -v21
	v_mov_b32_e32 v28, v26
	v_add_f32_e64 v12, v22, -v20
	v_add_f32_e64 v13, v23, -v21
	v_mov_b32_e32 v27, v19
	v_add_f32_e32 v20, v28, v12
	v_add_f32_e32 v21, v29, v13
	s_mov_b32 s5, 0x33800000
	v_add_f32_e32 v22, v20, v21
	v_add_f32_e32 v23, v21, v20
	s_nop 0
	v_pk_add_f32 v[18:19], v[18:19], v[22:23] op_sel:[1,0] op_sel_hi:[0,1]
	v_mov_b32_e32 v21, v18
	v_add_f32_e64 v24, v20, -v26
	v_add_f32_e64 v25, v21, -v27
	v_mov_b32_e32 v13, v22
	v_sub_f32_e32 v15, v20, v24
	v_add_f32_e64 v12, v12, -v24
	v_add_f32_e64 v13, v13, -v25
	v_sub_f32_e32 v15, v26, v15
	v_add_f32_e32 v12, v12, v15
	v_add_f32_e32 v12, v12, v13
	v_add_f32_e32 v12, v18, v12
	v_cndmask_b32_e32 v12, v219, v12, vcc
	v_cmp_ngt_f32_e32 vcc, -1.0, v11
	s_nop 1
	v_cndmask_b32_e32 v12, v220, v12, vcc
	v_cmp_neq_f32_e32 vcc, -1.0, v11
	s_nop 1
	v_cndmask_b32_e32 v12, v215, v12, vcc
	v_cmp_lt_f32_e64 vcc, |v11|, s5
	s_nop 1
	v_cndmask_b32_e32 v11, v12, v11, vcc
	v_sub_f32_e32 v18, v10, v11
.LBB0_184:
	s_or_b64 exec, exec, s[0:1]
	v_mov_b32_e32 v11, s65
	v_or_b32_e32 v10, s64, v128
	v_readlane_b32 s0, v254, 52
	v_lshlrev_b64 v[12:13], 5, v[10:11]
	v_readlane_b32 s1, v254, 53
	s_nop 1
	v_lshl_add_u64 v[12:13], s[0:1], 0, v[12:13]
	v_lshl_add_u64 v[12:13], v[12:13], 0, s[20:21]
	global_load_dword v15, v[12:13], off offset:16
	global_load_dword v19, v[12:13], off
	s_waitcnt vmcnt(1)
	v_add_f32_e32 v12, v14, v15
	v_cmp_le_f32_e32 vcc, 0, v12
	s_and_saveexec_b64 s[0:1], vcc
	s_xor_b64 s[0:1], exec, s[0:1]
	s_cbranch_execz .LBB0_186
	v_mul_f32_e32 v12, 0xbfb8aa3b, v12
	v_exp_f32_e32 v15, v12
	s_mov_b32 s5, 0x3f2aaaab
	v_add_f32_e32 v20, 1.0, v15
	v_frexp_mant_f32_e32 v22, v20
	v_cvt_f64_f32_e32 v[12:13], v20
	v_frexp_exp_i32_f64_e32 v12, v[12:13]
	v_cmp_gt_f32_e32 vcc, s5, v22
	v_add_f32_e32 v21, -1.0, v20
	v_sub_f32_e32 v23, v21, v20
	v_subbrev_co_u32_e32 v26, vcc, 0, v12, vcc
	v_sub_u32_e32 v12, 0, v26
	v_sub_f32_e32 v21, v15, v21
	v_add_f32_e32 v23, 1.0, v23
	v_ldexp_f32 v13, v20, v12
	v_add_f32_e32 v21, v21, v23
	v_add_f32_e32 v20, -1.0, v13
	v_add_f32_e32 v22, 1.0, v13
	v_ldexp_f32 v12, v21, v12
	v_add_f32_e32 v21, 1.0, v20
	v_add_f32_e32 v23, -1.0, v22
	v_sub_f32_e32 v21, v13, v21
	v_sub_f32_e32 v13, v13, v23
	v_add_f32_e32 v21, v12, v21
	v_add_f32_e32 v12, v12, v13
	v_add_f32_e32 v27, v22, v12
	v_rcp_f32_e32 v29, v27
	v_sub_f32_e32 v13, v27, v22
	v_sub_f32_e32 v28, v12, v13
	v_add_f32_e32 v13, v20, v21
	v_mul_f32_e32 v31, v13, v29
	v_sub_f32_e32 v12, v13, v20
	v_mul_f32_e32 v20, v27, v31
	v_fma_f32 v22, v31, v27, -v20
	v_fmac_f32_e32 v22, v31, v28
	v_sub_f32_e32 v30, v21, v12
	v_add_f32_e32 v12, v20, v22
	v_sub_f32_e32 v21, v13, v12
	v_add_f32_e64 v24, v12, -v20
	v_add_f32_e64 v25, v13, -v21
	v_mov_b32_e32 v23, v12
	v_add_f32_e64 v12, v24, -v22
	v_add_f32_e64 v13, v25, -v23
	s_mov_b32 s5, 0x3f317218
	v_add_f32_e32 v13, v30, v13
	v_add_f32_e32 v12, v12, v13
	v_add_f32_e32 v13, v21, v12
	v_mul_f32_e32 v30, v29, v13
	v_mul_f32_e32 v20, v27, v30
	v_fma_f32 v22, v30, v27, -v20
	v_fmac_f32_e32 v22, v30, v28
	v_sub_f32_e32 v21, v21, v13
	v_add_f32_e32 v27, v12, v21
	v_add_f32_e32 v12, v20, v22
	v_sub_f32_e32 v21, v13, v12
	v_add_f32_e64 v24, v12, -v20
	v_add_f32_e64 v25, v13, -v21
	v_mov_b32_e32 v23, v12
	v_add_f32_e64 v12, v24, -v22
	v_add_f32_e64 v13, v25, -v23
	v_cmp_neq_f32_e32 vcc, s2, v15
	v_add_f32_e32 v13, v27, v13
	v_add_f32_e32 v12, v12, v13
	v_add_f32_e32 v13, v31, v30
	v_add_f32_e32 v12, v21, v12
	v_sub_f32_e32 v20, v13, v31
	v_mul_f32_e32 v12, v29, v12
	v_sub_f32_e32 v20, v30, v20
	v_add_f32_e32 v20, v20, v12
	v_add_f32_e32 v22, v13, v20
	v_mul_f32_e32 v23, v22, v22
	v_fmamk_f32 v12, v23, 0x3e9b6dac, v210
	v_fmaak_f32 v175, v23, v12, 0x3f2aaada
	v_cvt_f32_i32_e32 v12, v26
	v_sub_f32_e32 v13, v22, v13
	v_sub_f32_e32 v13, v20, v13
	v_ldexp_f32 v24, v13, 1
	v_mul_f32_e32 v13, v22, v23
	v_ldexp_f32 v21, v22, 1
	v_mul_f32_e32 v22, v12, v174
	v_mul_f32_e32 v23, v13, v175
	s_nop 0
	v_fma_f32 v20, v12, s5, -v22
	v_fmac_f32_e32 v20, 0xb102e308, v12
	v_add_f32_e32 v12, v22, v20
	v_add_f32_e32 v13, v23, v21
	s_mov_b32 s5, 0x33800000
	v_sub_f32_e32 v21, v13, v21
	v_sub_f32_e32 v21, v23, v21
	v_add_f32_e32 v25, v24, v21
	v_mov_b32_e32 v24, v22
	v_add_f32_e64 v22, v12, -v22
	v_add_f32_e64 v23, v13, -v23
	v_add_f32_e32 v26, v12, v24
	v_add_f32_e32 v27, v13, v25
	v_mov_b32_e32 v21, v12
	v_mov_b32_e32 v23, v27
	v_add_f32_e64 v28, v20, -v22
	v_add_f32_e64 v29, v21, -v23
	v_add_f32_e32 v20, v20, v22
	v_add_f32_e32 v21, v21, v23
	v_mov_b32_e32 v24, v25
	v_add_f32_e64 v22, v21, -v12
	v_add_f32_e64 v23, v20, -v13
	v_add_f32_e64 v30, v26, -v22
	v_add_f32_e64 v31, v27, -v22
	v_mov_b32_e32 v26, v27
	v_mov_b32_e32 v27, v21
	v_pk_mov_b32 v[22:23], v[12:13], v[22:23] op_sel:[1,0]
	v_mov_b32_e32 v25, v12
	v_add_f32_e64 v22, v26, -v22
	v_add_f32_e64 v23, v27, -v23
	v_mov_b32_e32 v30, v28
	v_add_f32_e64 v12, v24, -v22
	v_add_f32_e64 v13, v25, -v23
	v_mov_b32_e32 v29, v21
	v_add_f32_e32 v22, v30, v12
	v_add_f32_e32 v23, v31, v13
	s_nop 0
	v_add_f32_e32 v24, v22, v23
	v_add_f32_e32 v25, v23, v22
	s_nop 0
	v_pk_add_f32 v[20:21], v[20:21], v[24:25] op_sel:[1,0] op_sel_hi:[0,1]
	v_mov_b32_e32 v23, v20
	v_add_f32_e64 v26, v22, -v28
	v_add_f32_e64 v27, v23, -v29
	v_mov_b32_e32 v13, v24
	v_sub_f32_e32 v21, v22, v26
	v_add_f32_e64 v12, v12, -v26
	v_add_f32_e64 v13, v13, -v27
	v_sub_f32_e32 v21, v28, v21
	v_add_f32_e32 v12, v12, v21
	v_add_f32_e32 v12, v12, v13
	v_add_f32_e32 v12, v20, v12
	v_cndmask_b32_e32 v12, v219, v12, vcc
	v_cmp_ngt_f32_e32 vcc, -1.0, v15
	s_nop 1
	v_cndmask_b32_e32 v12, v220, v12, vcc
	v_cmp_neq_f32_e32 vcc, -1.0, v15
	s_nop 1
	v_cndmask_b32_e32 v12, v215, v12, vcc
	v_cmp_lt_f32_e64 vcc, |v15|, s5
	s_nop 1
	v_cndmask_b32_e32 v12, v12, v15, vcc
	v_xor_b32_e32 v20, 0x80000000, v12
.LBB0_186:
	s_andn2_saveexec_b64 s[0:1], s[0:1]
	s_cbranch_execz .LBB0_188
	v_mul_f32_e32 v13, 0x3fb8aa3b, v12
	v_exp_f32_e32 v13, v13
	s_mov_b32 s5, 0x3f2aaaab
	v_add_f32_e32 v15, 1.0, v13
	v_frexp_mant_f32_e32 v23, v15
	v_cvt_f64_f32_e32 v[20:21], v15
	v_add_f32_e32 v22, -1.0, v15
	v_frexp_exp_i32_f64_e32 v20, v[20:21]
	v_cmp_gt_f32_e32 vcc, s5, v23
	v_sub_f32_e32 v24, v22, v15
	v_sub_f32_e32 v22, v13, v22
	v_subbrev_co_u32_e32 v28, vcc, 0, v20, vcc
	v_add_f32_e32 v24, 1.0, v24
	v_sub_u32_e32 v20, 0, v28
	v_add_f32_e32 v22, v22, v24
	v_ldexp_f32 v15, v15, v20
	v_ldexp_f32 v20, v22, v20
	v_add_f32_e32 v22, -1.0, v15
	v_add_f32_e32 v21, 1.0, v22
	v_sub_f32_e32 v21, v15, v21
	v_add_f32_e32 v23, v20, v21
	v_add_f32_e32 v21, 1.0, v15
	v_add_f32_e32 v24, -1.0, v21
	v_sub_f32_e32 v15, v15, v24
	v_add_f32_e32 v15, v20, v15
	v_add_f32_e32 v29, v21, v15
	v_rcp_f32_e32 v30, v29
	v_sub_f32_e32 v20, v29, v21
	v_add_f32_e32 v21, v22, v23
	v_sub_f32_e32 v15, v15, v20
	v_mul_f32_e32 v32, v21, v30
	v_sub_f32_e32 v20, v21, v22
	v_mul_f32_e32 v22, v29, v32
	v_fma_f32 v24, v32, v29, -v22
	v_fmac_f32_e32 v24, v32, v15
	v_sub_f32_e32 v31, v23, v20
	v_add_f32_e32 v20, v22, v24
	v_sub_f32_e32 v23, v21, v20
	v_add_f32_e64 v26, v20, -v22
	v_add_f32_e64 v27, v21, -v23
	v_mov_b32_e32 v25, v20
	v_add_f32_e64 v20, v26, -v24
	v_add_f32_e64 v21, v27, -v25
	s_mov_b32 s5, 0x3f317218
	v_add_f32_e32 v21, v31, v21
	v_add_f32_e32 v20, v20, v21
	v_add_f32_e32 v21, v23, v20
	v_mul_f32_e32 v31, v30, v21
	v_mul_f32_e32 v22, v29, v31
	v_fma_f32 v24, v31, v29, -v22
	v_fmac_f32_e32 v24, v31, v15
	v_sub_f32_e32 v15, v23, v21
	v_add_f32_e32 v15, v20, v15
	v_add_f32_e32 v20, v22, v24
	v_sub_f32_e32 v23, v21, v20
	v_add_f32_e64 v26, v20, -v22
	v_add_f32_e64 v27, v21, -v23
	v_mov_b32_e32 v25, v20
	v_add_f32_e64 v20, v26, -v24
	v_add_f32_e64 v21, v27, -v25
	v_cmp_neq_f32_e32 vcc, s2, v13
	v_add_f32_e32 v15, v15, v21
	v_add_f32_e32 v15, v20, v15
	v_add_f32_e32 v21, v32, v31
	v_add_f32_e32 v15, v23, v15
	v_sub_f32_e32 v20, v21, v32
	v_mul_f32_e32 v15, v30, v15
	v_sub_f32_e32 v20, v31, v20
	v_add_f32_e32 v15, v20, v15
	v_add_f32_e32 v22, v21, v15
	v_mul_f32_e32 v24, v22, v22
	v_fmamk_f32 v20, v24, 0x3e9b6dac, v210
	v_fmaak_f32 v175, v24, v20, 0x3f2aaada
	v_cvt_f32_i32_e32 v20, v28
	v_sub_f32_e32 v21, v22, v21
	v_sub_f32_e32 v15, v15, v21
	v_mul_f32_e32 v21, v22, v24
	v_mul_f32_e32 v24, v20, v174
	v_mul_f32_e32 v25, v21, v175
	v_ldexp_f32 v23, v22, 1
	v_fma_f32 v22, v20, s5, -v24
	v_fmac_f32_e32 v22, 0xb102e308, v20
	v_add_f32_e32 v20, v24, v22
	v_add_f32_e32 v21, v25, v23
	v_ldexp_f32 v15, v15, 1
	v_sub_f32_e32 v23, v21, v23
	v_sub_f32_e32 v23, v25, v23
	v_add_f32_e32 v27, v15, v23
	v_mov_b32_e32 v26, v24
	v_add_f32_e64 v24, v20, -v24
	v_add_f32_e64 v25, v21, -v25
	v_add_f32_e32 v28, v20, v26
	v_add_f32_e32 v29, v21, v27
	v_mov_b32_e32 v23, v20
	v_mov_b32_e32 v25, v29
	v_add_f32_e64 v30, v22, -v24
	v_add_f32_e64 v31, v23, -v25
	v_add_f32_e32 v22, v22, v24
	v_add_f32_e32 v23, v23, v25
	v_mov_b32_e32 v26, v27
	v_add_f32_e64 v24, v23, -v20
	v_add_f32_e64 v25, v22, -v21
	v_add_f32_e64 v32, v28, -v24
	v_add_f32_e64 v33, v29, -v24
	v_mov_b32_e32 v28, v29
	v_mov_b32_e32 v29, v23
	v_pk_mov_b32 v[24:25], v[20:21], v[24:25] op_sel:[1,0]
	v_mov_b32_e32 v27, v20
	v_add_f32_e64 v24, v28, -v24
	v_add_f32_e64 v25, v29, -v25
	v_mov_b32_e32 v32, v30
	v_add_f32_e64 v20, v26, -v24
	v_add_f32_e64 v21, v27, -v25
	v_mov_b32_e32 v31, v23
	v_add_f32_e32 v24, v32, v20
	v_add_f32_e32 v25, v33, v21
	s_mov_b32 s5, 0x33800000
	v_add_f32_e32 v26, v24, v25
	v_add_f32_e32 v27, v25, v24
	s_nop 0
	v_pk_add_f32 v[22:23], v[22:23], v[26:27] op_sel:[1,0] op_sel_hi:[0,1]
	v_mov_b32_e32 v25, v22
	v_add_f32_e64 v28, v24, -v30
	v_add_f32_e64 v29, v25, -v31
	v_mov_b32_e32 v21, v26
	v_sub_f32_e32 v15, v24, v28
	v_add_f32_e64 v20, v20, -v28
	v_add_f32_e64 v21, v21, -v29
	v_sub_f32_e32 v15, v30, v15
	v_add_f32_e32 v15, v20, v15
	v_add_f32_e32 v15, v15, v21
	v_add_f32_e32 v15, v22, v15
	v_cndmask_b32_e32 v15, v219, v15, vcc
	v_cmp_ngt_f32_e32 vcc, -1.0, v13
	s_nop 1
	v_cndmask_b32_e32 v15, v220, v15, vcc
	v_cmp_neq_f32_e32 vcc, -1.0, v13
	s_nop 1
	v_cndmask_b32_e32 v15, v215, v15, vcc
	v_cmp_lt_f32_e64 vcc, |v13|, s5
	s_nop 1
	v_cndmask_b32_e32 v13, v15, v13, vcc
	v_sub_f32_e32 v20, v12, v13
.LBB0_188:
	s_or_b64 exec, exec, s[0:1]
	v_mov_b32_e32 v13, s65
	v_or_b32_e32 v12, s64, v130
	v_readlane_b32 s0, v254, 52
	v_lshlrev_b64 v[22:23], 5, v[12:13]
	v_readlane_b32 s1, v254, 53
	s_nop 1
	v_lshl_add_u64 v[22:23], s[0:1], 0, v[22:23]
	v_lshl_add_u64 v[22:23], v[22:23], 0, s[20:21]
	global_load_dword v21, v[22:23], off offset:16
	global_load_dword v15, v[22:23], off
	s_waitcnt vmcnt(1)
	v_add_f32_e32 v14, v14, v21
	v_cmp_le_f32_e32 vcc, 0, v14
	s_and_saveexec_b64 s[0:1], vcc
	s_xor_b64 s[0:1], exec, s[0:1]
	s_cbranch_execz .LBB0_190
	v_mul_f32_e32 v14, 0xbfb8aa3b, v14
	v_exp_f32_e32 v14, v14
	s_mov_b32 s5, 0x3f2aaaab
	v_add_f32_e32 v21, 1.0, v14
	v_frexp_mant_f32_e32 v25, v21
	v_cvt_f64_f32_e32 v[22:23], v21
	v_add_f32_e32 v24, -1.0, v21
	v_frexp_exp_i32_f64_e32 v22, v[22:23]
	v_cmp_gt_f32_e32 vcc, s5, v25
	v_sub_f32_e32 v26, v24, v21
	v_sub_f32_e32 v24, v14, v24
	v_subbrev_co_u32_e32 v30, vcc, 0, v22, vcc
	v_add_f32_e32 v26, 1.0, v26
	v_sub_u32_e32 v22, 0, v30
	v_add_f32_e32 v24, v24, v26
	v_ldexp_f32 v21, v21, v22
	v_ldexp_f32 v22, v24, v22
	v_add_f32_e32 v24, -1.0, v21
	v_add_f32_e32 v23, 1.0, v24
	v_sub_f32_e32 v23, v21, v23
	v_add_f32_e32 v25, v22, v23
	v_add_f32_e32 v23, 1.0, v21
	v_add_f32_e32 v26, -1.0, v23
	v_sub_f32_e32 v21, v21, v26
	v_add_f32_e32 v21, v22, v21
	v_add_f32_e32 v31, v23, v21
	v_rcp_f32_e32 v32, v31
	v_sub_f32_e32 v22, v31, v23
	v_add_f32_e32 v23, v24, v25
	v_sub_f32_e32 v21, v21, v22
	v_mul_f32_e32 v34, v23, v32
	v_sub_f32_e32 v22, v23, v24
	v_mul_f32_e32 v24, v31, v34
	v_fma_f32 v26, v34, v31, -v24
	v_fmac_f32_e32 v26, v34, v21
	v_sub_f32_e32 v33, v25, v22
	v_add_f32_e32 v22, v24, v26
	v_sub_f32_e32 v25, v23, v22
	v_add_f32_e64 v28, v22, -v24
	v_add_f32_e64 v29, v23, -v25
	v_mov_b32_e32 v27, v22
	v_add_f32_e64 v22, v28, -v26
	v_add_f32_e64 v23, v29, -v27
	s_mov_b32 s5, 0x3f317218
	v_add_f32_e32 v23, v33, v23
	v_add_f32_e32 v22, v22, v23
	v_add_f32_e32 v23, v25, v22
	v_mul_f32_e32 v33, v32, v23
	v_mul_f32_e32 v24, v31, v33
	v_fma_f32 v26, v33, v31, -v24
	v_fmac_f32_e32 v26, v33, v21
	v_sub_f32_e32 v21, v25, v23
	v_add_f32_e32 v21, v22, v21
	v_add_f32_e32 v22, v24, v26
	v_sub_f32_e32 v25, v23, v22
	v_add_f32_e64 v28, v22, -v24
	v_add_f32_e64 v29, v23, -v25
	v_mov_b32_e32 v27, v22
	v_add_f32_e64 v22, v28, -v26
	v_add_f32_e64 v23, v29, -v27
	v_cmp_neq_f32_e32 vcc, s2, v14
	v_add_f32_e32 v21, v21, v23
	v_add_f32_e32 v21, v22, v21
	v_add_f32_e32 v23, v34, v33
	v_add_f32_e32 v21, v25, v21
	v_sub_f32_e32 v22, v23, v34
	v_mul_f32_e32 v21, v32, v21
	v_sub_f32_e32 v22, v33, v22
	v_add_f32_e32 v21, v22, v21
	v_add_f32_e32 v24, v23, v21
	v_mul_f32_e32 v26, v24, v24
	v_fmamk_f32 v22, v26, 0x3e9b6dac, v210
	v_fmaak_f32 v175, v26, v22, 0x3f2aaada
	v_cvt_f32_i32_e32 v22, v30
	v_sub_f32_e32 v23, v24, v23
	v_sub_f32_e32 v21, v21, v23
	v_mul_f32_e32 v23, v24, v26
	v_mul_f32_e32 v26, v22, v174
	v_mul_f32_e32 v27, v23, v175
	v_ldexp_f32 v25, v24, 1
	v_fma_f32 v24, v22, s5, -v26
	v_fmac_f32_e32 v24, 0xb102e308, v22
	v_add_f32_e32 v22, v26, v24
	v_add_f32_e32 v23, v27, v25
	v_ldexp_f32 v21, v21, 1
	v_sub_f32_e32 v25, v23, v25
	v_sub_f32_e32 v25, v27, v25
	v_add_f32_e32 v29, v21, v25
	v_mov_b32_e32 v28, v26
	v_add_f32_e64 v26, v22, -v26
	v_add_f32_e64 v27, v23, -v27
	v_add_f32_e32 v30, v22, v28
	v_add_f32_e32 v31, v23, v29
	v_mov_b32_e32 v25, v22
	v_mov_b32_e32 v27, v31
	v_add_f32_e64 v32, v24, -v26
	v_add_f32_e64 v33, v25, -v27
	v_add_f32_e32 v24, v24, v26
	v_add_f32_e32 v25, v25, v27
	v_mov_b32_e32 v28, v29
	v_add_f32_e64 v26, v25, -v22
	v_add_f32_e64 v27, v24, -v23
	v_add_f32_e64 v34, v30, -v26
	v_add_f32_e64 v35, v31, -v26
	v_mov_b32_e32 v30, v31
	v_mov_b32_e32 v31, v25
	v_pk_mov_b32 v[26:27], v[22:23], v[26:27] op_sel:[1,0]
	v_mov_b32_e32 v29, v22
	v_add_f32_e64 v26, v30, -v26
	v_add_f32_e64 v27, v31, -v27
	v_mov_b32_e32 v34, v32
	v_add_f32_e64 v22, v28, -v26
	v_add_f32_e64 v23, v29, -v27
	v_mov_b32_e32 v33, v25
	v_add_f32_e32 v26, v34, v22
	v_add_f32_e32 v27, v35, v23
	s_mov_b32 s5, 0x33800000
	v_add_f32_e32 v28, v26, v27
	v_add_f32_e32 v29, v27, v26
	s_nop 0
	v_pk_add_f32 v[24:25], v[24:25], v[28:29] op_sel:[1,0] op_sel_hi:[0,1]
	v_mov_b32_e32 v27, v24
	v_add_f32_e64 v30, v26, -v32
	v_add_f32_e64 v31, v27, -v33
	v_mov_b32_e32 v23, v28
	v_sub_f32_e32 v21, v26, v30
	v_add_f32_e64 v22, v22, -v30
	v_add_f32_e64 v23, v23, -v31
	v_sub_f32_e32 v21, v32, v21
	v_add_f32_e32 v21, v22, v21
	v_add_f32_e32 v21, v21, v23
	v_add_f32_e32 v21, v24, v21
	v_cndmask_b32_e32 v21, v219, v21, vcc
	v_cmp_ngt_f32_e32 vcc, -1.0, v14
	s_nop 1
	v_cndmask_b32_e32 v21, v220, v21, vcc
	v_cmp_neq_f32_e32 vcc, -1.0, v14
	s_nop 1
	v_cndmask_b32_e32 v21, v215, v21, vcc
	v_cmp_lt_f32_e64 vcc, |v14|, s5
	s_nop 1
	v_cndmask_b32_e32 v14, v21, v14, vcc
	v_xor_b32_e32 v21, 0x80000000, v14
.LBB0_190:
	s_andn2_saveexec_b64 s[0:1], s[0:1]
	s_cbranch_execz .LBB0_192
	v_mul_f32_e32 v21, 0x3fb8aa3b, v14
	v_exp_f32_e32 v21, v21
	s_mov_b32 s5, 0x3f2aaaab
	v_add_f32_e32 v24, 1.0, v21
	v_frexp_mant_f32_e32 v26, v24
	v_cvt_f64_f32_e32 v[22:23], v24
	v_frexp_exp_i32_f64_e32 v22, v[22:23]
	v_cmp_gt_f32_e32 vcc, s5, v26
	v_add_f32_e32 v25, -1.0, v24
	v_sub_f32_e32 v27, v25, v24
	v_subbrev_co_u32_e32 v30, vcc, 0, v22, vcc
	v_sub_u32_e32 v22, 0, v30
	v_sub_f32_e32 v25, v21, v25
	v_add_f32_e32 v27, 1.0, v27
	v_ldexp_f32 v23, v24, v22
	v_add_f32_e32 v25, v25, v27
	v_add_f32_e32 v24, -1.0, v23
	v_add_f32_e32 v26, 1.0, v23
	v_ldexp_f32 v22, v25, v22
	v_add_f32_e32 v25, 1.0, v24
	v_add_f32_e32 v27, -1.0, v26
	v_sub_f32_e32 v25, v23, v25
	v_sub_f32_e32 v23, v23, v27
	v_add_f32_e32 v25, v22, v25
	v_add_f32_e32 v22, v22, v23
	v_add_f32_e32 v31, v26, v22
	v_rcp_f32_e32 v33, v31
	v_sub_f32_e32 v23, v31, v26
	v_sub_f32_e32 v32, v22, v23
	v_add_f32_e32 v23, v24, v25
	v_mul_f32_e32 v35, v23, v33
	v_sub_f32_e32 v22, v23, v24
	v_mul_f32_e32 v24, v31, v35
	v_fma_f32 v26, v35, v31, -v24
	v_fmac_f32_e32 v26, v35, v32
	v_sub_f32_e32 v34, v25, v22
	v_add_f32_e32 v22, v24, v26
	v_sub_f32_e32 v25, v23, v22
	v_add_f32_e64 v28, v22, -v24
	v_add_f32_e64 v29, v23, -v25
	v_mov_b32_e32 v27, v22
	v_add_f32_e64 v22, v28, -v26
	v_add_f32_e64 v23, v29, -v27
	s_mov_b32 s5, 0x3f317218
	v_add_f32_e32 v23, v34, v23
	v_add_f32_e32 v22, v22, v23
	v_add_f32_e32 v23, v25, v22
	v_mul_f32_e32 v34, v33, v23
	v_mul_f32_e32 v24, v31, v34
	v_fma_f32 v26, v34, v31, -v24
	v_fmac_f32_e32 v26, v34, v32
	v_sub_f32_e32 v25, v25, v23
	v_add_f32_e32 v31, v22, v25
	v_add_f32_e32 v22, v24, v26
	v_sub_f32_e32 v25, v23, v22
	v_add_f32_e64 v28, v22, -v24
	v_add_f32_e64 v29, v23, -v25
	v_mov_b32_e32 v27, v22
	v_add_f32_e64 v22, v28, -v26
	v_add_f32_e64 v23, v29, -v27
	v_cmp_neq_f32_e32 vcc, s2, v21
	v_add_f32_e32 v23, v31, v23
	v_add_f32_e32 v22, v22, v23
	v_add_f32_e32 v23, v35, v34
	v_add_f32_e32 v22, v25, v22
	v_sub_f32_e32 v24, v23, v35
	v_mul_f32_e32 v22, v33, v22
	v_sub_f32_e32 v24, v34, v24
	v_add_f32_e32 v24, v24, v22
	v_add_f32_e32 v26, v23, v24
	v_mul_f32_e32 v27, v26, v26
	v_fmamk_f32 v22, v27, 0x3e9b6dac, v210
	v_fmaak_f32 v175, v27, v22, 0x3f2aaada
	v_cvt_f32_i32_e32 v22, v30
	v_sub_f32_e32 v23, v26, v23
	v_sub_f32_e32 v23, v24, v23
	v_ldexp_f32 v28, v23, 1
	v_mul_f32_e32 v23, v26, v27
	v_ldexp_f32 v25, v26, 1
	v_mul_f32_e32 v26, v22, v174
	v_mul_f32_e32 v27, v23, v175
	s_nop 0
	v_fma_f32 v24, v22, s5, -v26
	v_fmac_f32_e32 v24, 0xb102e308, v22
	v_add_f32_e32 v22, v26, v24
	v_add_f32_e32 v23, v27, v25
	s_mov_b32 s5, 0x33800000
	v_sub_f32_e32 v25, v23, v25
	v_sub_f32_e32 v25, v27, v25
	v_add_f32_e32 v29, v28, v25
	v_mov_b32_e32 v28, v26
	v_add_f32_e64 v26, v22, -v26
	v_add_f32_e64 v27, v23, -v27
	v_add_f32_e32 v30, v22, v28
	v_add_f32_e32 v31, v23, v29
	v_mov_b32_e32 v25, v22
	v_mov_b32_e32 v27, v31
	v_add_f32_e64 v32, v24, -v26
	v_add_f32_e64 v33, v25, -v27
	v_add_f32_e32 v24, v24, v26
	v_add_f32_e32 v25, v25, v27
	v_mov_b32_e32 v28, v29
	v_add_f32_e64 v26, v25, -v22
	v_add_f32_e64 v27, v24, -v23
	v_add_f32_e64 v34, v30, -v26
	v_add_f32_e64 v35, v31, -v26
	v_mov_b32_e32 v30, v31
	v_mov_b32_e32 v31, v25
	v_pk_mov_b32 v[26:27], v[22:23], v[26:27] op_sel:[1,0]
	v_mov_b32_e32 v29, v22
	v_add_f32_e64 v26, v30, -v26
	v_add_f32_e64 v27, v31, -v27
	v_mov_b32_e32 v34, v32
	v_add_f32_e64 v22, v28, -v26
	v_add_f32_e64 v23, v29, -v27
	v_mov_b32_e32 v33, v25
	v_add_f32_e32 v26, v34, v22
	v_add_f32_e32 v27, v35, v23
	s_nop 0
	v_add_f32_e32 v28, v26, v27
	v_add_f32_e32 v29, v27, v26
	s_nop 0
	v_pk_add_f32 v[24:25], v[24:25], v[28:29] op_sel:[1,0] op_sel_hi:[0,1]
	v_mov_b32_e32 v27, v24
	v_add_f32_e64 v30, v26, -v32
	v_add_f32_e64 v31, v27, -v33
	v_mov_b32_e32 v23, v28
	v_sub_f32_e32 v25, v26, v30
	v_add_f32_e64 v22, v22, -v30
	v_add_f32_e64 v23, v23, -v31
	v_sub_f32_e32 v25, v32, v25
	v_add_f32_e32 v22, v22, v25
	v_add_f32_e32 v22, v22, v23
	v_add_f32_e32 v22, v24, v22
	v_cndmask_b32_e32 v22, v219, v22, vcc
	v_cmp_ngt_f32_e32 vcc, -1.0, v21
	s_nop 1
	v_cndmask_b32_e32 v22, v220, v22, vcc
	v_cmp_neq_f32_e32 vcc, -1.0, v21
	s_nop 1
	v_cndmask_b32_e32 v22, v215, v22, vcc
	v_cmp_lt_f32_e64 vcc, |v21|, s5
	s_nop 1
	v_cndmask_b32_e32 v21, v22, v21, vcc
	v_sub_f32_e32 v21, v14, v21
.LBB0_192:
	s_or_b64 exec, exec, s[0:1]
	v_readlane_b32 s0, v254, 56
	s_add_u32 s0, s0, s20
	v_readlane_b32 s1, v254, 57
	s_waitcnt vmcnt(0)
	v_add_f32_e32 v15, v7, v15
	v_add_f32_e32 v14, v7, v19
	v_add_f32_e32 v23, v7, v17
	v_add_f32_e32 v22, v7, v16
	v_add_f32_e32 v7, v6, v18
	s_addc_u32 s1, s1, 0
	v_lshl_add_u64 v[24:25], v[8:9], 4, s[0:1]
	v_add_f32_e32 v8, v7, v20
	v_add_f32_e32 v9, v8, v21
	v_lshl_add_u64 v[18:19], v[4:5], 4, s[0:1]
	ds_bpermute_b32 v4, v148, v9
	v_readlane_b32 s10, v255, 6
	v_readlane_b32 s11, v255, 7
	v_lshl_add_u64 v[10:11], v[10:11], 4, s[0:1]
	s_waitcnt lgkmcnt(0)
	v_add_f32_e32 v4, v9, v4
	v_cndmask_b32_e64 v4, v4, v9, s[10:11]
	ds_bpermute_b32 v5, v149, v4
	v_readlane_b32 s10, v255, 8
	v_readlane_b32 s11, v255, 9
	s_waitcnt lgkmcnt(0)
	v_add_f32_e32 v5, v4, v5
	v_cndmask_b32_e64 v4, v5, v4, s[10:11]
	ds_bpermute_b32 v5, v150, v4
	v_readlane_b32 s10, v255, 10
	v_readlane_b32 s11, v255, 11
	s_waitcnt lgkmcnt(0)
	v_add_f32_e32 v5, v4, v5
	v_cndmask_b32_e64 v4, v5, v4, s[10:11]
	ds_bpermute_b32 v5, v151, v4
	v_readlane_b32 s10, v255, 12
	v_readlane_b32 s11, v255, 13
	s_waitcnt lgkmcnt(0)
	v_add_f32_e32 v5, v4, v5
	v_cndmask_b32_e64 v4, v5, v4, s[10:11]
	ds_bpermute_b32 v5, v152, v4
	v_readlane_b32 s10, v255, 14
	v_readlane_b32 s11, v255, 15
	s_waitcnt lgkmcnt(0)
	v_add_f32_e32 v5, v4, v5
	v_cndmask_b32_e64 v4, v5, v4, s[8:9]
	ds_bpermute_b32 v5, v153, v4
	s_waitcnt lgkmcnt(0)
	v_add_f32_e32 v5, v4, v5
	v_cndmask_b32_e64 v4, v5, v4, s[10:11]
	v_sub_f32_e32 v16, v4, v9
	ds_bpermute_b32 v4, v154, v4
	v_add_f32_e32 v6, v6, v16
	v_add_f32_e32 v7, v7, v16
	v_add_f32_e32 v8, v8, v16
	v_add_f32_e32 v9, v9, v16
	v_add_f32_e64 v20, v22, -v6
	v_add_f32_e64 v21, v23, -v7
	ds_write_b128 v142, v[6:9]
	s_waitcnt lgkmcnt(1)
	v_sub_f32_e32 v5, v4, v6
	v_add_f32_e32 v5, v22, v5
	v_mul_f32_e32 v5, 0x3fb8aa3b, v5
	v_exp_f32_e32 v16, v5
	v_mul_f32_e32 v5, 0x3fb8aa3b, v6
	v_exp_f32_e32 v5, v5
	global_store_dword v[18:19], v5, off
	v_sub_f32_e32 v5, v4, v7
	v_add_f32_e32 v5, v23, v5
	v_mul_f32_e32 v5, 0x3fb8aa3b, v5
	v_exp_f32_e32 v17, v5
	v_mul_f32_e32 v5, 0x3fb8aa3b, v7
	v_exp_f32_e32 v5, v5
	v_lshl_add_u64 v[6:7], v[12:13], 4, s[0:1]
	v_readlane_b32 s0, v255, 2
	v_add_f32_e64 v22, v14, -v8
	v_add_f32_e64 v23, v15, -v9
	global_store_dword v[24:25], v5, off
	v_sub_f32_e32 v5, v4, v8
	v_add_f32_e32 v5, v14, v5
	v_mul_f32_e32 v5, 0x3fb8aa3b, v5
	v_exp_f32_e32 v18, v5
	v_mul_f32_e32 v5, 0x3fb8aa3b, v8
	v_exp_f32_e32 v5, v5
	v_readlane_b32 s1, v255, 3
	ds_write_b128 v143, v[20:23]
	global_store_dword v[10:11], v5, off
	v_sub_f32_e32 v5, v4, v9
	v_add_f32_e32 v5, v15, v5
	v_mul_f32_e32 v5, 0x3fb8aa3b, v5
	v_exp_f32_e32 v19, v5
	v_mul_f32_e32 v5, 0x3fb8aa3b, v9
	v_exp_f32_e32 v5, v5
	ds_write_b128 v144, v[16:19]
	global_store_dword v[6:7], v5, off
	s_and_b64 exec, exec, s[0:1]
	s_cbranch_execz .LBB0_194
	v_mul_f32_e32 v4, 0x3fb8aa3b, v4
	v_exp_f32_e32 v4, v4
	s_ashr_i32 s63, s62, 31
	s_lshl_b64 s[0:1], s[62:63], 2
	v_readlane_b32 s5, v254, 60
	s_add_u32 s0, s5, s0
	v_readlane_b32 s5, v254, 61
	s_addc_u32 s1, s5, s1
	global_store_dword v3, v4, s[0:1]

.LBB0_204:
	v_add_u32_e32 v86, -16, v84
	ds_read_b128 v[86:89], v86
	ds_read_b128 v[90:93], v84
	ds_read_u16 v94, v85
	ds_read_u16 v95, v85 offset:272
	v_add_u32_e32 v84, 0x80, v84
	s_waitcnt lgkmcnt(1)
	v_lshlrev_b32_e32 v94, 16, v94
	s_waitcnt lgkmcnt(0)
	v_lshlrev_b32_e32 v95, 16, v95
	v_mul_f32_e32 v86, v86, v94
	v_mul_f32_e32 v87, v87, v95
	s_nop 0
	v_cvt_pk_bf16_f32 v86, v86, v87
	ds_read_u16 v87, v85 offset:544
	ds_read_u16 v94, v85 offset:816
	s_waitcnt lgkmcnt(0)
	v_lshlrev_b32_e32 v95, 16, v94
	v_lshlrev_b32_e32 v94, 16, v87
	v_mul_f32_e32 v88, v88, v94
	v_mul_f32_e32 v89, v89, v95
	v_add_u32_e32 v94, s1, v155
	v_cvt_pk_bf16_f32 v87, v88, v89
	ds_read_u16 v88, v85 offset:1088
	ds_read_u16 v89, v85 offset:1360
	s_add_i32 s1, s1, 64
	s_cmpk_eq_i32 s1, 0x100
	s_waitcnt lgkmcnt(1)
	v_lshlrev_b32_e32 v88, 16, v88
	s_waitcnt lgkmcnt(0)
	v_lshlrev_b32_e32 v89, 16, v89
	v_mul_f32_e32 v88, v90, v88
	v_mul_f32_e32 v89, v91, v89
	s_nop 0
	v_cvt_pk_bf16_f32 v88, v88, v89
	ds_read_u16 v89, v85 offset:1632
	ds_read_u16 v90, v85 offset:1904
	v_add_u32_e32 v85, 0x2200, v85
	s_waitcnt lgkmcnt(0)
	v_lshlrev_b32_e32 v91, 16, v90
	v_lshlrev_b32_e32 v90, 16, v89
	v_mul_f32_e32 v90, v92, v90
	v_mul_f32_e32 v91, v93, v91
	s_nop 0
	v_cvt_pk_bf16_f32 v89, v90, v91
	ds_read_b128 v[90:93], v94
	s_waitcnt lgkmcnt(0)
	v_mfma_f32_16x16x32_bf16 v[32:35], v[90:93], v[86:89], v[32:35]
	ds_read_b128 v[90:93], v94 offset:4352
	s_waitcnt lgkmcnt(0)
	v_mfma_f32_16x16x32_bf16 v[28:31], v[90:93], v[86:89], v[28:31]
	ds_read_b128 v[90:93], v94 offset:8704
	s_waitcnt lgkmcnt(0)
	v_mfma_f32_16x16x32_bf16 v[24:27], v[90:93], v[86:89], v[24:27]
	ds_read_b128 v[90:93], v94 offset:13056
	s_waitcnt lgkmcnt(0)
	v_mfma_f32_16x16x32_bf16 v[20:23], v[90:93], v[86:89], v[20:23]
	ds_read_b128 v[90:93], v94 offset:17408
	s_waitcnt lgkmcnt(0)
	v_mfma_f32_16x16x32_bf16 v[16:19], v[90:93], v[86:89], v[16:19]
	ds_read_b128 v[90:93], v94 offset:21760
	s_waitcnt lgkmcnt(0)
	v_mfma_f32_16x16x32_bf16 v[12:15], v[90:93], v[86:89], v[12:15]
	ds_read_b128 v[90:93], v94 offset:26112
	s_waitcnt lgkmcnt(0)
	v_mfma_f32_16x16x32_bf16 v[8:11], v[90:93], v[86:89], v[8:11]
	ds_read_b128 v[90:93], v94 offset:30464
	s_waitcnt lgkmcnt(0)
	v_mfma_f32_16x16x32_bf16 v[4:7], v[90:93], v[86:89], v[4:7]
	s_cbranch_scc0 .LBB0_204
	v_add_u32_e32 v84, s0, v159
	s_mov_b32 s0, 32
	v_mov_b32_e32 v85, v158
.LBB0_206:
	v_add_u32_e32 v86, 0, v84
	v_add_u32_e32 v86, 0x1a000, v86
	v_add_u32_e32 v90, 0, v85
	ds_read_b128 v[86:89], v86
	ds_read_u16 v91, v90
	s_add_i32 s0, s0, -4
	v_add_u32_e32 v85, 0x440, v85
	v_add_u32_e32 v84, 16, v84
	s_cmp_eq_u32 s0, 0
	s_waitcnt lgkmcnt(0)
	v_lshlrev_b32_e32 v91, 16, v91
	v_fmac_f32_e32 v165, v86, v91
	ds_read_u16 v86, v90 offset:272
	s_waitcnt lgkmcnt(0)
	v_lshlrev_b32_e32 v86, 16, v86
	v_fmac_f32_e32 v165, v87, v86
	ds_read_u16 v86, v90 offset:544
	s_waitcnt lgkmcnt(0)
	v_lshlrev_b32_e32 v86, 16, v86
	v_fmac_f32_e32 v165, v88, v86
	ds_read_u16 v86, v90 offset:816
	s_waitcnt lgkmcnt(0)
	v_lshlrev_b32_e32 v86, 16, v86
	v_fmac_f32_e32 v165, v89, v86
	s_cbranch_scc0 .LBB0_206
	s_mov_b32 s63, 1
	s_mov_b64 s[14:15], 0
	s_and_b64 vcc, exec, s[12:13]
	s_cbranch_vccz .LBB0_195
	s_ashr_i32 s63, s62, 31
	s_lshl_b64 s[0:1], s[62:63], 16
	v_lshl_add_u64 v[36:37], v[132:133], 0, s[0:1]
	global_store_dword v[36:37], v32, off
	global_store_dword v[36:37], v33, off offset:512
	global_store_dword v[36:37], v34, off offset:1024
	global_store_dword v[36:37], v35, off offset:1536
	v_add_co_u32_e32 v32, vcc, 0x2000, v36
	s_movk_i32 s0, 0x4000
	s_nop 0
	v_addc_co_u32_e32 v33, vcc, 0, v37, vcc
	global_store_dword v[32:33], v28, off
	global_store_dword v[32:33], v29, off offset:512
	global_store_dword v[32:33], v30, off offset:1024
	global_store_dword v[32:33], v31, off offset:1536
	v_add_co_u32_e32 v28, vcc, s0, v36
	s_movk_i32 s0, 0x6000
	s_nop 0
	v_addc_co_u32_e32 v29, vcc, 0, v37, vcc
	global_store_dword v[28:29], v24, off
	global_store_dword v[28:29], v25, off offset:512
	global_store_dword v[28:29], v26, off offset:1024
	global_store_dword v[28:29], v27, off offset:1536
	v_add_co_u32_e32 v24, vcc, s0, v36
	s_mov_b32 s0, 0x8000
	s_nop 0
	v_addc_co_u32_e32 v25, vcc, 0, v37, vcc
	global_store_dword v[24:25], v20, off
	global_store_dword v[24:25], v21, off offset:512
	global_store_dword v[24:25], v22, off offset:1024
	global_store_dword v[24:25], v23, off offset:1536
	v_add_co_u32_e32 v20, vcc, s0, v36
	s_mov_b32 s0, 0xa000
	s_nop 0
	v_addc_co_u32_e32 v21, vcc, 0, v37, vcc
	global_store_dword v[20:21], v16, off
	global_store_dword v[20:21], v17, off offset:512
	global_store_dword v[20:21], v18, off offset:1024
	global_store_dword v[20:21], v19, off offset:1536
	v_add_co_u32_e32 v16, vcc, s0, v36
	s_mov_b32 s0, 0xc000
	s_nop 0
	v_addc_co_u32_e32 v17, vcc, 0, v37, vcc
	global_store_dword v[16:17], v12, off
	global_store_dword v[16:17], v13, off offset:512
	global_store_dword v[16:17], v14, off offset:1024
	global_store_dword v[16:17], v15, off offset:1536
	v_add_co_u32_e32 v12, vcc, s0, v36
	s_nop 1
	v_addc_co_u32_e32 v13, vcc, 0, v37, vcc
	global_store_dword v[12:13], v8, off
	global_store_dword v[12:13], v9, off offset:512
	global_store_dword v[12:13], v10, off offset:1024
	global_store_dword v[12:13], v11, off offset:1536
	v_add_co_u32_e32 v8, vcc, 0xe000, v36
	s_nop 1
	v_addc_co_u32_e32 v9, vcc, 0, v37, vcc
	global_store_dword v[8:9], v4, off
	global_store_dword v[8:9], v5, off offset:512
	global_store_dword v[8:9], v6, off offset:1024
	global_store_dword v[8:9], v7, off offset:1536
	ds_write_b32 v131, v165
	s_waitcnt lgkmcnt(0)
	s_barrier
	s_mov_b64 s[0:1], exec
	v_readlane_b32 s4, v255, 4
	v_readlane_b32 s5, v255, 5
	s_and_b64 s[4:5], s[0:1], s[4:5]
	s_mov_b64 exec, s[4:5]
	s_cbranch_execz .LBB0_174
	ds_read2st64_b32 v[4:5], v131 offset1:2
	ds_read2st64_b32 v[6:7], v131 offset0:4 offset1:6
	v_readlane_b32 s4, v254, 58
	v_readlane_b32 s5, v254, 59
	s_waitcnt lgkmcnt(1)
	v_mov_b32_e32 v8, v4
	s_waitcnt lgkmcnt(0)
	v_mov_b32_e32 v9, v6
	v_mov_b32_e32 v6, v5
	v_add_f32_e32 v4, v8, v6
	v_add_f32_e32 v5, v9, v7
	s_nop 0
	v_add_f32_e32 v6, v4, v5
	v_lshl_add_u32 v4, s62, 7, v1
	v_ashrrev_i32_e32 v5, 31, v4
	v_lshl_add_u64 v[4:5], v[4:5], 2, s[4:5]
	global_store_dword v[4:5], v6, off
	s_branch .LBB0_174

.LBB0_218:
	v_lshl_add_u64 v[4:5], v[54:55], 0, s[8:9]
	v_mad_u64_u32 v[8:9], s[10:11], v4, s12, v[56:57]
	v_mov_b32_e32 v2, v9
	v_mad_u64_u32 v[10:11], s[10:11], v5, s12, v[2:3]
	v_mov_b32_e32 v9, v10
	s_mov_b32 s5, 0x38000
	v_add_co_u32_e32 v114, vcc, s5, v8
	s_mov_b32 s5, 0x70000
	s_nop 0
	v_addc_co_u32_e32 v115, vcc, 0, v10, vcc
	v_add_co_u32_e32 v116, vcc, s5, v8
	s_mov_b32 s5, 0xa8000
	s_nop 0
	v_addc_co_u32_e32 v117, vcc, 0, v10, vcc
	v_add_co_u32_e32 v118, vcc, s5, v8
	s_nop 1
	v_addc_co_u32_e32 v119, vcc, 0, v10, vcc
	global_load_dwordx4 v[120:123], v[8:9], off
	global_load_dwordx4 v[124:127], v[114:115], off
	global_load_dwordx4 v[128:131], v[116:117], off
	global_load_dwordx4 v[132:135], v[118:119], off
	v_lshl_add_u64 v[4:5], v[58:59], 0, s[8:9]
	v_mad_u64_u32 v[68:69], s[8:9], v4, s12, v[64:65]
	v_mov_b32_e32 v2, v69
	v_lshlrev_b64 v[84:85], 11, v[4:5]
	v_mad_u64_u32 v[4:5], s[8:9], v5, s12, v[2:3]
	v_lshl_add_u64 v[32:33], v[60:61], 0, v[84:85]
	v_mov_b32_e32 v69, v4
	global_load_dwordx4 v[24:27], v[32:33], off
	global_load_dwordx2 v[86:87], v[68:69], off offset:3072
	global_load_dwordx4 v[28:31], v[32:33], off offset:64
	global_load_dwordx2 v[80:81], v[68:69], off offset:3104
	global_load_dwordx4 v[20:23], v[32:33], off offset:128
	global_load_dwordx2 v[78:79], v[68:69], off offset:3136
	global_load_dwordx4 v[12:15], v[32:33], off offset:192
	global_load_dwordx2 v[76:77], v[68:69], off offset:3168
	global_load_dwordx4 v[16:19], v[32:33], off offset:256
	global_load_dwordx2 v[74:75], v[68:69], off offset:3200
	global_load_dwordx4 v[8:11], v[32:33], off offset:320
	global_load_dwordx2 v[72:73], v[68:69], off offset:3232
	global_load_dwordx4 v[4:7], v[32:33], off offset:384
	global_load_dwordx2 v[70:71], v[68:69], off offset:3264
	s_nop 0
	global_load_dwordx4 v[32:35], v[32:33], off offset:448
	s_nop 0
	global_load_dwordx2 v[68:69], v[68:69], off offset:3296
	s_waitcnt lgkmcnt(0)
	s_barrier
	s_waitcnt vmcnt(19)
	ds_write_b128 v93, v[120:123] offset:34816
	s_waitcnt vmcnt(18)
	ds_write_b128 v93, v[124:127] offset:43520
	s_waitcnt vmcnt(17)
	ds_write_b128 v93, v[128:131] offset:52224
	s_waitcnt vmcnt(16)
	ds_write_b128 v93, v[132:135] offset:60928
	s_waitcnt lgkmcnt(0)
	s_barrier
	ds_read_b128 v[94:97], v91 offset:34816
	ds_read_b128 v[98:101], v91 offset:34880
	ds_read_b128 v[102:105], v91 offset:34944
	ds_read_b128 v[106:109], v91 offset:35008
	ds_read_b128 v[110:113], v92
	ds_read_b128 v[114:117], v92 offset:64
	ds_read_b128 v[118:121], v92 offset:4416
	s_waitcnt lgkmcnt(2)
	v_mfma_f32_16x16x32_bf16 v[110:113], v[110:113], v[94:97], 0
	ds_read_b128 v[122:125], v92 offset:8768
	ds_read_b128 v[126:129], v92 offset:13120
	ds_read_b128 v[130:133], v92 offset:17472
	s_waitcnt lgkmcnt(4)
	v_mfma_f32_16x16x32_bf16 v[110:113], v[114:117], v[98:101], v[110:113]
	ds_read_b128 v[114:117], v92 offset:128
	s_mov_b64 s[8:9], 0x80
	ds_read_b128 v[134:137], v92 offset:21824
	s_waitcnt lgkmcnt(1)
	v_mfma_f32_16x16x32_bf16 v[110:113], v[114:117], v[102:105], v[110:113]
	ds_read_b128 v[114:117], v92 offset:192
	ds_read_b128 v[138:141], v92 offset:26176
	s_waitcnt lgkmcnt(1)
	v_mfma_f32_16x16x32_bf16 v[110:113], v[114:117], v[106:109], v[110:113]
	ds_read_b128 v[114:117], v92 offset:4352
	s_waitcnt vmcnt(15)
	s_nop 5
	v_add_f32_e32 v24, v24, v110
	v_add_f32_e32 v25, v25, v111
	s_waitcnt lgkmcnt(0)
	v_mfma_f32_16x16x32_bf16 v[114:117], v[114:117], v[94:97], 0
	v_mfma_f32_16x16x32_bf16 v[114:117], v[118:121], v[98:101], v[114:117]
	ds_read_b128 v[118:121], v92 offset:4480
	s_waitcnt lgkmcnt(0)
	v_mfma_f32_16x16x32_bf16 v[114:117], v[118:121], v[102:105], v[114:117]
	ds_read_b128 v[118:121], v92 offset:4544
	s_waitcnt lgkmcnt(0)
	v_mfma_f32_16x16x32_bf16 v[114:117], v[118:121], v[106:109], v[114:117]
	ds_read_b128 v[118:121], v92 offset:8704
	s_waitcnt vmcnt(13)
	s_nop 5
	v_add_f32_e32 v82, v28, v114
	v_add_f32_e32 v83, v29, v115
	s_waitcnt lgkmcnt(0)
	v_mfma_f32_16x16x32_bf16 v[118:121], v[118:121], v[94:97], 0
	v_add_f32_e64 v30, v30, v116
	v_add_f32_e64 v31, v31, v117
	v_mov_b32_e32 v28, v25
	v_mov_b32_e32 v29, v83
	v_mfma_f32_16x16x32_bf16 v[118:121], v[122:125], v[98:101], v[118:121]
	ds_read_b128 v[122:125], v92 offset:8832
	v_mul_f32_e32 v28, v28, v28
	v_mul_f32_e32 v29, v29, v29
	s_waitcnt lgkmcnt(0)
	v_mfma_f32_16x16x32_bf16 v[118:121], v[122:125], v[102:105], v[118:121]
	ds_read_b128 v[122:125], v92 offset:8896
	s_waitcnt lgkmcnt(0)
	v_mfma_f32_16x16x32_bf16 v[118:121], v[122:125], v[106:109], v[118:121]
	ds_read_b128 v[122:125], v92 offset:13056
	s_waitcnt lgkmcnt(0)
	v_mfma_f32_16x16x32_bf16 v[122:125], v[122:125], v[94:97], 0
	v_mfma_f32_16x16x32_bf16 v[122:125], v[126:129], v[98:101], v[122:125]
	ds_read_b128 v[126:129], v92 offset:13184
	s_waitcnt lgkmcnt(0)
	v_mfma_f32_16x16x32_bf16 v[122:125], v[126:129], v[102:105], v[122:125]
	ds_read_b128 v[126:129], v92 offset:13248
	s_waitcnt lgkmcnt(0)
	v_mfma_f32_16x16x32_bf16 v[122:125], v[126:129], v[106:109], v[122:125]
	ds_read_b128 v[126:129], v92 offset:17408
	s_waitcnt lgkmcnt(0)
	v_mfma_f32_16x16x32_bf16 v[126:129], v[126:129], v[94:97], 0
	v_mfma_f32_16x16x32_bf16 v[126:129], v[130:133], v[98:101], v[126:129]
	ds_read_b128 v[130:133], v92 offset:17536
	s_waitcnt lgkmcnt(0)
	v_mfma_f32_16x16x32_bf16 v[126:129], v[130:133], v[102:105], v[126:129]
	ds_read_b128 v[130:133], v92 offset:17600
	s_waitcnt lgkmcnt(0)
	v_mfma_f32_16x16x32_bf16 v[126:129], v[130:133], v[106:109], v[126:129]
	ds_read_b128 v[130:133], v92 offset:21760
	s_waitcnt vmcnt(7)
	s_nop 5
	v_add_f32_e32 v16, v16, v126
	v_add_f32_e32 v17, v17, v127
	s_waitcnt lgkmcnt(0)
	v_mfma_f32_16x16x32_bf16 v[130:133], v[130:133], v[94:97], 0
	v_mul_f32_e32 v2, v16, v16
	v_add_f32_e32 v18, v18, v128
	v_add_f32_e32 v19, v19, v129
	v_mfma_f32_16x16x32_bf16 v[130:133], v[134:137], v[98:101], v[130:133]
	ds_read_b128 v[134:137], v92 offset:21888
	s_waitcnt lgkmcnt(0)
	v_mfma_f32_16x16x32_bf16 v[130:133], v[134:137], v[102:105], v[130:133]
	ds_read_b128 v[134:137], v92 offset:21952
	s_waitcnt lgkmcnt(0)
	v_mfma_f32_16x16x32_bf16 v[130:133], v[134:137], v[106:109], v[130:133]
	ds_read_b128 v[134:137], v92 offset:26112
	s_waitcnt lgkmcnt(0)
	v_mfma_f32_16x16x32_bf16 v[134:137], v[134:137], v[94:97], 0
	v_mfma_f32_16x16x32_bf16 v[134:137], v[138:141], v[98:101], v[134:137]
	ds_read_b128 v[138:141], v92 offset:26240
	s_waitcnt lgkmcnt(0)
	v_mfma_f32_16x16x32_bf16 v[134:137], v[138:141], v[102:105], v[134:137]
	ds_read_b128 v[138:141], v92 offset:26304
	s_waitcnt lgkmcnt(0)
	v_mfma_f32_16x16x32_bf16 v[134:137], v[138:141], v[106:109], v[134:137]
	ds_read_b128 v[138:141], v92 offset:30464
	s_waitcnt lgkmcnt(0)
	v_mfma_f32_16x16x32_bf16 v[94:97], v[138:141], v[94:97], 0
	ds_read_b128 v[138:141], v92 offset:30528
	s_waitcnt lgkmcnt(0)
	v_mfma_f32_16x16x32_bf16 v[94:97], v[138:141], v[98:101], v[94:97]
	ds_read_b128 v[98:101], v92 offset:30592
	s_waitcnt lgkmcnt(0)
	v_mfma_f32_16x16x32_bf16 v[94:97], v[98:101], v[102:105], v[94:97]
	ds_read_b128 v[98:101], v92 offset:30656
	v_mul_f32_e32 v104, v17, v17
	v_mul_f32_e32 v105, v18, v18
	s_waitcnt lgkmcnt(0)
	v_mfma_f32_16x16x32_bf16 v[94:97], v[98:101], v[106:109], v[94:97]
	v_add_f32_e64 v98, v26, v112
	v_add_f32_e64 v99, v27, v113
	v_mov_b32_e32 v26, v24
	v_mov_b32_e32 v27, v82
	v_mov_b32_e32 v100, v99
	v_mov_b32_e32 v101, v31
	v_fma_f32 v26, v26, v26, v28
	v_fma_f32 v27, v27, v27, v29
	v_mov_b32_e32 v28, v98
	v_mov_b32_e32 v29, v30
	v_mul_f32_e32 v100, v100, v100
	v_mul_f32_e32 v101, v101, v101
	v_mul_f32_e32 v106, v19, v19
	v_fma_f32 v28, v28, v28, v100
	v_fma_f32 v29, v29, v29, v101
	s_nop 0
	v_add_f32_e32 v100, v26, v28
	v_add_f32_e32 v101, v27, v29
	v_add_f32_e32 v26, v22, v120
	v_add_f32_e32 v27, v23, v121
	v_add_f32_e32 v28, v20, v118
	v_add_f32_e32 v29, v21, v119
	v_mul_f32_e32 v20, v26, v26
	v_mul_f32_e32 v21, v27, v27
	v_mul_f32_e32 v22, v28, v28
	v_mul_f32_e32 v23, v29, v29
	s_nop 0
	v_pk_mov_b32 v[102:103], v[22:23], v[20:21] op_sel:[1,0]
	v_mov_b32_e32 v23, v21
	v_add_f32_e32 v102, v102, v22
	v_add_f32_e32 v103, v103, v23
	v_add_f32_e32 v20, v14, v124
	v_add_f32_e32 v21, v15, v125
	v_add_f32_e32 v22, v12, v122
	v_add_f32_e32 v23, v13, v123
	v_add_f32_e32 v12, v100, v101
	v_add_f32_e32 v13, v101, v100
	v_add_f32_e32 v14, v102, v103
	v_add_f32_e32 v15, v103, v102
	v_mov_b32_e32 v13, v2
	v_mov_b32_e32 v15, v104
	v_mul_f32_e32 v2, v23, v23
	v_add_f32_e32 v12, v12, v14
	v_add_f32_e32 v13, v13, v15
	v_fma_f32 v14, v22, v22, v2
	v_fma_f32 v15, v23, v23, v2
	v_mul_f32_e32 v2, v21, v21
	v_fma_f32 v100, v20, v20, v2
	v_fma_f32 v101, v21, v21, v2
	v_mov_b32_e32 v15, v105
	v_mov_b32_e32 v101, v106
	v_add_f32_e32 v14, v14, v100
	v_add_f32_e32 v15, v15, v101
	s_nop 0
	v_add_f32_e32 v100, v12, v14
	v_add_f32_e32 v101, v13, v15
	s_waitcnt vmcnt(5)
	v_add_f32_e32 v12, v10, v132
	v_add_f32_e32 v13, v11, v133
	v_add_f32_e32 v14, v8, v130
	v_add_f32_e32 v15, v9, v131
	v_mul_f32_e32 v8, v12, v12
	v_mul_f32_e32 v9, v13, v13
	v_mul_f32_e32 v10, v14, v14
	v_mul_f32_e32 v11, v15, v15
	s_nop 0
	v_pk_mov_b32 v[102:103], v[10:11], v[8:9] op_sel:[1,0]
	v_mov_b32_e32 v11, v9
	v_add_f32_e32 v102, v102, v10
	v_add_f32_e32 v103, v103, v11
	s_waitcnt vmcnt(3)
	v_add_f32_e32 v8, v6, v136
	v_add_f32_e32 v9, v7, v137
	s_waitcnt vmcnt(1)
	v_add_f32_e32 v6, v32, v94
	v_add_f32_e32 v7, v33, v95
	v_add_f32_e32 v10, v4, v134
	v_add_f32_e32 v11, v5, v135
	v_add_f32_e32 v4, v34, v96
	v_add_f32_e32 v5, v35, v97
	v_mul_f32_e32 v2, v6, v6
	v_mul_f32_e32 v94, v7, v7
	v_add_f32_e32 v32, v100, v101
	v_add_f32_e32 v33, v101, v100
	v_add_f32_e32 v34, v102, v103
	v_add_f32_e32 v35, v103, v102
	v_mov_b32_e32 v33, v2
	v_mov_b32_e32 v35, v94
	v_mul_f32_e32 v2, v11, v11
	v_mul_f32_e32 v95, v4, v4
	v_add_f32_e32 v32, v32, v34
	v_add_f32_e32 v33, v33, v35
	v_fma_f32 v34, v10, v10, v2
	v_fma_f32 v35, v11, v11, v2
	v_mul_f32_e32 v2, v9, v9
	v_mul_f32_e32 v96, v5, v5
	v_mov_b32_e32 v35, v95
	v_fma_f32 v94, v8, v8, v2
	v_fma_f32 v95, v9, v9, v2
	s_nop 0
	v_mov_b32_e32 v95, v96
	v_add_f32_e32 v34, v34, v94
	v_add_f32_e32 v35, v35, v95
	v_lshlrev_b32_e32 v94, 16, v86
	v_add_f32_e32 v32, v32, v34
	v_add_f32_e32 v33, v33, v35
	v_and_b32_e32 v95, 0xffff0000, v86
	v_add_f32_e32 v2, v32, v33
	ds_bpermute_b32 v32, v89, v2
	v_mul_f32_e32 v86, 0xbfb8aa3b, v94
	v_exp_f32_e32 v86, v86
	s_waitcnt lgkmcnt(0)
	v_add_f32_e32 v2, v2, v32
	ds_bpermute_b32 v32, v90, v2
	v_add_f32_e32 v86, 1.0, v86
	v_rcp_f32_e32 v96, v86
	s_waitcnt lgkmcnt(0)
	v_add_f32_e32 v2, v2, v32
	v_fmamk_f32 v2, v2, 0x3c000000, v172
	v_cmp_gt_f32_e32 vcc, s33, v2
	v_mul_f32_e32 v32, 0x4b800000, v2
	s_nop 0
	v_cndmask_b32_e32 v2, v2, v32, vcc
	v_rsq_f32_e32 v2, v2
	s_nop 0
	v_mul_f32_e32 v32, 0x45800000, v2
	v_cndmask_b32_e32 v2, v2, v32, vcc
	v_mul_f32_e32 v24, v24, v2
	v_mul_f32_e32 v25, v25, v2
	v_mul_f32_e32 v82, v82, v2
	v_mul_f32_e32 v83, v83, v2
	v_mul_f32_e32 v30, v30, v2
	v_mul_f32_e32 v31, v31, v2
	v_mul_f32_e32 v28, v28, v2
	v_mul_f32_e32 v29, v29, v2
	v_mul_f32_e32 v26, v26, v2
	v_mul_f32_e32 v27, v27, v2
	v_mul_f32_e32 v22, v22, v2
	v_mul_f32_e32 v23, v23, v2
	v_mul_f32_e32 v20, v20, v2
	v_mul_f32_e32 v21, v21, v2
	v_mul_f32_e32 v16, v16, v2
	v_mul_f32_e32 v17, v17, v2
	v_mul_f32_e32 v18, v18, v2
	v_mul_f32_e32 v19, v19, v2
	v_mul_f32_e32 v14, v14, v2
	v_mul_f32_e32 v15, v15, v2
	v_mul_f32_e32 v12, v12, v2
	v_mul_f32_e32 v13, v13, v2
	v_mul_f32_e32 v10, v10, v2
	v_mul_f32_e32 v11, v11, v2
	v_mul_f32_e32 v8, v8, v2
	v_mul_f32_e32 v9, v9, v2
	v_mul_f32_e32 v6, v6, v2
	v_mul_f32_e32 v7, v7, v2
	v_mul_f32_e32 v4, v4, v2
	v_mul_f32_e32 v5, v5, v2
	s_andn2_b64 vcc, exec, s[6:7]
	s_mov_b64 s[6:7], 0
	s_waitcnt vmcnt(0)
	v_mov_b64_e32 v[32:33], v[184:185]
	v_mov_b64_e32 v[34:35], v[186:187]
	v_mul_f32_e32 v24, v32, v24
	v_mul_f32_e32 v25, v33, v25
	v_mul_f32_e32 v32, 0xbfb8aa3b, v95
	v_exp_f32_e32 v32, v32
	s_nop 0
	v_add_f32_e32 v32, 1.0, v32
	v_rcp_f32_e32 v97, v32
	s_nop 0
	v_mul_f32_e32 v32, v96, v94
	v_mul_f32_e32 v33, v97, v95
	s_nop 0
	v_mul_f32_e32 v24, v32, v24
	v_mul_f32_e32 v25, v33, v25
	v_lshlrev_b32_e32 v32, 16, v87
	v_and_b32_e32 v33, 0xffff0000, v87
	v_mul_f32_e32 v86, 0xbfb8aa3b, v32
	v_mul_f32_e32 v87, 0xbfb8aa3b, v33
	v_exp_f32_e32 v86, v86
	v_exp_f32_e32 v87, v87
	v_mul_f32_e32 v94, v98, v2
	v_mul_f32_e32 v95, v99, v2
	v_add_f32_e32 v86, 1.0, v86
	v_add_f32_e32 v87, 1.0, v87
	v_rcp_f32_e32 v86, v86
	v_rcp_f32_e32 v87, v87
	v_mul_f32_e32 v34, v34, v94
	v_mul_f32_e32 v35, v35, v95
	v_mul_f32_e32 v32, v86, v32
	v_mul_f32_e32 v33, v87, v33
	s_nop 0
	v_mul_f32_e32 v34, v32, v34
	v_mul_f32_e32 v35, v33, v35
	v_cvt_pk_bf16_f32 v32, v24, v25
	v_cvt_pk_bf16_f32 v33, v34, v35
	v_lshl_add_u64 v[24:25], v[66:67], 0, v[84:85]
	global_store_dwordx2 v[24:25], v[32:33], off
	v_lshlrev_b32_e32 v84, 16, v80
	v_and_b32_e32 v85, 0xffff0000, v80
	v_mul_f32_e32 v80, 0xbfb8aa3b, v84
	v_exp_f32_e32 v80, v80
	v_mov_b64_e32 v[32:33], v[188:189]
	v_mov_b64_e32 v[34:35], v[190:191]
	v_mul_f32_e32 v32, v32, v82
	v_mul_f32_e32 v33, v33, v83
	v_add_f32_e32 v80, 1.0, v80
	v_rcp_f32_e32 v86, v80
	v_mul_f32_e32 v80, 0xbfb8aa3b, v85
	v_exp_f32_e32 v80, v80
	v_mul_f32_e32 v30, v34, v30
	v_mul_f32_e32 v31, v35, v31
	v_add_f32_e32 v80, 1.0, v80
	v_rcp_f32_e32 v87, v80
	v_lshlrev_b32_e32 v80, 16, v81
	v_and_b32_e32 v81, 0xffff0000, v81
	v_mul_f32_e32 v34, 0xbfb8aa3b, v81
	v_mul_f32_e32 v82, v86, v84
	v_mul_f32_e32 v83, v87, v85
	v_exp_f32_e32 v34, v34
	v_mul_f32_e32 v32, v82, v32
	v_mul_f32_e32 v33, v83, v33
	v_mul_f32_e32 v82, 0xbfb8aa3b, v80
	v_exp_f32_e32 v82, v82
	v_add_f32_e32 v34, 1.0, v34
	v_rcp_f32_e32 v83, v34
	v_cvt_pk_bf16_f32 v32, v32, v33
	v_add_f32_e32 v82, 1.0, v82
	v_rcp_f32_e32 v82, v82
	s_nop 0
	v_mul_f32_e32 v34, v82, v80
	v_mul_f32_e32 v35, v83, v81
	s_nop 0
	v_mul_f32_e32 v30, v34, v30
	v_mul_f32_e32 v31, v35, v31
	v_lshlrev_b32_e32 v34, 16, v78
	v_cvt_pk_bf16_f32 v33, v30, v31
	global_store_dwordx2 v[24:25], v[32:33], off offset:32
	v_and_b32_e32 v35, 0xffff0000, v78
	v_mul_f32_e32 v78, 0xbfb8aa3b, v34
	v_exp_f32_e32 v78, v78
	v_mov_b64_e32 v[30:31], v[192:193]
	v_mov_b64_e32 v[32:33], v[194:195]
	v_mul_f32_e32 v28, v30, v28
	v_mul_f32_e32 v29, v31, v29
	v_mul_f32_e32 v30, 0xbfb8aa3b, v35
	v_exp_f32_e32 v30, v30
	v_add_f32_e32 v78, 1.0, v78
	v_rcp_f32_e32 v80, v78
	v_mul_f32_e32 v26, v32, v26
	v_mul_f32_e32 v27, v33, v27
	v_add_f32_e32 v30, 1.0, v30
	v_rcp_f32_e32 v81, v30
	s_nop 0
	v_mul_f32_e32 v30, v80, v34
	v_mul_f32_e32 v31, v81, v35
	s_nop 0
	v_mul_f32_e32 v28, v30, v28
	v_mul_f32_e32 v29, v31, v29
	v_lshlrev_b32_e32 v30, 16, v79
	v_and_b32_e32 v31, 0xffff0000, v79
	v_mul_f32_e32 v34, 0xbfb8aa3b, v30
	v_mul_f32_e32 v32, 0xbfb8aa3b, v31
	v_exp_f32_e32 v34, v34
	v_exp_f32_e32 v32, v32
	v_cvt_pk_bf16_f32 v28, v28, v29
	v_add_f32_e32 v34, 1.0, v34
	v_add_f32_e32 v32, 1.0, v32
	v_rcp_f32_e32 v34, v34
	v_rcp_f32_e32 v35, v32
	s_nop 0
	v_mul_f32_e32 v30, v34, v30
	v_mul_f32_e32 v31, v35, v31
	s_nop 0
	v_mul_f32_e32 v26, v30, v26
	v_mul_f32_e32 v27, v31, v27
	v_lshlrev_b32_e32 v30, 16, v76
	v_cvt_pk_bf16_f32 v29, v26, v27
	global_store_dwordx2 v[24:25], v[28:29], off offset:64
	v_and_b32_e32 v31, 0xffff0000, v76
	v_mul_f32_e32 v32, 0xbfb8aa3b, v30
	v_exp_f32_e32 v32, v32
	v_mov_b64_e32 v[26:27], v[196:197]
	v_mov_b64_e32 v[28:29], v[198:199]
	v_mul_f32_e32 v22, v26, v22
	v_mul_f32_e32 v23, v27, v23
	v_mul_f32_e32 v26, 0xbfb8aa3b, v31
	v_exp_f32_e32 v26, v26
	v_add_f32_e32 v32, 1.0, v32
	v_rcp_f32_e32 v32, v32
	v_mul_f32_e32 v20, v28, v20
	v_mul_f32_e32 v21, v29, v21
	v_add_f32_e32 v26, 1.0, v26
	v_rcp_f32_e32 v33, v26
	s_nop 0
	v_mul_f32_e32 v26, v32, v30
	v_mul_f32_e32 v27, v33, v31
	s_nop 0
	v_mul_f32_e32 v22, v26, v22
	v_mul_f32_e32 v23, v27, v23
	v_lshlrev_b32_e32 v26, 16, v77
	v_and_b32_e32 v27, 0xffff0000, v77
	v_mul_f32_e32 v30, 0xbfb8aa3b, v26
	v_mul_f32_e32 v28, 0xbfb8aa3b, v27
	v_exp_f32_e32 v30, v30
	v_exp_f32_e32 v28, v28
	v_cvt_pk_bf16_f32 v22, v22, v23
	v_add_f32_e32 v30, 1.0, v30
	v_add_f32_e32 v28, 1.0, v28
	v_rcp_f32_e32 v30, v30
	v_rcp_f32_e32 v31, v28
	s_nop 0
	v_mul_f32_e32 v26, v30, v26
	v_mul_f32_e32 v27, v31, v27
	s_nop 0
	v_mul_f32_e32 v20, v26, v20
	v_mul_f32_e32 v21, v27, v21
	v_lshlrev_b32_e32 v26, 16, v74
	v_cvt_pk_bf16_f32 v23, v20, v21
	global_store_dwordx2 v[24:25], v[22:23], off offset:96
	v_and_b32_e32 v27, 0xffff0000, v74
	v_mul_f32_e32 v28, 0xbfb8aa3b, v26
	v_exp_f32_e32 v28, v28
	v_mov_b64_e32 v[20:21], v[200:201]
	v_mov_b64_e32 v[22:23], v[202:203]
	v_mul_f32_e32 v16, v20, v16
	v_mul_f32_e32 v17, v21, v17
	v_mul_f32_e32 v20, 0xbfb8aa3b, v27
	v_exp_f32_e32 v20, v20
	v_add_f32_e32 v28, 1.0, v28
	v_rcp_f32_e32 v28, v28
	v_mul_f32_e32 v18, v22, v18
	v_mul_f32_e32 v19, v23, v19
	v_add_f32_e32 v20, 1.0, v20
	v_rcp_f32_e32 v29, v20
	s_nop 0
	v_mul_f32_e32 v20, v28, v26
	v_mul_f32_e32 v21, v29, v27
	s_nop 0
	v_mul_f32_e32 v16, v20, v16
	v_mul_f32_e32 v17, v21, v17
	v_lshlrev_b32_e32 v20, 16, v75
	v_and_b32_e32 v21, 0xffff0000, v75
	v_mul_f32_e32 v26, 0xbfb8aa3b, v20
	v_mul_f32_e32 v22, 0xbfb8aa3b, v21
	v_exp_f32_e32 v26, v26
	v_exp_f32_e32 v22, v22
	v_cvt_pk_bf16_f32 v16, v16, v17
	v_add_f32_e32 v26, 1.0, v26
	v_add_f32_e32 v22, 1.0, v22
	v_rcp_f32_e32 v26, v26
	v_rcp_f32_e32 v27, v22
	s_nop 0
	v_mul_f32_e32 v20, v26, v20
	v_mul_f32_e32 v21, v27, v21
	s_nop 0
	v_mul_f32_e32 v18, v20, v18
	v_mul_f32_e32 v19, v21, v19
	v_lshlrev_b32_e32 v20, 16, v72
	v_cvt_pk_bf16_f32 v17, v18, v19
	global_store_dwordx2 v[24:25], v[16:17], off offset:128
	v_and_b32_e32 v21, 0xffff0000, v72
	v_mul_f32_e32 v22, 0xbfb8aa3b, v20
	v_exp_f32_e32 v22, v22
	v_mov_b64_e32 v[16:17], v[204:205]
	v_mov_b64_e32 v[18:19], v[206:207]
	v_mul_f32_e32 v14, v16, v14
	v_mul_f32_e32 v15, v17, v15
	v_mul_f32_e32 v16, 0xbfb8aa3b, v21
	v_exp_f32_e32 v16, v16
	v_add_f32_e32 v22, 1.0, v22
	v_rcp_f32_e32 v22, v22
	v_mul_f32_e32 v12, v18, v12
	v_mul_f32_e32 v13, v19, v13
	v_add_f32_e32 v16, 1.0, v16
	v_rcp_f32_e32 v23, v16
	s_nop 0
	v_mul_f32_e32 v16, v22, v20
	v_mul_f32_e32 v17, v23, v21
	s_nop 0
	v_mul_f32_e32 v14, v16, v14
	v_mul_f32_e32 v15, v17, v15
	v_lshlrev_b32_e32 v16, 16, v73
	v_and_b32_e32 v17, 0xffff0000, v73
	v_mul_f32_e32 v20, 0xbfb8aa3b, v16
	v_mul_f32_e32 v18, 0xbfb8aa3b, v17
	v_exp_f32_e32 v20, v20
	v_exp_f32_e32 v18, v18
	v_cvt_pk_bf16_f32 v14, v14, v15
	v_add_f32_e32 v20, 1.0, v20
	v_add_f32_e32 v18, 1.0, v18
	v_rcp_f32_e32 v20, v20
	v_rcp_f32_e32 v21, v18
	s_nop 0
	v_mul_f32_e32 v16, v20, v16
	v_mul_f32_e32 v17, v21, v17
	s_nop 0
	v_mul_f32_e32 v12, v16, v12
	v_mul_f32_e32 v13, v17, v13
	v_lshlrev_b32_e32 v16, 16, v70
	v_cvt_pk_bf16_f32 v15, v12, v13
	global_store_dwordx2 v[24:25], v[14:15], off offset:160
	v_and_b32_e32 v17, 0xffff0000, v70
	v_mul_f32_e32 v18, 0xbfb8aa3b, v16
	v_exp_f32_e32 v18, v18
	v_mov_b64_e32 v[12:13], v[230:231]
	v_mov_b64_e32 v[14:15], v[232:233]
	v_mul_f32_e32 v10, v12, v10
	v_mul_f32_e32 v11, v13, v11
	v_mul_f32_e32 v12, 0xbfb8aa3b, v17
	v_exp_f32_e32 v12, v12
	v_add_f32_e32 v18, 1.0, v18
	v_rcp_f32_e32 v18, v18
	v_mul_f32_e32 v8, v14, v8
	v_mul_f32_e32 v9, v15, v9
	v_add_f32_e32 v12, 1.0, v12
	v_rcp_f32_e32 v19, v12
	s_nop 0
	v_mul_f32_e32 v12, v18, v16
	v_mul_f32_e32 v13, v19, v17
	s_nop 0
	v_mul_f32_e32 v10, v12, v10
	v_mul_f32_e32 v11, v13, v11
	v_lshlrev_b32_e32 v12, 16, v71
	v_and_b32_e32 v13, 0xffff0000, v71
	v_mul_f32_e32 v16, 0xbfb8aa3b, v12
	v_mul_f32_e32 v14, 0xbfb8aa3b, v13
	v_exp_f32_e32 v16, v16
	v_exp_f32_e32 v14, v14
	v_cvt_pk_bf16_f32 v10, v10, v11
	v_add_f32_e32 v16, 1.0, v16
	v_add_f32_e32 v14, 1.0, v14
	v_rcp_f32_e32 v16, v16
	v_rcp_f32_e32 v17, v14
	s_nop 0
	v_mul_f32_e32 v12, v16, v12
	v_mul_f32_e32 v13, v17, v13
	s_nop 0
	v_mul_f32_e32 v8, v12, v8
	v_mul_f32_e32 v9, v13, v9
	v_lshlrev_b32_e32 v12, 16, v68
	v_cvt_pk_bf16_f32 v11, v8, v9
	global_store_dwordx2 v[24:25], v[10:11], off offset:192
	v_and_b32_e32 v13, 0xffff0000, v68
	v_mul_f32_e32 v14, 0xbfb8aa3b, v12
	v_exp_f32_e32 v14, v14
	v_mov_b64_e32 v[8:9], v[234:235]
	v_mov_b64_e32 v[10:11], v[236:237]
	v_mul_f32_e32 v6, v6, v8
	v_mul_f32_e32 v7, v7, v9
	v_mul_f32_e32 v8, 0xbfb8aa3b, v13
	v_exp_f32_e32 v8, v8
	v_add_f32_e32 v14, 1.0, v14
	v_rcp_f32_e32 v14, v14
	v_mul_f32_e32 v4, v4, v10
	v_mul_f32_e32 v5, v5, v11
	v_add_f32_e32 v8, 1.0, v8
	v_rcp_f32_e32 v15, v8
	s_nop 0
	v_mul_f32_e32 v8, v14, v12
	v_mul_f32_e32 v9, v15, v13
	s_nop 0
	v_mul_f32_e32 v6, v8, v6
	v_mul_f32_e32 v7, v9, v7
	v_lshlrev_b32_e32 v8, 16, v69
	v_and_b32_e32 v9, 0xffff0000, v69
	v_mul_f32_e32 v12, 0xbfb8aa3b, v8
	v_mul_f32_e32 v2, 0xbfb8aa3b, v9
	v_exp_f32_e32 v12, v12
	v_exp_f32_e32 v2, v2
	v_cvt_pk_bf16_f32 v6, v6, v7
	v_add_f32_e32 v12, 1.0, v12
	v_add_f32_e32 v2, 1.0, v2
	v_rcp_f32_e32 v12, v12
	v_rcp_f32_e32 v13, v2
	s_nop 0
	v_mul_f32_e32 v8, v12, v8
	v_mul_f32_e32 v9, v13, v9
	s_nop 0
	v_mul_f32_e32 v4, v8, v4
	v_mul_f32_e32 v5, v9, v5
	s_nop 0
	v_cvt_pk_bf16_f32 v7, v4, v5
	global_store_dwordx2 v[24:25], v[6:7], off offset:224
	s_cbranch_vccz .LBB0_218
	v_readlane_b32 s6, v252, 7
	v_readlane_b32 s7, v252, 8
	s_load_dword s5, s[6:7], 0x0
	s_waitcnt lgkmcnt(0)
	s_add_i32 s4, s4, s5
	s_cmpk_gt_i32 s4, 0xff
	s_cbranch_scc0 .LBB0_217

.LBB0_227:
	s_and_b32 s0, s28, 0x7f
	s_cmp_eq_u32 s0, 0
	s_cbranch_scc1 .LBB0_229
	s_lshl_b32 s4, s28, 6
	s_mul_i32 s1, s28, 0x70000
	s_add_i32 s0, s4, -2
	s_addk_i32 s1, 0xc800
	s_mul_hi_i32 s5, s0, 0x1c00
	s_add_u32 s0, s88, s1
	s_addc_u32 s1, s89, s5
	s_add_i32 s4, s4, -1
	s_mul_hi_i32 s5, s4, 0x1c00
	s_mulk_i32 s4, 0x1c00
	s_add_u32 s4, s88, s4
	s_addc_u32 s5, s89, s5
	v_lshl_add_u64 v[10:11], s[0:1], 0, v[6:7]
	s_waitcnt vmcnt(17)
	v_lshl_add_u64 v[12:13], s[0:1], 0, v[8:9]
	v_lshl_add_u64 v[14:15], s[4:5], 0, v[6:7]
	s_waitcnt vmcnt(16)
	v_lshl_add_u64 v[16:17], s[4:5], 0, v[8:9]
	global_load_ushort v2, v[10:11], off
	s_nop 0
	global_load_ushort v11, v[14:15], off
	s_nop 0
	global_load_ushort v14, v[16:17], off
	s_nop 0
	global_load_ushort v12, v[12:13], off
	s_waitcnt vmcnt(3)
	v_lshlrev_b32_e32 v10, 16, v2
	s_waitcnt vmcnt(2)
	v_lshlrev_b32_e32 v11, 16, v11
	s_waitcnt vmcnt(1)
	v_lshlrev_b32_e32 v13, 16, v14
	s_waitcnt vmcnt(0)
	v_lshlrev_b32_e32 v12, 16, v12
	v_mul_f32_e32 v10, v10, v12
	v_mul_f32_e32 v11, v11, v13
	s_branch .LBB0_230

.LBB0_231:
	s_add_i32 s30, s27, s29
	s_add_i32 s24, s30, 16
	v_mad_i64_i32 v[46:47], s[0:1], s24, v221, v[0:1]
	v_add_co_u32_e32 v46, vcc, s3, v46
	s_add_i32 s64, s30, 17
	s_nop 0
	v_addc_co_u32_e32 v47, vcc, 0, v47, vcc
	global_load_ushort v2, v[46:47], off offset:1024
	global_load_ushort v48, v[46:47], off offset:2048
	v_mad_i64_i32 v[40:41], s[0:1], s64, v221, v[0:1]
	global_load_ushort v46, v[46:47], off
	v_add_co_u32_e32 v40, vcc, s3, v40
	s_add_i32 s62, s30, 18
	s_nop 0
	v_addc_co_u32_e32 v41, vcc, 0, v41, vcc
	global_load_ushort v49, v[40:41], off offset:1024
	global_load_ushort v50, v[40:41], off offset:2048
	s_nop 0
	global_load_ushort v40, v[40:41], off
	v_mad_i64_i32 v[38:39], s[0:1], s62, v221, v[0:1]
	v_add_co_u32_e32 v38, vcc, s3, v38
	s_add_i32 s60, s30, 19
	s_nop 0
	v_addc_co_u32_e32 v39, vcc, 0, v39, vcc
	global_load_ushort v41, v[38:39], off offset:1024
	global_load_ushort v51, v[38:39], off offset:2048
	s_nop 0
	global_load_ushort v38, v[38:39], off
	v_mad_i64_i32 v[36:37], s[0:1], s60, v221, v[0:1]
	v_add_co_u32_e32 v36, vcc, s3, v36
	s_add_i32 s58, s30, 20
	s_nop 0
	v_addc_co_u32_e32 v37, vcc, 0, v37, vcc
	global_load_ushort v39, v[36:37], off offset:1024
	global_load_ushort v52, v[36:37], off offset:2048
	s_nop 0
	global_load_ushort v36, v[36:37], off
	s_waitcnt vmcnt(24)
	v_mad_i64_i32 v[34:35], s[0:1], s58, v221, v[0:1]
	v_add_co_u32_e32 v34, vcc, s3, v34
	s_add_i32 s56, s30, 21
	s_nop 0
	v_addc_co_u32_e32 v35, vcc, 0, v35, vcc
	global_load_ushort v37, v[34:35], off offset:1024
	global_load_ushort v53, v[34:35], off offset:2048
	global_load_ushort v54, v[34:35], off
	v_mad_i64_i32 v[32:33], s[0:1], s56, v221, v[0:1]
	v_add_co_u32_e32 v32, vcc, s3, v32
	s_add_i32 s52, s30, 22
	s_nop 0
	v_addc_co_u32_e32 v33, vcc, 0, v33, vcc
	global_load_ushort v55, v[32:33], off offset:1024
	global_load_ushort v56, v[32:33], off offset:2048
	global_load_ushort v57, v[32:33], off
	v_mad_i64_i32 v[30:31], s[0:1], s52, v221, v[0:1]
	v_add_co_u32_e32 v30, vcc, s3, v30
	s_add_i32 s18, s30, 23
	s_nop 0
	v_addc_co_u32_e32 v31, vcc, 0, v31, vcc
	global_load_ushort v58, v[30:31], off offset:1024
	global_load_ushort v59, v[30:31], off offset:2048
	global_load_ushort v60, v[30:31], off
	v_mad_i64_i32 v[28:29], s[0:1], s18, v221, v[0:1]
	v_add_co_u32_e32 v28, vcc, s3, v28
	s_add_i32 s16, s30, 24
	s_nop 0
	v_addc_co_u32_e32 v29, vcc, 0, v29, vcc
	global_load_ushort v61, v[28:29], off offset:1024
	global_load_ushort v62, v[28:29], off offset:2048
	global_load_ushort v63, v[28:29], off
	v_mad_i64_i32 v[26:27], s[0:1], s16, v221, v[0:1]
	v_add_co_u32_e32 v26, vcc, s3, v26
	s_add_i32 s14, s30, 25
	s_nop 0
	v_addc_co_u32_e32 v27, vcc, 0, v27, vcc
	global_load_ushort v64, v[26:27], off offset:1024
	global_load_ushort v65, v[26:27], off offset:2048
	global_load_ushort v66, v[26:27], off
	v_mad_i64_i32 v[24:25], s[0:1], s14, v221, v[0:1]
	s_add_i32 s12, s30, 26
	v_add_co_u32_e32 v24, vcc, s3, v24
	v_mad_i64_i32 v[22:23], s[0:1], s12, v221, v[0:1]
	s_nop 0
	v_addc_co_u32_e32 v25, vcc, 0, v25, vcc
	global_load_ushort v30, v[24:25], off offset:1024
	global_load_ushort v31, v[24:25], off offset:2048
	global_load_ushort v29, v[24:25], off
	v_add_co_u32_e32 v22, vcc, s3, v22
	s_add_i32 s10, s30, 27
	s_nop 0
	v_addc_co_u32_e32 v23, vcc, 0, v23, vcc
	global_load_ushort v27, v[22:23], off offset:1024
	global_load_ushort v28, v[22:23], off offset:2048
	global_load_ushort v26, v[22:23], off
	v_mad_i64_i32 v[20:21], s[0:1], s10, v221, v[0:1]
	v_add_co_u32_e32 v20, vcc, s3, v20
	s_add_i32 s8, s30, 28
	s_nop 0
	v_addc_co_u32_e32 v21, vcc, 0, v21, vcc
	global_load_ushort v24, v[20:21], off offset:1024
	global_load_ushort v25, v[20:21], off offset:2048
	global_load_ushort v23, v[20:21], off
	v_mad_i64_i32 v[18:19], s[0:1], s8, v221, v[0:1]
	v_add_co_u32_e32 v18, vcc, s3, v18
	s_add_i32 s6, s30, 29
	s_nop 0
	v_addc_co_u32_e32 v19, vcc, 0, v19, vcc
	global_load_ushort v21, v[18:19], off offset:1024
	global_load_ushort v22, v[18:19], off offset:2048
	global_load_ushort v20, v[18:19], off
	v_mad_i64_i32 v[16:17], s[0:1], s6, v221, v[0:1]
	v_add_co_u32_e32 v16, vcc, s3, v16
	s_add_i32 s4, s30, 30
	s_nop 0
	v_addc_co_u32_e32 v17, vcc, 0, v17, vcc
	v_mad_i64_i32 v[14:15], s[0:1], s4, v221, v[0:1]
	s_waitcnt vmcnt(38)
	v_lshlrev_b32_e32 v2, 16, v2
	s_waitcnt vmcnt(37)
	v_lshlrev_b32_e32 v48, 16, v48
	v_fma_f32 v10, v42, v10, v45
	global_load_ushort v18, v[16:17], off offset:1024
	global_load_ushort v19, v[16:17], off offset:2048
	s_nop 0
	global_load_ushort v17, v[16:17], off
	s_add_i32 s0, s30, 31
	v_mul_f32_e32 v2, v2, v48
	v_fmac_f32_e32 v10, v43, v11
	v_add_co_u32_e32 v32, vcc, s3, v14
	v_mad_i64_i32 v[12:13], s[30:31], s0, v221, v[0:1]
	s_waitcnt vmcnt(39)
	v_lshlrev_b32_e32 v46, 16, v46
	v_fmac_f32_e32 v10, v44, v2
	v_addc_co_u32_e32 v33, vcc, 0, v15, vcc
	v_mul_f32_e32 v10, v10, v46
	v_add_co_u32_e32 v34, vcc, s3, v12
	v_cvt_pk_bf16_f32 v48, v10, s0
	global_load_ushort v16, v[32:33], off
	global_load_ushort v10, v[32:33], off offset:1024
	v_addc_co_u32_e32 v35, vcc, 0, v13, vcc
	global_load_ushort v14, v[34:35], off offset:1024
	global_load_ushort v13, v[32:33], off offset:2048
	global_load_ushort v15, v[34:35], off offset:2048
	global_load_ushort v12, v[34:35], off
	s_waitcnt vmcnt(44)
	v_lshlrev_b32_e32 v32, 16, v49
	s_waitcnt vmcnt(43)
	v_lshlrev_b32_e32 v33, 16, v50
	v_fma_f32 v11, v42, v11, v45
	s_ashr_i32 s25, s24, 31
	v_mul_f32_e32 v34, v32, v33
	v_fmac_f32_e32 v11, v43, v2
	s_ashr_i32 s65, s64, 31
	s_lshl_b64 s[24:25], s[24:25], 11
	s_waitcnt vmcnt(42)
	v_lshlrev_b32_e32 v32, 16, v40
	v_fmac_f32_e32 v11, v44, v34
	v_lshl_add_u64 v[46:47], v[4:5], 0, s[24:25]
	v_mul_f32_e32 v11, v11, v32
	s_lshl_b64 s[24:25], s[64:65], 11
	v_cvt_pk_bf16_f32 v11, v11, s0
	v_lshl_add_u64 v[32:33], v[4:5], 0, s[24:25]
	global_store_short v[32:33], v11, off
	s_waitcnt vmcnt(42)
	v_lshlrev_b32_e32 v11, 16, v41
	s_waitcnt vmcnt(41)
	v_lshlrev_b32_e32 v32, 16, v51
	v_fma_f32 v2, v42, v2, v45
	v_mul_f32_e32 v11, v11, v32
	v_fmac_f32_e32 v2, v43, v34
	s_ashr_i32 s63, s62, 31
	s_waitcnt vmcnt(40)
	v_lshlrev_b32_e32 v32, 16, v38
	v_fmac_f32_e32 v2, v44, v11
	v_mul_f32_e32 v2, v2, v32
	s_lshl_b64 s[24:25], s[62:63], 11
	v_cvt_pk_bf16_f32 v2, v2, s0
	v_lshl_add_u64 v[32:33], v[4:5], 0, s[24:25]
	global_store_short v[32:33], v2, off
	s_waitcnt vmcnt(40)
	v_lshlrev_b32_e32 v2, 16, v39
	s_waitcnt vmcnt(39)
	v_lshlrev_b32_e32 v32, 16, v52
	v_fma_f32 v33, v42, v34, v45
	v_mul_f32_e32 v2, v2, v32
	v_fmac_f32_e32 v33, v43, v11
	s_ashr_i32 s61, s60, 31
	s_waitcnt vmcnt(38)
	v_lshlrev_b32_e32 v32, 16, v36
	v_fmac_f32_e32 v33, v44, v2
	v_mul_f32_e32 v32, v33, v32
	s_lshl_b64 s[24:25], s[60:61], 11
	v_cvt_pk_bf16_f32 v34, v32, s0
	v_lshl_add_u64 v[32:33], v[4:5], 0, s[24:25]
	global_store_short v[32:33], v34, off
	s_waitcnt vmcnt(38)
	v_lshlrev_b32_e32 v32, 16, v37
	s_waitcnt vmcnt(37)
	v_lshlrev_b32_e32 v33, 16, v53
	v_fma_f32 v11, v42, v11, v45
	v_mul_f32_e32 v34, v32, v33
	v_fmac_f32_e32 v11, v43, v2
	s_ashr_i32 s59, s58, 31
	s_waitcnt vmcnt(36)
	v_lshlrev_b32_e32 v32, 16, v54
	v_fmac_f32_e32 v11, v44, v34
	v_mul_f32_e32 v11, v11, v32
	s_lshl_b64 s[24:25], s[58:59], 11
	v_cvt_pk_bf16_f32 v11, v11, s0
	v_lshl_add_u64 v[32:33], v[4:5], 0, s[24:25]
	global_store_short v[32:33], v11, off
	s_waitcnt vmcnt(36)
	v_lshlrev_b32_e32 v11, 16, v55
	s_waitcnt vmcnt(35)
	v_lshlrev_b32_e32 v32, 16, v56
	v_fma_f32 v2, v42, v2, v45
	v_mul_f32_e32 v11, v11, v32
	v_fmac_f32_e32 v2, v43, v34
	s_ashr_i32 s57, s56, 31
	s_waitcnt vmcnt(34)
	v_lshlrev_b32_e32 v32, 16, v57
	v_fmac_f32_e32 v2, v44, v11
	v_mul_f32_e32 v2, v2, v32
	s_lshl_b64 s[24:25], s[56:57], 11
	v_cvt_pk_bf16_f32 v2, v2, s0
	v_lshl_add_u64 v[32:33], v[4:5], 0, s[24:25]
	global_store_short v[32:33], v2, off
	s_waitcnt vmcnt(34)
	v_lshlrev_b32_e32 v2, 16, v58
	s_waitcnt vmcnt(33)
	v_lshlrev_b32_e32 v32, 16, v59
	v_fma_f32 v33, v42, v34, v45
	v_mul_f32_e32 v2, v2, v32
	v_fmac_f32_e32 v33, v43, v11
	s_ashr_i32 s53, s52, 31
	s_waitcnt vmcnt(32)
	v_lshlrev_b32_e32 v32, 16, v60
	v_fmac_f32_e32 v33, v44, v2
	v_mul_f32_e32 v32, v33, v32
	s_lshl_b64 s[24:25], s[52:53], 11
	v_cvt_pk_bf16_f32 v34, v32, s0
	v_lshl_add_u64 v[32:33], v[4:5], 0, s[24:25]
	global_store_short v[32:33], v34, off
	s_waitcnt vmcnt(32)
	v_lshlrev_b32_e32 v32, 16, v61
	s_waitcnt vmcnt(31)
	v_lshlrev_b32_e32 v33, 16, v62
	v_fma_f32 v11, v42, v11, v45
	v_mul_f32_e32 v34, v32, v33
	v_fmac_f32_e32 v11, v43, v2
	s_ashr_i32 s19, s18, 31
	s_waitcnt vmcnt(30)
	v_lshlrev_b32_e32 v32, 16, v63
	v_fmac_f32_e32 v11, v44, v34
	v_mul_f32_e32 v11, v11, v32
	s_lshl_b64 s[18:19], s[18:19], 11
	v_cvt_pk_bf16_f32 v11, v11, s0
	v_lshl_add_u64 v[32:33], v[4:5], 0, s[18:19]
	global_store_short v[32:33], v11, off
	s_waitcnt vmcnt(30)
	v_lshlrev_b32_e32 v11, 16, v64
	s_waitcnt vmcnt(29)
	v_lshlrev_b32_e32 v32, 16, v65
	v_fma_f32 v2, v42, v2, v45
	v_mul_f32_e32 v11, v11, v32
	v_fmac_f32_e32 v2, v43, v34
	s_ashr_i32 s17, s16, 31
	s_waitcnt vmcnt(28)
	v_lshlrev_b32_e32 v32, 16, v66
	v_fmac_f32_e32 v2, v44, v11
	v_mul_f32_e32 v2, v2, v32
	s_lshl_b64 s[16:17], s[16:17], 11
	v_cvt_pk_bf16_f32 v2, v2, s0
	v_lshl_add_u64 v[32:33], v[4:5], 0, s[16:17]
	global_store_short v[32:33], v2, off
	s_waitcnt vmcnt(28)
	v_lshlrev_b32_e32 v2, 16, v30
	s_waitcnt vmcnt(27)
	v_lshlrev_b32_e32 v30, 16, v31
	v_mul_f32_e32 v2, v2, v30
	v_fma_f32 v30, v42, v34, v45
	v_fmac_f32_e32 v30, v43, v11
	s_waitcnt vmcnt(25)
	v_lshlrev_b32_e32 v27, 16, v27
	s_waitcnt vmcnt(24)
	v_lshlrev_b32_e32 v28, 16, v28
	v_fma_f32 v11, v42, v11, v45
	v_mul_f32_e32 v28, v27, v28
	v_fmac_f32_e32 v11, v43, v2
	s_ashr_i32 s13, s12, 31
	s_waitcnt vmcnt(23)
	v_lshlrev_b32_e32 v26, 16, v26
	v_fmac_f32_e32 v11, v44, v28
	v_mul_f32_e32 v11, v11, v26
	s_lshl_b64 s[12:13], s[12:13], 11
	v_cvt_pk_bf16_f32 v11, v11, s0
	v_lshl_add_u64 v[26:27], v[4:5], 0, s[12:13]
	v_fmac_f32_e32 v30, v44, v2
	global_store_short v[26:27], v11, off
	s_waitcnt vmcnt(23)
	v_lshlrev_b32_e32 v11, 16, v24
	s_waitcnt vmcnt(22)
	v_lshlrev_b32_e32 v24, 16, v25
	v_fma_f32 v2, v42, v2, v45
	v_mul_f32_e32 v11, v11, v24
	v_fmac_f32_e32 v2, v43, v28
	s_ashr_i32 s11, s10, 31
	s_waitcnt vmcnt(21)
	v_lshlrev_b32_e32 v23, 16, v23
	v_fmac_f32_e32 v2, v44, v11
	v_mul_f32_e32 v2, v2, v23
	s_lshl_b64 s[10:11], s[10:11], 11
	v_cvt_pk_bf16_f32 v2, v2, s0
	v_lshl_add_u64 v[24:25], v[4:5], 0, s[10:11]
	global_store_short v[24:25], v2, off
	s_waitcnt vmcnt(21)
	v_lshlrev_b32_e32 v2, 16, v21
	s_waitcnt vmcnt(20)
	v_lshlrev_b32_e32 v21, 16, v22
	v_mul_f32_e32 v2, v2, v21
	v_fma_f32 v21, v42, v28, v45
	v_fmac_f32_e32 v21, v43, v11
	s_ashr_i32 s9, s8, 31
	s_waitcnt vmcnt(19)
	v_lshlrev_b32_e32 v20, 16, v20
	v_fmac_f32_e32 v21, v44, v2
	v_mul_f32_e32 v20, v21, v20
	s_lshl_b64 s[8:9], s[8:9], 11
	v_cvt_pk_bf16_f32 v22, v20, s0
	v_lshl_add_u64 v[20:21], v[4:5], 0, s[8:9]
	s_waitcnt vmcnt(18)
	v_lshlrev_b32_e32 v18, 16, v18
	s_waitcnt vmcnt(17)
	v_lshlrev_b32_e32 v19, 16, v19
	v_fma_f32 v11, v42, v11, v45
	global_store_short v[20:21], v22, off
	v_mul_f32_e32 v20, v18, v19
	v_fmac_f32_e32 v11, v43, v2
	s_ashr_i32 s7, s6, 31
	s_waitcnt vmcnt(17)
	v_lshlrev_b32_e32 v17, 16, v17
	v_fmac_f32_e32 v11, v44, v20
	v_mul_f32_e32 v11, v11, v17
	s_lshl_b64 s[6:7], s[6:7], 11
	v_cvt_pk_bf16_f32 v11, v11, s0
	v_lshl_add_u64 v[18:19], v[4:5], 0, s[6:7]
	global_store_short v[18:19], v11, off
	v_fma_f32 v2, v42, v2, v45
	s_waitcnt vmcnt(15)
	v_lshlrev_b32_e32 v11, 16, v14
	v_lshlrev_b32_e32 v10, 16, v10
	s_waitcnt vmcnt(13)
	v_lshlrev_b32_e32 v15, 16, v15
	v_lshlrev_b32_e32 v14, 16, v13
	v_fmac_f32_e32 v2, v43, v20
	v_mul_f32_e32 v10, v10, v14
	v_mul_f32_e32 v11, v11, v15
	s_ashr_i32 s5, s4, 31
	v_lshlrev_b32_e32 v18, 16, v16
	v_fmac_f32_e32 v2, v44, v10
	s_lshl_b64 s[4:5], s[4:5], 11
	v_mul_f32_e32 v2, v2, v18
	v_lshl_add_u64 v[16:17], v[4:5], 0, s[4:5]
	v_cvt_pk_bf16_f32 v2, v2, s0
	global_store_short v[16:17], v2, off
	s_waitcnt vmcnt(13)
	v_lshlrev_b32_e32 v2, 16, v12
	v_fma_f32 v12, v42, v20, v45
	v_fmac_f32_e32 v12, v43, v10
	v_lshlrev_b32_e32 v29, 16, v29
	v_fmac_f32_e32 v12, v44, v11
	s_ashr_i32 s15, s14, 31
	s_ashr_i32 s1, s0, 31
	v_mul_f32_e32 v29, v30, v29
	v_mul_f32_e32 v2, v12, v2
	v_cvt_pk_bf16_f32 v29, v29, s0
	s_lshl_b64 s[14:15], s[14:15], 11
	v_cvt_pk_bf16_f32 v2, v2, s0
	s_lshl_b64 s[0:1], s[0:1], 11
	s_add_i32 s29, s29, 16
	v_lshl_add_u64 v[30:31], v[4:5], 0, s[14:15]
	v_lshl_add_u64 v[12:13], v[4:5], 0, s[0:1]
	s_cmp_lt_u32 s29, 48
	global_store_short v[46:47], v48, off
	global_store_short v[30:31], v29, off
	global_store_short v[12:13], v2, off
	s_cbranch_scc1 .LBB0_231
	s_add_i32 s28, s28, s20
	s_add_i32 s27, s27, s26
	s_cmpk_gt_i32 s28, 0xff
	s_movk_i32 s62, 0xb1
	s_movk_i32 s63, 0x3fff
	s_movk_i32 s64, 0x110
	s_movk_i32 s65, 0x2000
	s_cbranch_scc0 .LBB0_227

.LBB0_242:
	s_waitcnt lgkmcnt(0)
	s_barrier
	ds_read_b128 v[146:149], v119
	ds_read_b128 v[150:153], v119 offset:64
	ds_read_b128 v[154:157], v119 offset:128
	ds_read_b128 v[56:59], v119 offset:192
	ds_read_b128 v[52:55], v120
	ds_read_b128 v[48:51], v120 offset:64
	ds_read_b128 v[44:47], v120 offset:128
	ds_read_b128 v[40:43], v120 offset:192
	ds_read_b128 v[158:161], v121 offset:8704
	ds_read_b128 v[162:165], v121 offset:13056
	ds_read_b128 v[184:187], v121 offset:8768
	ds_read_b128 v[188:191], v121 offset:13120
	s_waitcnt lgkmcnt(3)
	v_mfma_f32_16x16x32_bf16 v[166:169], v[158:161], v[146:149], 0
	v_add_f32_e32 v133, v133, v2
	s_add_i32 s20, s20, -1
	s_cmp_eq_u32 s20, 0
	s_waitcnt lgkmcnt(2)
	v_mfma_f32_16x16x32_bf16 v[162:165], v[162:165], v[52:55], 0
	v_mfma_f32_16x16x32_bf16 v[158:161], v[158:161], v[52:55], 0
	s_waitcnt lgkmcnt(0)
	v_mfma_f32_16x16x32_bf16 v[162:165], v[188:191], v[48:51], v[162:165]
	ds_read_b128 v[188:191], v121 offset:8832
	ds_read_b128 v[192:195], v121 offset:13184
	v_mfma_f32_16x16x32_bf16 v[166:169], v[184:187], v[150:153], v[166:169]
	v_mfma_f32_16x16x32_bf16 v[158:161], v[184:187], v[48:51], v[158:161]
	s_waitcnt lgkmcnt(0)
	v_mfma_f32_16x16x32_bf16 v[162:165], v[192:195], v[44:47], v[162:165]
	ds_read_b128 v[192:195], v121 offset:8896
	ds_read_b128 v[196:199], v121 offset:13248
	v_mfma_f32_16x16x32_bf16 v[166:169], v[188:191], v[154:157], v[166:169]
	v_mfma_f32_16x16x32_bf16 v[158:161], v[188:191], v[44:47], v[158:161]
	s_waitcnt lgkmcnt(1)
	v_mfma_f32_16x16x32_bf16 v[166:169], v[192:195], v[56:59], v[166:169]
	s_waitcnt lgkmcnt(0)
	v_mfma_f32_16x16x32_bf16 v[162:165], v[196:199], v[40:43], v[162:165]
	v_mfma_f32_16x16x32_bf16 v[158:161], v[192:195], v[40:43], v[158:161]
	s_nop 4
	v_cndmask_b32_e64 v0, v166, 0, s[12:13]
	s_nop 0
	v_cndmask_b32_e64 v145, v162, 0, s[12:13]
	v_cndmask_b32_e64 v1, 0, v167, s[14:15]
	v_cndmask_b32_e64 v162, 0, v163, s[14:15]
	v_cndmask_b32_e64 v2, v168, 0, s[16:17]
	v_cndmask_b32_e64 v163, v164, 0, s[16:17]
	v_cndmask_b32_e64 v164, v169, 0, s[18:19]
	v_cndmask_b32_e64 v165, v165, 0, s[18:19]
	v_cvt_pk_bf16_f32 v0, v0, v1
	v_cvt_pk_bf16_f32 v1, v2, v164
	v_cvt_pk_bf16_f32 v158, v158, v159
	v_cvt_pk_bf16_f32 v159, v160, v161
	v_cvt_pk_bf16_f32 v160, v145, v162
	v_cvt_pk_bf16_f32 v161, v163, v165
	ds_read2_b64 v[162:165], v126 offset0:128 offset1:132
	ds_read_b128 v[166:169], v122 offset:37888
	ds_read_b128 v[184:187], v122 offset:37952
	s_waitcnt lgkmcnt(1)
	v_mfma_f32_16x16x32_bf16 v[146:149], v[166:169], v[146:149], 0
	v_mov_b32_e32 v2, v3
	s_waitcnt lgkmcnt(0)
	v_mfma_f32_16x16x32_bf16 v[146:149], v[184:187], v[150:153], v[146:149]
	ds_read_b128 v[150:153], v122 offset:38016
	v_mfma_f32_16x16x32_bf16 v[52:55], v[166:169], v[52:55], 0
	s_waitcnt lgkmcnt(0)
	v_mfma_f32_16x16x32_bf16 v[146:149], v[150:153], v[154:157], v[146:149]
	ds_read_b128 v[154:157], v122 offset:38080
	v_mfma_f32_16x16x32_bf16 v[48:51], v[184:187], v[48:51], v[52:55]
	v_mfma_f32_16x16x32_bf16 v[44:47], v[150:153], v[44:47], v[48:51]
	s_waitcnt lgkmcnt(0)
	v_mfma_f32_16x16x32_bf16 v[56:59], v[154:157], v[56:59], v[146:149]
	v_mfma_f32_16x16x32_bf16 v[40:43], v[154:157], v[40:43], v[44:47]
	v_mfma_f32_16x16x32_bf16 v[56:59], v[162:165], v[0:3], v[56:59]
	v_lshl_add_u64 v[0:1], v[86:87], 0, s[54:55]
	v_mfma_f32_16x16x32_bf16 v[40:43], v[162:165], v[158:161], v[40:43]
	s_nop 5
	global_store_dwordx4 v[0:1], v[56:59], off
	v_lshl_add_u64 v[0:1], v[84:85], 0, s[54:55]
	global_store_dwordx4 v[0:1], v[40:43], off
	v_add_u32_e32 v0, v97, v96
	ds_read_b128 v[40:43], v0 offset:27648
	ds_read_b128 v[44:47], v123 offset:17408
	ds_read_b32 v0, v99
	s_waitcnt lgkmcnt(0)
	v_mul_f32_e32 v10, v10, v0
	v_mul_f32_e32 v11, v11, v0
	v_mul_f32_e32 v8, v8, v0
	v_mul_f32_e32 v9, v9, v0
	s_nop 1
	v_mfma_f32_16x16x32_bf16 v[8:11], v[40:43], v[44:47], v[8:11]
	ds_read_b128 v[44:47], v123 offset:18688
	ds_read_b32 v0, v100
	s_waitcnt lgkmcnt(0)
	v_mul_f32_e32 v14, v14, v0
	v_mul_f32_e32 v15, v15, v0
	v_mul_f32_e32 v12, v12, v0
	v_mul_f32_e32 v13, v13, v0
	s_nop 1
	v_mfma_f32_16x16x32_bf16 v[12:15], v[40:43], v[44:47], v[12:15]
	ds_read_b128 v[44:47], v123 offset:19968
	ds_read_b32 v0, v101
	s_waitcnt lgkmcnt(0)
	v_mul_f32_e32 v18, v18, v0
	v_mul_f32_e32 v19, v19, v0
	v_mul_f32_e32 v16, v16, v0
	v_mul_f32_e32 v17, v17, v0
	s_nop 1
	v_mfma_f32_16x16x32_bf16 v[16:19], v[40:43], v[44:47], v[16:19]
	ds_read_b128 v[44:47], v123 offset:21248
	ds_read_b32 v0, v102
	s_waitcnt lgkmcnt(0)
	v_mul_f32_e32 v22, v22, v0
	v_mul_f32_e32 v23, v23, v0
	v_mul_f32_e32 v20, v20, v0
	v_mul_f32_e32 v21, v21, v0
	s_nop 1
	v_mfma_f32_16x16x32_bf16 v[20:23], v[40:43], v[44:47], v[20:23]
	ds_read_b128 v[44:47], v123 offset:22528
	ds_read_b32 v0, v103
	s_waitcnt lgkmcnt(0)
	v_mul_f32_e32 v26, v26, v0
	v_mul_f32_e32 v27, v27, v0
	v_mul_f32_e32 v24, v24, v0
	v_mul_f32_e32 v25, v25, v0
	s_nop 1
	v_mfma_f32_16x16x32_bf16 v[24:27], v[40:43], v[44:47], v[24:27]
	ds_read_b128 v[44:47], v123 offset:23808
	ds_read_b32 v0, v104
	s_waitcnt lgkmcnt(0)
	v_mul_f32_e32 v30, v30, v0
	v_mul_f32_e32 v31, v31, v0
	v_mul_f32_e32 v28, v28, v0
	v_mul_f32_e32 v29, v29, v0
	s_nop 1
	v_mfma_f32_16x16x32_bf16 v[28:31], v[40:43], v[44:47], v[28:31]
	ds_read_b128 v[44:47], v123 offset:25088
	ds_read_b32 v0, v105
	s_waitcnt lgkmcnt(0)
	v_mul_f32_e32 v34, v34, v0
	v_mul_f32_e32 v35, v35, v0
	v_mul_f32_e32 v32, v32, v0
	v_mul_f32_e32 v33, v33, v0
	s_nop 1
	v_mfma_f32_16x16x32_bf16 v[32:35], v[40:43], v[44:47], v[32:35]
	ds_read_b128 v[44:47], v123 offset:26368
	ds_read_b32 v0, v106
	s_waitcnt lgkmcnt(0)
	s_waitcnt lgkmcnt(0)
	v_mul_f32_e32 v6, v6, v0
	v_mul_f32_e32 v7, v7, v0
	v_mul_f32_e32 v4, v4, v0
	v_mul_f32_e32 v5, v5, v0
	v_cvt_pk_bf16_f32 v0, v8, s0
	ds_write_b16 v124, v0 offset:37888
	v_cvt_pk_bf16_f32 v0, v9, s0
	ds_write_b16 v124, v0 offset:38160
	v_cvt_pk_bf16_f32 v0, v10, s0
	ds_write_b16 v125, v0 offset:37888
	v_cvt_pk_bf16_f32 v0, v11, s0
	ds_write_b16 v125, v0 offset:38160
	v_cvt_pk_bf16_f32 v0, v12, s0
	ds_write_b16 v124, v0 offset:37920
	v_cvt_pk_bf16_f32 v0, v13, s0
	ds_write_b16 v124, v0 offset:38192
	v_cvt_pk_bf16_f32 v0, v14, s0
	ds_write_b16 v125, v0 offset:37920
	v_cvt_pk_bf16_f32 v0, v15, s0
	ds_write_b16 v125, v0 offset:38192
	v_cvt_pk_bf16_f32 v0, v16, s0
	ds_write_b16 v124, v0 offset:37952
	v_cvt_pk_bf16_f32 v0, v17, s0
	ds_write_b16 v124, v0 offset:38224
	v_cvt_pk_bf16_f32 v0, v18, s0
	ds_write_b16 v125, v0 offset:37952
	v_cvt_pk_bf16_f32 v0, v19, s0
	ds_write_b16 v125, v0 offset:38224
	v_cvt_pk_bf16_f32 v0, v20, s0
	ds_write_b16 v124, v0 offset:37984
	v_cvt_pk_bf16_f32 v0, v21, s0
	ds_write_b16 v124, v0 offset:38256
	v_cvt_pk_bf16_f32 v0, v22, s0
	ds_write_b16 v125, v0 offset:37984
	v_cvt_pk_bf16_f32 v0, v23, s0
	ds_write_b16 v125, v0 offset:38256
	v_cvt_pk_bf16_f32 v0, v24, s0
	ds_write_b16 v124, v0 offset:38016
	v_cvt_pk_bf16_f32 v0, v25, s0
	ds_write_b16 v124, v0 offset:38288
	v_cvt_pk_bf16_f32 v0, v26, s0
	ds_write_b16 v125, v0 offset:38016
	v_cvt_pk_bf16_f32 v0, v27, s0
	ds_write_b16 v125, v0 offset:38288
	v_cvt_pk_bf16_f32 v0, v28, s0
	ds_write_b16 v124, v0 offset:38048
	v_cvt_pk_bf16_f32 v0, v29, s0
	ds_write_b16 v124, v0 offset:38320
	v_cvt_pk_bf16_f32 v0, v30, s0
	ds_write_b16 v125, v0 offset:38048
	v_cvt_pk_bf16_f32 v0, v31, s0
	v_mfma_f32_16x16x32_bf16 v[4:7], v[40:43], v[44:47], v[4:7]
	ds_write_b16 v125, v0 offset:38320
	v_cvt_pk_bf16_f32 v0, v32, s0
	ds_write_b16 v124, v0 offset:38080
	v_cvt_pk_bf16_f32 v0, v33, s0
	ds_write_b16 v124, v0 offset:38352
	v_cvt_pk_bf16_f32 v0, v34, s0
	ds_write_b16 v125, v0 offset:38080
	v_cvt_pk_bf16_f32 v0, v35, s0
	ds_write_b16 v125, v0 offset:38352
	v_cvt_pk_bf16_f32 v0, v4, s0
	ds_write_b16 v124, v0 offset:38112
	v_cvt_pk_bf16_f32 v0, v5, s0
	ds_write_b16 v124, v0 offset:38384
	v_cvt_pk_bf16_f32 v0, v6, s0
	ds_write_b16 v125, v0 offset:38112
	v_cvt_pk_bf16_f32 v0, v7, s0
	ds_write_b16 v125, v0 offset:38384
	s_waitcnt lgkmcnt(0)
	s_mov_b64 s[0:1], 0x10000
	v_lshl_add_u64 v[84:85], v[84:85], 0, s[0:1]
	v_lshl_add_u64 v[86:87], v[86:87], 0, s[0:1]
	s_mov_b64 s[0:1], 0x38000
	v_lshl_add_u64 v[88:89], v[88:89], 0, s[0:1]
	v_lshl_add_u64 v[90:91], v[90:91], 0, s[0:1]
	v_lshl_add_u64 v[92:93], v[92:93], 0, s[0:1]
	s_cbranch_scc1 .LBB0_247

.LBB0_284:
	s_cmp_eq_u32 s86, 0
	s_cbranch_scc1 .Lcg_nog_3
	s_waitcnt vmcnt(0)
	v_mul_f32_e32 v6, v6, v242
	v_mul_f32_e32 v7, v7, v242
	v_mul_f32_e32 v4, v4, v242
	v_mul_f32_e32 v5, v5, v242
	v_mul_f32_e32 v10, v10, v244
	v_mul_f32_e32 v11, v11, v244
	v_mul_f32_e32 v8, v8, v244
	v_mul_f32_e32 v9, v9, v244
	v_mul_f32_e32 v14, v14, v246
	v_mul_f32_e32 v15, v15, v246
	v_mul_f32_e32 v12, v12, v246
	v_mul_f32_e32 v13, v13, v246
	v_mul_f32_e32 v18, v18, v248
	v_mul_f32_e32 v19, v19, v248
	v_mul_f32_e32 v16, v16, v248
	v_mul_f32_e32 v17, v17, v248

.LBB0_359:
	v_lshl_add_u32 v144, s58, 8, v166
	v_or_b32_e32 v160, 16, v144
	v_or_b32_e32 v156, 32, v144
	v_or_b32_e32 v152, 48, v144
	v_ashrrev_i32_e32 v145, 31, v144
	v_ashrrev_i32_e32 v161, 31, v160
	v_ashrrev_i32_e32 v157, 31, v156
	v_ashrrev_i32_e32 v153, 31, v152
	v_lshl_add_u64 v[140:141], v[144:145], 2, s[18:19]
	v_lshl_add_u64 v[142:143], v[160:161], 2, s[18:19]
	v_lshl_add_u64 v[146:147], v[156:157], 2, s[18:19]
	v_lshl_add_u64 v[148:149], v[152:153], 2, s[18:19]
	global_load_dword v164, v[140:141], off
	global_load_dword v162, v[142:143], off
	global_load_dword v158, v[146:147], off
	global_load_dword v154, v[148:149], off
	global_load_dword v150, v[140:141], off offset:512
	s_nop 0
	global_load_dword v148, v[140:141], off offset:576
	global_load_dword v146, v[140:141], off offset:640
	global_load_dword v142, v[140:141], off offset:704
	v_lshl_or_b32 v140, s6, 8, v168
	s_movk_i32 s0, 0xe00
	v_ashrrev_i32_e32 v141, 31, v140
	v_cmp_gt_i32_e32 vcc, s0, v140
	s_waitcnt vmcnt(0)
	v_mul_f32_e32 v130, v130, v164
	v_mul_f32_e32 v131, v131, v164
	v_mul_f32_e32 v128, v128, v164
	v_mul_f32_e32 v129, v129, v164
	v_mul_f32_e32 v126, v126, v164
	v_mul_f32_e32 v127, v127, v164
	v_mul_f32_e32 v124, v124, v164
	v_mul_f32_e32 v125, v125, v164
	s_and_saveexec_b64 s[0:1], vcc
	s_cbranch_execz .LBB0_361
	v_mad_i64_i32 v[170:171], s[6:7], v144, s29, 0
	v_lshl_add_u64 v[170:171], v[170:171], 1, s[88:89]
	v_cvt_pk_bf16_f32 v187, v126, v127
	v_cvt_pk_bf16_f32 v186, v124, v125
	v_cvt_pk_bf16_f32 v185, v130, v131
	v_cvt_pk_bf16_f32 v184, v128, v129
	v_lshl_add_u64 v[170:171], v[140:141], 1, v[170:171]
	global_store_dwordx4 v[170:171], v[184:187], off

.LBB0_363:
	s_or_b64 exec, exec, s[6:7]
	s_nop 0
	v_or_b32_e32 v124, 0x80, v140
	s_movk_i32 s6, 0xe00
	v_cmp_gt_i32_e64 s[6:7], s6, v124
	s_and_saveexec_b64 s[24:25], s[6:7]
	s_cbranch_execz .LBB0_365
	v_mov_b32_e32 v165, v164
	v_mov_b32_e32 v124, v164
	v_mov_b32_e32 v125, v164
	v_mul_f32_e32 v114, v114, v124
	v_mul_f32_e32 v115, v115, v125
	v_mul_f32_e32 v112, v112, v164
	v_mul_f32_e32 v113, v113, v165
	v_mul_f32_e32 v116, v116, v164
	v_mul_f32_e32 v117, v117, v165
	v_cvt_pk_bf16_f32 v115, v114, v115
	v_cvt_pk_bf16_f32 v114, v112, v113
	v_cvt_pk_bf16_f32 v112, v116, v117
	v_mad_i64_i32 v[116:117], s[26:27], v144, s29, 0
	v_mul_f32_e32 v118, v118, v124
	v_mul_f32_e32 v119, v119, v125
	v_lshl_add_u64 v[116:117], v[116:117], 1, s[88:89]
	v_cvt_pk_bf16_f32 v113, v118, v119
	v_lshl_add_u64 v[116:117], v[140:141], 1, v[116:117]
	global_store_dwordx4 v[116:117], v[112:115], off offset:256
.LBB0_365:
	s_or_b64 exec, exec, s[24:25]
	s_nop 0
	v_mul_f32_e32 v114, v122, v162
	v_mul_f32_e32 v115, v123, v162
	v_mul_f32_e32 v112, v120, v162
	v_mul_f32_e32 v113, v121, v162
	v_mul_f32_e32 v110, v110, v162
	v_mul_f32_e32 v111, v111, v162
	v_mul_f32_e32 v108, v108, v162
	v_mul_f32_e32 v109, v109, v162
	s_and_saveexec_b64 s[24:25], vcc
	s_cbranch_execz .LBB0_393
	v_mad_i64_i32 v[120:121], s[26:27], v160, s29, 0
	v_lshl_add_u64 v[120:121], v[120:121], 1, s[88:89]
	v_cvt_pk_bf16_f32 v119, v110, v111
	v_cvt_pk_bf16_f32 v118, v108, v109
	v_cvt_pk_bf16_f32 v117, v114, v115
	v_cvt_pk_bf16_f32 v116, v112, v113
	v_lshl_add_u64 v[120:121], v[140:141], 1, v[120:121]
	global_store_dwordx4 v[120:121], v[116:119], off
	s_or_b64 exec, exec, s[24:25]
	s_and_saveexec_b64 s[24:25], s[0:1]
	s_cbranch_execnz .LBB0_394

.LBB0_368:
	v_mov_b32_e32 v163, v162
	v_mov_b32_e32 v108, v162
	v_mov_b32_e32 v109, v162
	v_mul_f32_e32 v98, v98, v108
	v_mul_f32_e32 v99, v99, v109
	v_mul_f32_e32 v96, v96, v162
	v_mul_f32_e32 v97, v97, v163
	v_mul_f32_e32 v100, v100, v162
	v_mul_f32_e32 v101, v101, v163
	v_cvt_pk_bf16_f32 v99, v98, v99
	v_cvt_pk_bf16_f32 v98, v96, v97
	v_cvt_pk_bf16_f32 v96, v100, v101
	v_mad_i64_i32 v[100:101], s[26:27], v160, s29, 0
	v_mul_f32_e32 v102, v102, v108
	v_mul_f32_e32 v103, v103, v109
	v_lshl_add_u64 v[100:101], v[100:101], 1, s[88:89]
	v_cvt_pk_bf16_f32 v97, v102, v103
	v_lshl_add_u64 v[100:101], v[140:141], 1, v[100:101]
	global_store_dwordx4 v[100:101], v[96:99], off offset:256
.LBB0_369:
	s_or_b64 exec, exec, s[24:25]
	s_nop 0
	v_mul_f32_e32 v98, v106, v158
	v_mul_f32_e32 v99, v107, v158
	v_mul_f32_e32 v96, v104, v158
	v_mul_f32_e32 v97, v105, v158
	v_mul_f32_e32 v94, v94, v158
	v_mul_f32_e32 v95, v95, v158
	v_mul_f32_e32 v92, v92, v158
	v_mul_f32_e32 v93, v93, v158
	s_and_saveexec_b64 s[24:25], vcc
	s_cbranch_execz .LBB0_395
	v_mad_i64_i32 v[104:105], s[26:27], v156, s29, 0
	v_lshl_add_u64 v[104:105], v[104:105], 1, s[88:89]
	v_cvt_pk_bf16_f32 v103, v94, v95
	v_cvt_pk_bf16_f32 v102, v92, v93
	v_cvt_pk_bf16_f32 v101, v98, v99
	v_cvt_pk_bf16_f32 v100, v96, v97
	v_lshl_add_u64 v[104:105], v[140:141], 1, v[104:105]
	global_store_dwordx4 v[104:105], v[100:103], off
	s_or_b64 exec, exec, s[24:25]
	s_and_saveexec_b64 s[24:25], s[0:1]
	s_cbranch_execnz .LBB0_396

.LBB0_372:
	v_mov_b32_e32 v159, v158
	v_mov_b32_e32 v92, v158
	v_mov_b32_e32 v93, v158
	v_mul_f32_e32 v82, v82, v92
	v_mul_f32_e32 v83, v83, v93
	v_mul_f32_e32 v80, v80, v158
	v_mul_f32_e32 v81, v81, v159
	v_mul_f32_e32 v84, v84, v158
	v_mul_f32_e32 v85, v85, v159
	v_cvt_pk_bf16_f32 v83, v82, v83
	v_cvt_pk_bf16_f32 v82, v80, v81
	v_cvt_pk_bf16_f32 v80, v84, v85
	v_mad_i64_i32 v[84:85], s[26:27], v156, s29, 0
	v_mul_f32_e32 v86, v86, v92
	v_mul_f32_e32 v87, v87, v93
	v_lshl_add_u64 v[84:85], v[84:85], 1, s[88:89]
	v_cvt_pk_bf16_f32 v81, v86, v87
	v_lshl_add_u64 v[84:85], v[140:141], 1, v[84:85]
	global_store_dwordx4 v[84:85], v[80:83], off offset:256
.LBB0_373:
	s_or_b64 exec, exec, s[24:25]
	s_nop 0
	v_mul_f32_e32 v82, v90, v154
	v_mul_f32_e32 v83, v91, v154
	v_mul_f32_e32 v80, v88, v154
	v_mul_f32_e32 v81, v89, v154
	v_mul_f32_e32 v78, v78, v154
	v_mul_f32_e32 v79, v79, v154
	v_mul_f32_e32 v76, v76, v154
	v_mul_f32_e32 v77, v77, v154
	s_and_saveexec_b64 s[24:25], vcc
	s_cbranch_execz .LBB0_397
	v_mad_i64_i32 v[88:89], s[26:27], v152, s29, 0
	v_lshl_add_u64 v[88:89], v[88:89], 1, s[88:89]
	v_cvt_pk_bf16_f32 v87, v78, v79
	v_cvt_pk_bf16_f32 v86, v76, v77
	v_cvt_pk_bf16_f32 v85, v82, v83
	v_cvt_pk_bf16_f32 v84, v80, v81
	v_lshl_add_u64 v[88:89], v[140:141], 1, v[88:89]
	global_store_dwordx4 v[88:89], v[84:87], off
	s_or_b64 exec, exec, s[24:25]
	s_and_saveexec_b64 s[24:25], s[0:1]
	s_cbranch_execnz .LBB0_398

.LBB0_376:
	v_mov_b32_e32 v155, v154
	v_mov_b32_e32 v76, v154
	v_mov_b32_e32 v77, v154
	v_mul_f32_e32 v70, v70, v76
	v_mul_f32_e32 v71, v71, v77
	v_mul_f32_e32 v68, v68, v154
	v_mul_f32_e32 v69, v69, v155
	v_mul_f32_e32 v72, v72, v154
	v_mul_f32_e32 v73, v73, v155
	v_cvt_pk_bf16_f32 v71, v70, v71
	v_cvt_pk_bf16_f32 v70, v68, v69
	v_cvt_pk_bf16_f32 v68, v72, v73
	v_mad_i64_i32 v[72:73], s[26:27], v152, s29, 0
	v_mul_f32_e32 v74, v74, v76
	v_mul_f32_e32 v75, v75, v77
	v_lshl_add_u64 v[72:73], v[72:73], 1, s[88:89]
	v_cvt_pk_bf16_f32 v69, v74, v75
	v_lshl_add_u64 v[72:73], v[140:141], 1, v[72:73]
	global_store_dwordx4 v[72:73], v[68:71], off offset:256
.LBB0_377:
	s_or_b64 exec, exec, s[24:25]
	s_nop 0
	v_add_u32_e32 v68, 0x80, v144
	v_ashrrev_i32_e32 v69, 31, v68
	v_mul_f32_e32 v66, v66, v150
	v_mul_f32_e32 v67, v67, v150
	v_mul_f32_e32 v64, v64, v150
	v_mul_f32_e32 v65, v65, v150
	v_mul_f32_e32 v62, v62, v150
	v_mul_f32_e32 v63, v63, v150
	v_mul_f32_e32 v60, v60, v150
	v_mul_f32_e32 v61, v61, v150
	s_and_saveexec_b64 s[24:25], vcc
	s_cbranch_execz .LBB0_399
	v_mad_i64_i32 v[74:75], s[26:27], v68, s29, 0
	v_lshl_add_u64 v[74:75], v[74:75], 1, s[88:89]
	v_cvt_pk_bf16_f32 v73, v62, v63
	v_cvt_pk_bf16_f32 v72, v60, v61
	v_cvt_pk_bf16_f32 v71, v66, v67
	v_cvt_pk_bf16_f32 v70, v64, v65
	v_lshl_add_u64 v[74:75], v[140:141], 1, v[74:75]
	global_store_dwordx4 v[74:75], v[70:73], off
	s_or_b64 exec, exec, s[24:25]
	s_and_saveexec_b64 s[24:25], s[0:1]
	s_cbranch_execnz .LBB0_400

.LBB0_380:
	v_mov_b32_e32 v151, v150
	v_mov_b32_e32 v60, v150
	v_mov_b32_e32 v61, v150
	v_mul_f32_e32 v54, v54, v60
	v_mul_f32_e32 v55, v55, v61
	v_mul_f32_e32 v52, v52, v150
	v_mul_f32_e32 v53, v53, v151
	v_mul_f32_e32 v56, v56, v150
	v_mul_f32_e32 v57, v57, v151
	v_cvt_pk_bf16_f32 v55, v54, v55
	v_cvt_pk_bf16_f32 v54, v52, v53
	v_cvt_pk_bf16_f32 v52, v56, v57
	v_mad_i64_i32 v[56:57], s[26:27], v68, s29, 0
	v_mul_f32_e32 v58, v58, v60
	v_mul_f32_e32 v59, v59, v61
	v_lshl_add_u64 v[56:57], v[56:57], 1, s[88:89]
	v_cvt_pk_bf16_f32 v53, v58, v59
	v_lshl_add_u64 v[56:57], v[140:141], 1, v[56:57]
	global_store_dwordx4 v[56:57], v[52:55], off offset:256
.LBB0_381:
	s_or_b64 exec, exec, s[24:25]
	s_nop 0
	v_add_u32_e32 v52, 0x90, v144
	v_ashrrev_i32_e32 v53, 31, v52
	v_mul_f32_e32 v50, v50, v148
	v_mul_f32_e32 v51, v51, v148
	v_mul_f32_e32 v48, v48, v148
	v_mul_f32_e32 v49, v49, v148
	v_mul_f32_e32 v46, v46, v148
	v_mul_f32_e32 v47, v47, v148
	v_mul_f32_e32 v44, v44, v148
	v_mul_f32_e32 v45, v45, v148
	s_and_saveexec_b64 s[24:25], vcc
	s_cbranch_execz .LBB0_401
	v_mad_i64_i32 v[58:59], s[26:27], v52, s29, 0
	v_lshl_add_u64 v[58:59], v[58:59], 1, s[88:89]
	v_cvt_pk_bf16_f32 v57, v46, v47
	v_cvt_pk_bf16_f32 v56, v44, v45
	v_cvt_pk_bf16_f32 v55, v50, v51
	v_cvt_pk_bf16_f32 v54, v48, v49
	v_lshl_add_u64 v[58:59], v[140:141], 1, v[58:59]
	global_store_dwordx4 v[58:59], v[54:57], off
	s_or_b64 exec, exec, s[24:25]
	s_and_saveexec_b64 s[24:25], s[0:1]
	s_cbranch_execnz .LBB0_402

.LBB0_384:
	v_mov_b32_e32 v149, v148
	v_mov_b32_e32 v44, v148
	v_mov_b32_e32 v45, v148
	v_mul_f32_e32 v38, v38, v44
	v_mul_f32_e32 v39, v39, v45
	v_mul_f32_e32 v36, v36, v148
	v_mul_f32_e32 v37, v37, v149
	v_mul_f32_e32 v40, v40, v148
	v_mul_f32_e32 v41, v41, v149
	v_cvt_pk_bf16_f32 v39, v38, v39
	v_cvt_pk_bf16_f32 v38, v36, v37
	v_cvt_pk_bf16_f32 v36, v40, v41
	v_mad_i64_i32 v[40:41], s[26:27], v52, s29, 0
	v_mul_f32_e32 v42, v42, v44
	v_mul_f32_e32 v43, v43, v45
	v_lshl_add_u64 v[40:41], v[40:41], 1, s[88:89]
	v_cvt_pk_bf16_f32 v37, v42, v43
	v_lshl_add_u64 v[40:41], v[140:141], 1, v[40:41]
	global_store_dwordx4 v[40:41], v[36:39], off offset:256
.LBB0_385:
	s_or_b64 exec, exec, s[24:25]
	s_nop 0
	v_add_u32_e32 v36, 0xa0, v144
	v_ashrrev_i32_e32 v37, 31, v36
	v_mul_f32_e32 v34, v34, v146
	v_mul_f32_e32 v35, v35, v146
	v_mul_f32_e32 v32, v32, v146
	v_mul_f32_e32 v33, v33, v146
	v_mul_f32_e32 v30, v30, v146
	v_mul_f32_e32 v31, v31, v146
	v_mul_f32_e32 v28, v28, v146
	v_mul_f32_e32 v29, v29, v146
	s_and_saveexec_b64 s[24:25], vcc
	s_cbranch_execz .LBB0_403
	v_mad_i64_i32 v[42:43], s[26:27], v36, s29, 0
	v_lshl_add_u64 v[42:43], v[42:43], 1, s[88:89]
	v_cvt_pk_bf16_f32 v41, v30, v31
	v_cvt_pk_bf16_f32 v40, v28, v29
	v_cvt_pk_bf16_f32 v39, v34, v35
	v_cvt_pk_bf16_f32 v38, v32, v33
	v_lshl_add_u64 v[42:43], v[140:141], 1, v[42:43]
	global_store_dwordx4 v[42:43], v[38:41], off
	s_or_b64 exec, exec, s[24:25]
	s_and_saveexec_b64 s[24:25], s[0:1]
	s_cbranch_execnz .LBB0_404

.LBB0_388:
	v_mov_b32_e32 v147, v146
	v_mov_b32_e32 v28, v146
	v_mov_b32_e32 v29, v146
	v_mul_f32_e32 v22, v22, v28
	v_mul_f32_e32 v23, v23, v29
	v_mul_f32_e32 v20, v20, v146
	v_mul_f32_e32 v21, v21, v147
	v_mul_f32_e32 v24, v24, v146
	v_mul_f32_e32 v25, v25, v147
	v_cvt_pk_bf16_f32 v23, v22, v23
	v_cvt_pk_bf16_f32 v22, v20, v21
	v_cvt_pk_bf16_f32 v20, v24, v25
	v_mad_i64_i32 v[24:25], s[26:27], v36, s29, 0
	v_mul_f32_e32 v26, v26, v28
	v_mul_f32_e32 v27, v27, v29
	v_lshl_add_u64 v[24:25], v[24:25], 1, s[88:89]
	v_cvt_pk_bf16_f32 v21, v26, v27
	v_lshl_add_u64 v[24:25], v[140:141], 1, v[24:25]
	global_store_dwordx4 v[24:25], v[20:23], off offset:256
.LBB0_389:
	s_or_b64 exec, exec, s[24:25]
	s_nop 0
	v_add_u32_e32 v20, 0xb0, v144
	v_ashrrev_i32_e32 v21, 31, v20
	v_mul_f32_e32 v18, v18, v142
	v_mul_f32_e32 v19, v19, v142
	v_mul_f32_e32 v16, v16, v142
	v_mul_f32_e32 v17, v17, v142
	v_mul_f32_e32 v14, v14, v142
	v_mul_f32_e32 v15, v15, v142
	v_mul_f32_e32 v12, v12, v142
	v_mul_f32_e32 v13, v13, v142
	s_and_saveexec_b64 s[24:25], vcc
	s_cbranch_execz .LBB0_405
	v_mad_i64_i32 v[26:27], s[26:27], v20, s29, 0
	v_lshl_add_u64 v[26:27], v[26:27], 1, s[88:89]
	v_cvt_pk_bf16_f32 v25, v14, v15
	v_cvt_pk_bf16_f32 v24, v12, v13
	v_cvt_pk_bf16_f32 v23, v18, v19
	v_cvt_pk_bf16_f32 v22, v16, v17
	v_lshl_add_u64 v[26:27], v[140:141], 1, v[26:27]
	global_store_dwordx4 v[26:27], v[22:25], off
	s_or_b64 exec, exec, s[24:25]
	s_and_saveexec_b64 s[24:25], s[0:1]
	s_cbranch_execnz .LBB0_406

.LBB0_392:
	v_mov_b32_e32 v143, v142
	v_mov_b32_e32 v12, v142
	v_mov_b32_e32 v13, v142
	v_mul_f32_e32 v6, v6, v12
	v_mul_f32_e32 v7, v7, v13
	v_mul_f32_e32 v4, v4, v142
	v_mul_f32_e32 v5, v5, v143
	v_mul_f32_e32 v8, v8, v142
	v_mul_f32_e32 v9, v9, v143
	v_cvt_pk_bf16_f32 v7, v6, v7
	v_cvt_pk_bf16_f32 v6, v4, v5
	v_cvt_pk_bf16_f32 v4, v8, v9
	v_mad_i64_i32 v[8:9], s[6:7], v20, s29, 0
	v_mul_f32_e32 v10, v10, v12
	v_mul_f32_e32 v11, v11, v13
	v_lshl_add_u64 v[8:9], v[8:9], 1, s[88:89]
	v_cvt_pk_bf16_f32 v5, v10, v11
	v_lshl_add_u64 v[8:9], v[140:141], 1, v[8:9]
	global_store_dwordx4 v[8:9], v[4:7], off offset:256
	s_or_b64 exec, exec, s[0:1]
	s_andn2_b64 vcc, exec, s[4:5]
	s_mov_b64 s[0:1], -1
	s_cbranch_vccnz .LBB0_352
	s_branch .LBB0_408

.LBB0_490:
	v_lshl_add_u32 v202, s45, 8, v175
	v_lshl_or_b32 v196, s20, 8, v224
	v_ashrrev_i32_e32 v203, 31, v202
	v_ashrrev_i32_e32 v197, 31, v196
	v_lshlrev_b64 v[132:133], 12, v[202:203]
	v_lshl_add_u64 v[198:199], s[16:17], 0, v[132:133]
	v_lshlrev_b64 v[132:133], 2, v[196:197]
	v_or_b32_e32 v204, 16, v202
	v_lshl_add_u64 v[134:135], v[198:199], 0, v[132:133]
	v_ashrrev_i32_e32 v205, 31, v204
	global_load_dwordx4 v[230:233], v[134:135], off offset:16
	global_load_dwordx4 v[234:237], v[134:135], off
	global_load_dwordx4 v[164:167], v[134:135], off offset:528
	global_load_dwordx4 v[168:171], v[134:135], off offset:512
	v_lshlrev_b64 v[134:135], 12, v[204:205]
	v_lshl_add_u64 v[134:135], s[16:17], 0, v[134:135]
	v_or_b32_e32 v200, 32, v202
	v_lshl_add_u64 v[134:135], v[134:135], 0, v[132:133]
	v_ashrrev_i32_e32 v201, 31, v200
	global_load_dwordx4 v[156:159], v[134:135], off offset:16
	global_load_dwordx4 v[160:163], v[134:135], off
	global_load_dwordx4 v[148:151], v[134:135], off offset:528
	global_load_dwordx4 v[152:155], v[134:135], off offset:512
	v_lshlrev_b64 v[134:135], 12, v[200:201]
	v_lshl_add_u64 v[134:135], s[16:17], 0, v[134:135]
	v_lshl_add_u64 v[136:137], v[134:135], 0, v[132:133]
	global_load_dwordx4 v[140:143], v[136:137], off offset:16
	global_load_dwordx4 v[144:147], v[136:137], off
	global_load_dwordx4 v[132:135], v[136:137], off offset:528
	s_nop 0
	global_load_dwordx4 v[136:139], v[136:137], off offset:512
	v_lshlrev_b64 v[206:207], 10, v[202:203]
	v_lshl_add_u64 v[206:207], v[206:207], 0, v[196:197]
	v_mov_b32_e32 v189, v188
	v_cndmask_b32_e64 v216, 0, 1, s[18:19]
	v_lshl_add_u64 v[208:209], v[206:207], 2, s[22:23]
	v_cmp_ne_u32_e64 s[8:9], 1, v216
	s_andn2_b64 vcc, exec, s[18:19]
	s_waitcnt vmcnt(0)
	v_fma_f32 v126, v188, v126, v232
	v_fma_f32 v127, v189, v127, v233
	v_fma_f32 v130, v188, v130, v236
	v_fma_f32 v131, v189, v131, v237
	v_fma_f32 v128, v190, v128, v234
	v_fma_f32 v129, v191, v129, v235
	v_fma_f32 v124, v190, v124, v230
	v_fma_f32 v125, v191, v125, v231
	global_store_dwordx4 v[208:209], v[128:131], off nt
	global_store_dwordx4 v[208:209], v[124:127], off offset:16 nt
	s_cbranch_vccnz .LBB0_492
	v_cvt_pk_bf16_f32 v230, v128, v129
	v_cvt_pk_bf16_f32 v231, v130, v131
	v_cvt_pk_bf16_f32 v232, v124, v125
	v_cvt_pk_bf16_f32 v233, v126, v127
	v_lshl_add_u64 v[216:217], v[206:207], 1, s[84:85]
	global_store_dwordx4 v[216:217], v[230:233], off
.LBB0_492:
	v_fma_f32 v122, v188, v122, v170
	v_fma_f32 v123, v189, v123, v171
	v_fma_f32 v120, v190, v120, v168
	v_fma_f32 v121, v191, v121, v169
	v_fma_f32 v118, v188, v118, v166
	v_fma_f32 v119, v189, v119, v167
	v_fma_f32 v116, v190, v116, v164
	v_fma_f32 v117, v191, v117, v165
	s_and_b64 vcc, exec, s[8:9]
	global_store_dwordx4 v[208:209], v[120:123], off offset:512 nt
	global_store_dwordx4 v[208:209], v[116:119], off offset:528 nt
	s_cbranch_vccnz .LBB0_494
	v_lshlrev_b64 v[168:169], 1, v[206:207]
	v_or_b32_e32 v168, 0x100, v168
	v_cvt_pk_bf16_f32 v164, v120, v121
	v_cvt_pk_bf16_f32 v165, v122, v123
	v_cvt_pk_bf16_f32 v166, v116, v117
	v_cvt_pk_bf16_f32 v167, v118, v119
	v_lshl_add_u64 v[168:169], s[84:85], 0, v[168:169]
	global_store_dwordx4 v[168:169], v[164:167], off

.LBB0_496:
	s_or_b64 exec, exec, s[24:25]
	v_or_b32_e32 v164, 48, v202
	v_ashrrev_i32_e32 v165, 31, v164
	s_waitcnt lgkmcnt(0)
	v_lshlrev_b64 v[116:117], 12, v[164:165]
	v_lshl_add_u64 v[116:117], s[16:17], 0, v[116:117]
	v_lshl_add_u64 v[120:121], v[196:197], 2, v[116:117]
	global_load_dwordx4 v[124:127], v[120:121], off offset:16
	global_load_dwordx4 v[128:131], v[120:121], off
	global_load_dwordx4 v[116:119], v[120:121], off offset:528
	s_nop 0
	global_load_dwordx4 v[120:123], v[120:121], off offset:512
	v_lshlrev_b64 v[166:167], 10, v[204:205]
	v_lshl_add_u64 v[166:167], v[166:167], 0, v[196:197]
	v_mov_b32_e32 v189, v188
	v_fma_f32 v114, v188, v114, v162
	v_fma_f32 v115, v189, v115, v163
	v_fma_f32 v112, v190, v112, v160
	v_fma_f32 v113, v191, v113, v161
	v_fma_f32 v110, v188, v110, v158
	v_fma_f32 v111, v189, v111, v159
	v_fma_f32 v108, v190, v108, v156
	v_fma_f32 v109, v191, v109, v157
	v_lshl_add_u64 v[156:157], v[166:167], 2, s[22:23]
	s_and_b64 vcc, exec, s[8:9]
	global_store_dwordx4 v[156:157], v[112:115], off nt
	global_store_dwordx4 v[156:157], v[108:111], off offset:16 nt
	s_cbranch_vccnz .LBB0_498
	v_cvt_pk_bf16_f32 v158, v112, v113
	v_cvt_pk_bf16_f32 v159, v114, v115
	v_cvt_pk_bf16_f32 v160, v108, v109
	v_cvt_pk_bf16_f32 v161, v110, v111
	v_lshl_add_u64 v[162:163], v[166:167], 1, s[84:85]
	global_store_dwordx4 v[162:163], v[158:161], off
.LBB0_498:
	v_fma_f32 v106, v188, v106, v154
	v_fma_f32 v107, v189, v107, v155
	v_fma_f32 v104, v190, v104, v152
	v_fma_f32 v105, v191, v105, v153
	v_fma_f32 v102, v188, v102, v150
	v_fma_f32 v103, v189, v103, v151
	v_fma_f32 v100, v190, v100, v148
	v_fma_f32 v101, v191, v101, v149
	s_and_b64 vcc, exec, s[8:9]
	global_store_dwordx4 v[156:157], v[104:107], off offset:512 nt
	global_store_dwordx4 v[156:157], v[100:103], off offset:528 nt
	s_cbranch_vccnz .LBB0_500
	v_lshlrev_b64 v[152:153], 1, v[166:167]
	v_or_b32_e32 v152, 0x100, v152
	v_cvt_pk_bf16_f32 v148, v104, v105
	v_cvt_pk_bf16_f32 v149, v106, v107
	v_cvt_pk_bf16_f32 v150, v100, v101
	v_cvt_pk_bf16_f32 v151, v102, v103
	v_lshl_add_u64 v[152:153], s[84:85], 0, v[152:153]
	global_store_dwordx4 v[152:153], v[148:151], off

.LBB0_502:
	s_or_b64 exec, exec, s[24:25]
	v_add_u32_e32 v148, 0x80, v202
	v_ashrrev_i32_e32 v149, 31, v148
	s_waitcnt lgkmcnt(0)
	v_lshlrev_b64 v[100:101], 12, v[148:149]
	v_lshl_add_u64 v[100:101], s[16:17], 0, v[100:101]
	v_lshl_add_u64 v[104:105], v[196:197], 2, v[100:101]
	global_load_dwordx4 v[108:111], v[104:105], off offset:16
	global_load_dwordx4 v[112:115], v[104:105], off
	global_load_dwordx4 v[100:103], v[104:105], off offset:528
	s_nop 0
	global_load_dwordx4 v[104:107], v[104:105], off offset:512
	v_lshlrev_b64 v[150:151], 10, v[200:201]
	v_lshl_add_u64 v[150:151], v[150:151], 0, v[196:197]
	v_mov_b32_e32 v189, v188
	v_fma_f32 v98, v188, v98, v146
	v_fma_f32 v99, v189, v99, v147
	v_fma_f32 v96, v190, v96, v144
	v_fma_f32 v97, v191, v97, v145
	v_fma_f32 v94, v188, v94, v142
	v_fma_f32 v95, v189, v95, v143
	v_fma_f32 v92, v190, v92, v140
	v_fma_f32 v93, v191, v93, v141
	v_lshl_add_u64 v[140:141], v[150:151], 2, s[22:23]
	s_and_b64 vcc, exec, s[8:9]
	global_store_dwordx4 v[140:141], v[96:99], off nt
	global_store_dwordx4 v[140:141], v[92:95], off offset:16 nt
	s_cbranch_vccnz .LBB0_504
	v_cvt_pk_bf16_f32 v142, v96, v97
	v_cvt_pk_bf16_f32 v143, v98, v99
	v_cvt_pk_bf16_f32 v144, v92, v93
	v_cvt_pk_bf16_f32 v145, v94, v95
	v_lshl_add_u64 v[146:147], v[150:151], 1, s[84:85]
	global_store_dwordx4 v[146:147], v[142:145], off
.LBB0_504:
	v_fma_f32 v90, v188, v90, v138
	v_fma_f32 v91, v189, v91, v139
	v_fma_f32 v88, v190, v88, v136
	v_fma_f32 v89, v191, v89, v137
	v_fma_f32 v86, v188, v86, v134
	v_fma_f32 v87, v189, v87, v135
	v_fma_f32 v84, v190, v84, v132
	v_fma_f32 v85, v191, v85, v133
	s_and_b64 vcc, exec, s[8:9]
	global_store_dwordx4 v[140:141], v[88:91], off offset:512 nt
	global_store_dwordx4 v[140:141], v[84:87], off offset:528 nt
	s_cbranch_vccnz .LBB0_506
	v_lshlrev_b64 v[136:137], 1, v[150:151]
	v_or_b32_e32 v136, 0x100, v136
	v_cvt_pk_bf16_f32 v132, v88, v89
	v_cvt_pk_bf16_f32 v133, v90, v91
	v_cvt_pk_bf16_f32 v134, v84, v85
	v_cvt_pk_bf16_f32 v135, v86, v87
	v_lshl_add_u64 v[136:137], s[84:85], 0, v[136:137]
	global_store_dwordx4 v[136:137], v[132:135], off

.LBB0_508:
	s_or_b64 exec, exec, s[24:25]
	s_waitcnt lgkmcnt(0)
	v_lshl_add_u64 v[84:85], v[196:197], 2, v[198:199]
	s_mov_b64 s[24:25], 0x90000
	v_lshl_add_u64 v[88:89], v[84:85], 0, s[24:25]
	v_add_co_u32_e32 v84, vcc, 0x90000, v84
	v_lshlrev_b64 v[132:133], 10, v[164:165]
	s_nop 0
	v_addc_co_u32_e32 v85, vcc, 0, v85, vcc
	global_load_dwordx4 v[96:99], v[84:85], off
	s_nop 0
	global_load_dwordx4 v[84:87], v[88:89], off offset:528
	global_load_dwordx4 v[92:95], v[88:89], off offset:16
	s_nop 0
	global_load_dwordx4 v[88:91], v[88:89], off offset:512
	v_lshl_add_u64 v[132:133], v[132:133], 0, v[196:197]
	v_mov_b32_e32 v189, v188
	s_waitcnt vmcnt(18)
	v_fma_f32 v82, v188, v82, v130
	v_fma_f32 v83, v189, v83, v131
	v_fma_f32 v80, v190, v80, v128
	v_fma_f32 v81, v191, v81, v129
	v_fma_f32 v78, v188, v78, v126
	v_fma_f32 v79, v189, v79, v127
	v_fma_f32 v76, v190, v76, v124
	v_fma_f32 v77, v191, v77, v125
	v_lshl_add_u64 v[124:125], v[132:133], 2, s[22:23]
	s_and_b64 vcc, exec, s[8:9]
	global_store_dwordx4 v[124:125], v[80:83], off nt
	global_store_dwordx4 v[124:125], v[76:79], off offset:16 nt
	s_cbranch_vccnz .LBB0_510
	v_cvt_pk_bf16_f32 v126, v80, v81
	v_cvt_pk_bf16_f32 v127, v82, v83
	v_cvt_pk_bf16_f32 v128, v76, v77
	v_cvt_pk_bf16_f32 v129, v78, v79
	v_lshl_add_u64 v[130:131], v[132:133], 1, s[84:85]
	global_store_dwordx4 v[130:131], v[126:129], off
.LBB0_510:
	s_waitcnt vmcnt(18)
	v_fma_f32 v74, v188, v74, v122
	v_fma_f32 v75, v189, v75, v123
	v_fma_f32 v72, v190, v72, v120
	v_fma_f32 v73, v191, v73, v121
	v_fma_f32 v70, v188, v70, v118
	v_fma_f32 v71, v189, v71, v119
	v_fma_f32 v68, v190, v68, v116
	v_fma_f32 v69, v191, v69, v117
	s_and_b64 vcc, exec, s[8:9]
	global_store_dwordx4 v[124:125], v[72:75], off offset:512 nt
	global_store_dwordx4 v[124:125], v[68:71], off offset:528 nt
	s_cbranch_vccnz .LBB0_512
	v_lshlrev_b64 v[120:121], 1, v[132:133]
	v_or_b32_e32 v120, 0x100, v120
	v_cvt_pk_bf16_f32 v116, v72, v73
	v_cvt_pk_bf16_f32 v117, v74, v75
	v_cvt_pk_bf16_f32 v118, v68, v69
	v_cvt_pk_bf16_f32 v119, v70, v71
	v_lshl_add_u64 v[120:121], s[84:85], 0, v[120:121]
	global_store_dwordx4 v[120:121], v[116:119], off

.LBB0_514:
	s_or_b64 exec, exec, s[24:25]
	v_or_b32_e32 v116, 32, v148
	v_ashrrev_i32_e32 v117, 31, v116
	s_waitcnt lgkmcnt(0)
	v_lshlrev_b64 v[68:69], 12, v[116:117]
	v_lshl_add_u64 v[68:69], s[16:17], 0, v[68:69]
	v_lshl_add_u64 v[72:73], v[196:197], 2, v[68:69]
	global_load_dwordx4 v[76:79], v[72:73], off offset:16
	global_load_dwordx4 v[80:83], v[72:73], off
	global_load_dwordx4 v[68:71], v[72:73], off offset:528
	s_nop 0
	global_load_dwordx4 v[72:75], v[72:73], off offset:512
	v_lshlrev_b64 v[118:119], 10, v[148:149]
	v_lshl_add_u64 v[118:119], v[118:119], 0, v[196:197]
	v_mov_b32_e32 v189, v188
	s_waitcnt vmcnt(18)
	v_fma_f32 v66, v188, v66, v114
	v_fma_f32 v67, v189, v67, v115
	v_fma_f32 v64, v190, v64, v112
	v_fma_f32 v65, v191, v65, v113
	v_fma_f32 v62, v188, v62, v110
	v_fma_f32 v63, v189, v63, v111
	v_fma_f32 v60, v190, v60, v108
	v_fma_f32 v61, v191, v61, v109
	v_lshl_add_u64 v[108:109], v[118:119], 2, s[22:23]
	s_and_b64 vcc, exec, s[8:9]
	global_store_dwordx4 v[108:109], v[64:67], off nt
	global_store_dwordx4 v[108:109], v[60:63], off offset:16 nt
	s_cbranch_vccnz .LBB0_516
	v_cvt_pk_bf16_f32 v110, v64, v65
	v_cvt_pk_bf16_f32 v111, v66, v67
	v_cvt_pk_bf16_f32 v112, v60, v61
	v_cvt_pk_bf16_f32 v113, v62, v63
	v_lshl_add_u64 v[114:115], v[118:119], 1, s[84:85]
	global_store_dwordx4 v[114:115], v[110:113], off
.LBB0_516:
	s_waitcnt vmcnt(18)
	v_fma_f32 v58, v188, v58, v106
	v_fma_f32 v59, v189, v59, v107
	v_fma_f32 v56, v190, v56, v104
	v_fma_f32 v57, v191, v57, v105
	v_fma_f32 v54, v188, v54, v102
	v_fma_f32 v55, v189, v55, v103
	v_fma_f32 v52, v190, v52, v100
	v_fma_f32 v53, v191, v53, v101
	s_and_b64 vcc, exec, s[8:9]
	global_store_dwordx4 v[108:109], v[56:59], off offset:512 nt
	global_store_dwordx4 v[108:109], v[52:55], off offset:528 nt
	s_cbranch_vccnz .LBB0_518
	v_lshlrev_b64 v[104:105], 1, v[118:119]
	v_or_b32_e32 v104, 0x100, v104
	v_cvt_pk_bf16_f32 v100, v56, v57
	v_cvt_pk_bf16_f32 v101, v58, v59
	v_cvt_pk_bf16_f32 v102, v52, v53
	v_cvt_pk_bf16_f32 v103, v54, v55
	v_lshl_add_u64 v[104:105], s[84:85], 0, v[104:105]
	global_store_dwordx4 v[104:105], v[100:103], off

.LBB0_520:
	s_or_b64 exec, exec, s[24:25]
	v_or_b32_e32 v100, 48, v148
	v_ashrrev_i32_e32 v101, 31, v100
	s_waitcnt lgkmcnt(0)
	v_lshlrev_b64 v[52:53], 12, v[100:101]
	v_lshl_add_u64 v[52:53], s[16:17], 0, v[52:53]
	v_lshl_add_u64 v[56:57], v[196:197], 2, v[52:53]
	global_load_dwordx4 v[60:63], v[56:57], off offset:16
	global_load_dwordx4 v[64:67], v[56:57], off
	global_load_dwordx4 v[52:55], v[56:57], off offset:528
	s_nop 0
	global_load_dwordx4 v[56:59], v[56:57], off offset:512
	v_or_b32_e32 v102, 16, v148
	v_ashrrev_i32_e32 v103, 31, v102
	v_lshlrev_b64 v[104:105], 10, v[102:103]
	v_lshl_add_u64 v[104:105], v[104:105], 0, v[196:197]
	v_mov_b32_e32 v189, v188
	s_waitcnt vmcnt(19)
	v_fma_f32 v50, v188, v50, v98
	v_fma_f32 v51, v189, v51, v99
	v_fma_f32 v48, v190, v48, v96
	v_fma_f32 v49, v191, v49, v97
	s_waitcnt vmcnt(17)
	v_fma_f32 v46, v188, v46, v94
	v_fma_f32 v47, v189, v47, v95
	v_fma_f32 v44, v190, v44, v92
	v_fma_f32 v45, v191, v45, v93
	v_lshl_add_u64 v[92:93], v[104:105], 2, s[22:23]
	s_and_b64 vcc, exec, s[8:9]
	global_store_dwordx4 v[92:93], v[48:51], off nt
	global_store_dwordx4 v[92:93], v[44:47], off offset:16 nt
	s_cbranch_vccnz .LBB0_522
	v_cvt_pk_bf16_f32 v94, v48, v49
	v_cvt_pk_bf16_f32 v95, v50, v51
	v_cvt_pk_bf16_f32 v96, v44, v45
	v_cvt_pk_bf16_f32 v97, v46, v47
	v_lshl_add_u64 v[98:99], v[104:105], 1, s[84:85]
	global_store_dwordx4 v[98:99], v[94:97], off
.LBB0_522:
	s_waitcnt vmcnt(18)
	v_fma_f32 v42, v188, v42, v90
	v_fma_f32 v43, v189, v43, v91
	v_fma_f32 v40, v190, v40, v88
	v_fma_f32 v41, v191, v41, v89
	v_fma_f32 v38, v188, v38, v86
	v_fma_f32 v39, v189, v39, v87
	v_fma_f32 v36, v190, v36, v84
	v_fma_f32 v37, v191, v37, v85
	s_and_b64 vcc, exec, s[8:9]
	global_store_dwordx4 v[92:93], v[40:43], off offset:512 nt
	global_store_dwordx4 v[92:93], v[36:39], off offset:528 nt
	s_cbranch_vccnz .LBB0_524
	v_lshlrev_b64 v[88:89], 1, v[104:105]
	v_or_b32_e32 v88, 0x100, v88
	v_cvt_pk_bf16_f32 v84, v40, v41
	v_cvt_pk_bf16_f32 v85, v42, v43
	v_cvt_pk_bf16_f32 v86, v36, v37
	v_cvt_pk_bf16_f32 v87, v38, v39
	v_lshl_add_u64 v[88:89], s[84:85], 0, v[88:89]
	global_store_dwordx4 v[88:89], v[84:87], off

.LBB0_526:
	s_or_b64 exec, exec, s[24:25]
	s_waitcnt lgkmcnt(0)
	v_lshlrev_b64 v[36:37], 10, v[116:117]
	v_lshl_add_u64 v[36:37], v[36:37], 0, v[196:197]
	v_mov_b32_e32 v189, v188
	s_waitcnt vmcnt(14)
	v_fma_f32 v34, v188, v34, v82
	v_fma_f32 v35, v189, v35, v83
	v_fma_f32 v32, v190, v32, v80
	v_fma_f32 v33, v191, v33, v81
	v_fma_f32 v30, v188, v30, v78
	v_fma_f32 v31, v189, v31, v79
	v_fma_f32 v28, v190, v28, v76
	v_fma_f32 v29, v191, v29, v77
	v_lshl_add_u64 v[38:39], v[36:37], 2, s[22:23]
	s_and_b64 vcc, exec, s[8:9]
	global_store_dwordx4 v[38:39], v[32:35], off nt
	global_store_dwordx4 v[38:39], v[28:31], off offset:16 nt
	s_cbranch_vccnz .LBB0_528
	v_cvt_pk_bf16_f32 v40, v32, v33
	v_cvt_pk_bf16_f32 v41, v34, v35
	v_cvt_pk_bf16_f32 v42, v28, v29
	v_cvt_pk_bf16_f32 v43, v30, v31
	v_lshl_add_u64 v[44:45], v[36:37], 1, s[84:85]
	global_store_dwordx4 v[44:45], v[40:43], off
.LBB0_528:
	s_waitcnt vmcnt(14)
	v_fma_f32 v26, v188, v26, v74
	v_fma_f32 v27, v189, v27, v75
	v_fma_f32 v24, v190, v24, v72
	v_fma_f32 v25, v191, v25, v73
	v_fma_f32 v22, v188, v22, v70
	v_fma_f32 v23, v189, v23, v71
	v_fma_f32 v20, v190, v20, v68
	v_fma_f32 v21, v191, v21, v69
	s_and_b64 vcc, exec, s[8:9]
	global_store_dwordx4 v[38:39], v[24:27], off offset:512 nt
	global_store_dwordx4 v[38:39], v[20:23], off offset:528 nt
	s_cbranch_vccnz .LBB0_530
	v_lshlrev_b64 v[40:41], 1, v[36:37]
	v_or_b32_e32 v40, 0x100, v40
	v_cvt_pk_bf16_f32 v36, v24, v25
	v_cvt_pk_bf16_f32 v37, v26, v27
	v_cvt_pk_bf16_f32 v38, v20, v21
	v_cvt_pk_bf16_f32 v39, v22, v23
	v_lshl_add_u64 v[40:41], s[84:85], 0, v[40:41]
	global_store_dwordx4 v[40:41], v[36:39], off

.LBB0_532:
	s_or_b64 exec, exec, s[24:25]
	s_waitcnt lgkmcnt(0)
	v_lshlrev_b64 v[20:21], 10, v[100:101]
	v_lshl_add_u64 v[20:21], v[20:21], 0, v[196:197]
	v_mov_b32_e32 v189, v188
	s_waitcnt vmcnt(10)
	v_fma_f32 v18, v188, v18, v66
	v_fma_f32 v19, v189, v19, v67
	v_fma_f32 v16, v190, v16, v64
	v_fma_f32 v17, v191, v17, v65
	v_fma_f32 v14, v188, v14, v62
	v_fma_f32 v15, v189, v15, v63
	v_fma_f32 v12, v190, v12, v60
	v_fma_f32 v13, v191, v13, v61
	v_lshl_add_u64 v[22:23], v[20:21], 2, s[22:23]
	s_and_b64 vcc, exec, s[8:9]
	global_store_dwordx4 v[22:23], v[16:19], off nt
	global_store_dwordx4 v[22:23], v[12:15], off offset:16 nt
	s_cbranch_vccnz .LBB0_534
	v_cvt_pk_bf16_f32 v24, v16, v17
	v_cvt_pk_bf16_f32 v25, v18, v19
	v_cvt_pk_bf16_f32 v26, v12, v13
	v_cvt_pk_bf16_f32 v27, v14, v15
	v_lshl_add_u64 v[28:29], v[20:21], 1, s[84:85]
	global_store_dwordx4 v[28:29], v[24:27], off
.LBB0_534:
	s_waitcnt vmcnt(10)
	v_fma_f32 v10, v188, v10, v58
	v_fma_f32 v11, v189, v11, v59
	v_fma_f32 v8, v190, v8, v56
	v_fma_f32 v9, v191, v9, v57
	v_fma_f32 v6, v188, v6, v54
	v_fma_f32 v7, v189, v7, v55
	v_fma_f32 v4, v190, v4, v52
	v_fma_f32 v5, v191, v5, v53
	s_and_b64 vcc, exec, s[8:9]
	global_store_dwordx4 v[22:23], v[8:11], off offset:512 nt
	global_store_dwordx4 v[22:23], v[4:7], off offset:528 nt
	s_cbranch_vccnz .LBB0_536
	v_lshlrev_b64 v[24:25], 1, v[20:21]
	v_or_b32_e32 v24, 0x100, v24
	v_cvt_pk_bf16_f32 v20, v8, v9
	v_cvt_pk_bf16_f32 v21, v10, v11
	v_cvt_pk_bf16_f32 v22, v4, v5
	v_cvt_pk_bf16_f32 v23, v6, v7
	v_lshl_add_u64 v[24:25], s[84:85], 0, v[24:25]
	global_store_dwordx4 v[24:25], v[20:23], off

.LBB0_594:
	v_lshl_add_u32 v146, s41, 8, v150
	v_ashrrev_i32_e32 v147, 31, v146
	v_lshl_add_u64 v[148:149], v[146:147], 2, s[18:19]
	global_load_dword v161, v[148:149], off
	global_load_dword v147, v[148:149], off offset:640
	v_or_b32_e32 v144, 16, v146
	v_ashrrev_i32_e32 v145, 31, v144
	v_lshl_add_u64 v[140:141], v[144:145], 2, s[18:19]
	global_load_dword v164, v[140:141], off
	v_or_b32_e32 v142, 32, v146
	v_ashrrev_i32_e32 v143, 31, v142
	v_lshl_add_u64 v[140:141], v[142:143], 2, s[18:19]
	global_load_dword v159, v[140:141], off
	global_load_dword v157, v[148:149], off offset:512
	global_load_dword v143, v[148:149], off offset:704
	v_mul_f32_e32 v124, v128, v124
	v_mul_f32_e32 v125, v129, v125
	v_or_b32_e32 v140, 48, v146
	v_ashrrev_i32_e32 v141, 31, v140
	v_mul_f32_e32 v126, v130, v126
	v_mul_f32_e32 v127, v131, v127
	v_lshl_add_u64 v[154:155], v[140:141], 2, s[18:19]
	global_load_dword v158, v[154:155], off
	v_mul_f32_e32 v116, v120, v116
	v_mul_f32_e32 v117, v121, v117
	v_mul_f32_e32 v118, v122, v118
	v_mul_f32_e32 v119, v123, v119
	global_load_dword v155, v[148:149], off offset:576
	v_lshl_or_b32 v148, s40, 7, v152
	v_ashrrev_i32_e32 v149, 31, v148
	v_mul_f32_e32 v114, v110, v114
	v_mul_f32_e32 v115, v111, v115
	v_mul_f32_e32 v100, v104, v100
	v_mul_f32_e32 v101, v105, v101
	v_mul_f32_e32 v102, v106, v102
	v_mul_f32_e32 v103, v107, v103
	v_mul_f32_e32 v92, v96, v92
	v_mul_f32_e32 v93, v97, v93
	v_mul_f32_e32 v94, v98, v94
	v_mul_f32_e32 v95, v99, v95
	v_mul_f32_e32 v84, v88, v84
	v_mul_f32_e32 v85, v89, v85
	v_mul_f32_e32 v86, v90, v86
	v_mul_f32_e32 v87, v91, v87
	v_mul_f32_e32 v76, v80, v76
	v_mul_f32_e32 v77, v81, v77
	v_mul_f32_e32 v78, v82, v78
	v_mul_f32_e32 v79, v83, v79
	v_mul_f32_e32 v68, v72, v68
	v_mul_f32_e32 v69, v73, v69
	v_mul_f32_e32 v70, v74, v70
	v_mul_f32_e32 v71, v75, v71
	v_mul_f32_e32 v60, v64, v60
	v_mul_f32_e32 v61, v65, v61
	v_mul_f32_e32 v62, v66, v62
	v_mul_f32_e32 v63, v67, v63
	v_mul_f32_e32 v52, v56, v52
	v_mul_f32_e32 v53, v57, v53
	v_mul_f32_e32 v54, v58, v54
	v_mul_f32_e32 v55, v59, v55
	v_add_u32_e32 v156, 0x80, v146
	v_mul_f32_e32 v44, v48, v44
	v_mul_f32_e32 v45, v49, v45
	v_mul_f32_e32 v46, v50, v46
	v_mul_f32_e32 v47, v51, v47
	v_mul_f32_e32 v36, v40, v36
	v_mul_f32_e32 v37, v41, v37
	v_mul_f32_e32 v38, v42, v38
	v_mul_f32_e32 v39, v43, v39
	v_add_u32_e32 v154, 0x90, v146
	v_mul_f32_e32 v28, v32, v28
	v_mul_f32_e32 v29, v33, v29
	v_mul_f32_e32 v30, v34, v30
	v_mul_f32_e32 v31, v35, v31
	v_mul_f32_e32 v20, v24, v20
	v_mul_f32_e32 v21, v25, v21
	v_mul_f32_e32 v22, v26, v22
	v_mul_f32_e32 v23, v27, v23
	v_add_u32_e32 v145, 0xa0, v146
	v_mul_f32_e32 v12, v16, v12
	v_mul_f32_e32 v13, v17, v13
	v_mul_f32_e32 v14, v18, v14
	v_mul_f32_e32 v15, v19, v15
	v_mul_f32_e32 v4, v8, v4
	v_mul_f32_e32 v5, v9, v5
	v_mul_f32_e32 v6, v10, v6
	v_mul_f32_e32 v7, v11, v7
	v_add_u32_e32 v141, 0xb0, v146
	s_andn2_b64 vcc, exec, s[4:5]
	s_waitcnt vmcnt(0)
	v_mul_f32_e32 v160, v161, v161
	v_mul_f32_e32 v161, 0xbfb8aa3b, v161
	v_mul_f32_e32 v162, v128, v161
	v_mul_f32_e32 v163, v129, v161
	v_mul_f32_e32 v128, v130, v161
	v_mul_f32_e32 v129, v131, v161
	v_exp_f32_e32 v128, v128
	v_exp_f32_e32 v129, v129
	v_mul_f32_e32 v126, v126, v160
	v_mul_f32_e32 v127, v127, v160
	v_exp_f32_e32 v162, v162
	v_add_f32_e32 v128, 1.0, v128
	v_add_f32_e32 v129, 1.0, v129
	v_rcp_f32_e32 v128, v128
	v_rcp_f32_e32 v129, v129
	v_exp_f32_e32 v163, v163
	v_add_f32_e32 v162, 1.0, v162
	v_rcp_f32_e32 v162, v162
	v_mul_f32_e32 v126, v126, v128
	v_mul_f32_e32 v127, v127, v129
	v_mul_f32_e32 v128, v120, v161
	v_mul_f32_e32 v129, v121, v161
	v_exp_f32_e32 v128, v128
	v_exp_f32_e32 v129, v129
	v_mul_f32_e32 v120, v122, v161
	v_mul_f32_e32 v121, v123, v161
	v_exp_f32_e32 v120, v120
	v_exp_f32_e32 v121, v121
	v_add_f32_e32 v128, 1.0, v128
	v_add_f32_e32 v129, 1.0, v129
	v_add_f32_e32 v163, 1.0, v163
	v_rcp_f32_e32 v128, v128
	v_rcp_f32_e32 v129, v129
	v_add_f32_e32 v120, 1.0, v120
	v_add_f32_e32 v121, 1.0, v121
	v_rcp_f32_e32 v163, v163
	v_rcp_f32_e32 v120, v120
	v_rcp_f32_e32 v121, v121
	v_mul_f32_e32 v116, v116, v160
	v_mul_f32_e32 v117, v117, v160
	v_mul_f32_e32 v124, v124, v160
	v_mul_f32_e32 v125, v125, v160
	v_mul_f32_e32 v116, v116, v128
	v_mul_f32_e32 v117, v117, v129
	v_mul_f32_e32 v118, v118, v160
	v_mul_f32_e32 v119, v119, v160
	v_mul_f32_e32 v124, v124, v162
	v_mul_f32_e32 v125, v125, v163
	v_mul_f32_e32 v118, v118, v120
	v_mul_f32_e32 v119, v119, v121
	v_cvt_pk_bf16_f32 v122, v116, v117
	v_mov_b64_e32 v[116:117], s[88:89]
	v_cvt_pk_bf16_f32 v120, v124, v125
	v_cvt_pk_bf16_f32 v123, v118, v119
	v_mad_i64_i32 v[124:125], s[16:17], v146, s91, v[116:117]
	v_lshlrev_b64 v[118:119], 1, v[148:149]
	v_cvt_pk_bf16_f32 v121, v126, v127
	v_lshl_add_u64 v[124:125], v[124:125], 0, v[118:119]
	global_store_dwordx4 v[124:125], v[120:123], off
	s_nop 1
	v_mul_f32_e32 v121, 0xbfb8aa3b, v164
	v_mul_f32_e32 v110, v110, v121
	v_mul_f32_e32 v111, v111, v121
	v_exp_f32_e32 v110, v110
	v_exp_f32_e32 v111, v111
	v_mul_f32_e32 v120, v164, v164
	v_mul_f32_e32 v122, v108, v121
	v_add_f32_e32 v110, 1.0, v110
	v_add_f32_e32 v111, 1.0, v111
	v_rcp_f32_e32 v110, v110
	v_rcp_f32_e32 v111, v111
	v_mul_f32_e32 v123, v109, v121
	v_mul_f32_e32 v108, v108, v112
	v_mul_f32_e32 v109, v109, v113
	v_mul_f32_e32 v112, v114, v120
	v_mul_f32_e32 v113, v115, v120
	v_mul_f32_e32 v100, v100, v120
	v_mul_f32_e32 v101, v101, v120
	v_mul_f32_e32 v110, v112, v110
	v_mul_f32_e32 v111, v113, v111
	v_mul_f32_e32 v112, v104, v121
	v_mul_f32_e32 v113, v105, v121
	v_exp_f32_e32 v112, v112
	v_exp_f32_e32 v113, v113
	v_exp_f32_e32 v122, v122
	v_exp_f32_e32 v123, v123
	v_add_f32_e32 v112, 1.0, v112
	v_add_f32_e32 v113, 1.0, v113
	v_rcp_f32_e32 v112, v112
	v_rcp_f32_e32 v113, v113
	v_add_f32_e32 v122, 1.0, v122
	v_add_f32_e32 v123, 1.0, v123
	v_rcp_f32_e32 v122, v122
	v_mul_f32_e32 v104, v100, v112
	v_mul_f32_e32 v105, v101, v113
	v_mul_f32_e32 v100, v106, v121
	v_mul_f32_e32 v101, v107, v121
	v_exp_f32_e32 v100, v100
	v_exp_f32_e32 v101, v101
	v_rcp_f32_e32 v123, v123
	v_mul_f32_e32 v108, v108, v120
	v_mul_f32_e32 v109, v109, v120
	v_add_f32_e32 v100, 1.0, v100
	v_add_f32_e32 v101, 1.0, v101
	v_rcp_f32_e32 v100, v100
	v_rcp_f32_e32 v101, v101
	v_mul_f32_e32 v102, v102, v120
	v_mul_f32_e32 v103, v103, v120
	v_mul_f32_e32 v108, v108, v122
	v_mul_f32_e32 v109, v109, v123
	v_mul_f32_e32 v106, v102, v100
	v_mul_f32_e32 v107, v103, v101
	v_cvt_pk_bf16_f32 v102, v104, v105
	v_mad_i64_i32 v[104:105], s[16:17], v144, s91, v[116:117]
	v_cvt_pk_bf16_f32 v100, v108, v109
	v_cvt_pk_bf16_f32 v101, v110, v111
	v_cvt_pk_bf16_f32 v103, v106, v107
	v_lshl_add_u64 v[104:105], v[104:105], 0, v[118:119]
	global_store_dwordx4 v[104:105], v[100:103], off
	s_nop 1
	v_mul_f32_e32 v101, 0xbfb8aa3b, v159
	v_mul_f32_e32 v102, v96, v101
	v_mul_f32_e32 v103, v97, v101
	v_mul_f32_e32 v96, v98, v101
	v_mul_f32_e32 v97, v99, v101
	v_exp_f32_e32 v96, v96
	v_exp_f32_e32 v97, v97
	v_mul_f32_e32 v100, v159, v159
	v_mul_f32_e32 v94, v94, v100
	v_mul_f32_e32 v95, v95, v100
	v_add_f32_e32 v96, 1.0, v96
	v_add_f32_e32 v97, 1.0, v97
	v_rcp_f32_e32 v96, v96
	v_rcp_f32_e32 v97, v97
	v_mul_f32_e32 v84, v84, v100
	v_mul_f32_e32 v85, v85, v100
	v_exp_f32_e32 v102, v102
	v_exp_f32_e32 v103, v103
	v_mul_f32_e32 v94, v94, v96
	v_mul_f32_e32 v95, v95, v97
	v_mul_f32_e32 v96, v88, v101
	v_mul_f32_e32 v97, v89, v101
	v_exp_f32_e32 v96, v96
	v_exp_f32_e32 v97, v97
	v_add_f32_e32 v102, 1.0, v102
	v_add_f32_e32 v103, 1.0, v103
	v_add_f32_e32 v96, 1.0, v96
	v_add_f32_e32 v97, 1.0, v97
	v_rcp_f32_e32 v96, v96
	v_rcp_f32_e32 v97, v97
	v_rcp_f32_e32 v102, v102
	v_rcp_f32_e32 v103, v103
	v_mul_f32_e32 v92, v92, v100
	v_mul_f32_e32 v93, v93, v100
	v_mul_f32_e32 v88, v84, v96
	v_mul_f32_e32 v89, v85, v97
	v_mul_f32_e32 v84, v90, v101
	v_mul_f32_e32 v85, v91, v101
	v_exp_f32_e32 v84, v84
	v_exp_f32_e32 v85, v85
	v_mul_f32_e32 v86, v86, v100
	v_mul_f32_e32 v87, v87, v100
	v_mul_f32_e32 v92, v92, v102
	v_mul_f32_e32 v93, v93, v103
	v_add_f32_e32 v84, 1.0, v84
	v_add_f32_e32 v85, 1.0, v85
	v_rcp_f32_e32 v84, v84
	v_rcp_f32_e32 v85, v85
	s_nop 0
	v_mul_f32_e32 v90, v86, v84
	v_mul_f32_e32 v91, v87, v85
	v_cvt_pk_bf16_f32 v86, v88, v89
	v_mad_i64_i32 v[88:89], s[16:17], v142, s91, v[116:117]
	v_cvt_pk_bf16_f32 v84, v92, v93
	v_cvt_pk_bf16_f32 v85, v94, v95
	v_cvt_pk_bf16_f32 v87, v90, v91
	v_lshl_add_u64 v[88:89], v[88:89], 0, v[118:119]
	global_store_dwordx4 v[88:89], v[84:87], off
	s_nop 1
	v_mul_f32_e32 v85, 0xbfb8aa3b, v158
	v_mul_f32_e32 v86, v80, v85
	v_mul_f32_e32 v87, v81, v85
	v_mul_f32_e32 v80, v82, v85
	v_mul_f32_e32 v81, v83, v85
	v_exp_f32_e32 v80, v80
	v_exp_f32_e32 v81, v81
	v_mul_f32_e32 v84, v158, v158
	v_mul_f32_e32 v78, v78, v84
	v_mul_f32_e32 v79, v79, v84
	v_add_f32_e32 v80, 1.0, v80
	v_add_f32_e32 v81, 1.0, v81
	v_rcp_f32_e32 v80, v80
	v_rcp_f32_e32 v81, v81
	v_mul_f32_e32 v68, v68, v84
	v_mul_f32_e32 v69, v69, v84
	v_exp_f32_e32 v86, v86
	v_exp_f32_e32 v87, v87
	v_mul_f32_e32 v78, v78, v80
	v_mul_f32_e32 v79, v79, v81
	v_mul_f32_e32 v80, v72, v85
	v_mul_f32_e32 v81, v73, v85
	v_exp_f32_e32 v80, v80
	v_exp_f32_e32 v81, v81
	v_add_f32_e32 v86, 1.0, v86
	v_add_f32_e32 v87, 1.0, v87
	v_add_f32_e32 v80, 1.0, v80
	v_add_f32_e32 v81, 1.0, v81
	v_rcp_f32_e32 v80, v80
	v_rcp_f32_e32 v81, v81
	v_rcp_f32_e32 v86, v86
	v_rcp_f32_e32 v87, v87
	v_mul_f32_e32 v76, v76, v84
	v_mul_f32_e32 v77, v77, v84
	v_mul_f32_e32 v72, v68, v80
	v_mul_f32_e32 v73, v69, v81
	v_mul_f32_e32 v68, v74, v85
	v_mul_f32_e32 v69, v75, v85
	v_exp_f32_e32 v68, v68
	v_exp_f32_e32 v69, v69
	v_mul_f32_e32 v70, v70, v84
	v_mul_f32_e32 v71, v71, v84
	v_mul_f32_e32 v76, v76, v86
	v_mul_f32_e32 v77, v77, v87
	v_add_f32_e32 v68, 1.0, v68
	v_add_f32_e32 v69, 1.0, v69
	v_rcp_f32_e32 v68, v68
	v_rcp_f32_e32 v69, v69
	s_nop 0
	v_mul_f32_e32 v74, v70, v68
	v_mul_f32_e32 v75, v71, v69
	v_cvt_pk_bf16_f32 v70, v72, v73
	v_mad_i64_i32 v[72:73], s[16:17], v140, s91, v[116:117]
	v_cvt_pk_bf16_f32 v68, v76, v77
	v_cvt_pk_bf16_f32 v69, v78, v79
	v_cvt_pk_bf16_f32 v71, v74, v75
	v_lshl_add_u64 v[72:73], v[72:73], 0, v[118:119]
	global_store_dwordx4 v[72:73], v[68:71], off
	s_nop 1
	v_mul_f32_e32 v69, 0xbfb8aa3b, v157
	v_mul_f32_e32 v70, v64, v69
	v_mul_f32_e32 v71, v65, v69
	v_mul_f32_e32 v64, v66, v69
	v_mul_f32_e32 v65, v67, v69
	v_exp_f32_e32 v64, v64
	v_exp_f32_e32 v65, v65
	v_mul_f32_e32 v68, v157, v157
	v_mul_f32_e32 v62, v62, v68
	v_mul_f32_e32 v63, v63, v68
	v_add_f32_e32 v64, 1.0, v64
	v_add_f32_e32 v65, 1.0, v65
	v_rcp_f32_e32 v64, v64
	v_rcp_f32_e32 v65, v65
	v_mul_f32_e32 v52, v52, v68
	v_mul_f32_e32 v53, v53, v68
	v_exp_f32_e32 v70, v70
	v_exp_f32_e32 v71, v71
	v_mul_f32_e32 v62, v62, v64
	v_mul_f32_e32 v63, v63, v65
	v_mul_f32_e32 v64, v56, v69
	v_mul_f32_e32 v65, v57, v69
	v_exp_f32_e32 v64, v64
	v_exp_f32_e32 v65, v65
	v_add_f32_e32 v70, 1.0, v70
	v_add_f32_e32 v71, 1.0, v71
	v_add_f32_e32 v64, 1.0, v64
	v_add_f32_e32 v65, 1.0, v65
	v_rcp_f32_e32 v64, v64
	v_rcp_f32_e32 v65, v65
	v_rcp_f32_e32 v70, v70
	v_rcp_f32_e32 v71, v71
	v_mul_f32_e32 v60, v60, v68
	v_mul_f32_e32 v61, v61, v68
	v_mul_f32_e32 v56, v52, v64
	v_mul_f32_e32 v57, v53, v65
	v_mul_f32_e32 v52, v58, v69
	v_mul_f32_e32 v53, v59, v69
	v_exp_f32_e32 v52, v52
	v_exp_f32_e32 v53, v53
	v_mul_f32_e32 v54, v54, v68
	v_mul_f32_e32 v55, v55, v68
	v_mul_f32_e32 v60, v60, v70
	v_mul_f32_e32 v61, v61, v71
	v_add_f32_e32 v52, 1.0, v52
	v_add_f32_e32 v53, 1.0, v53
	v_rcp_f32_e32 v52, v52
	v_rcp_f32_e32 v53, v53
	s_nop 0
	v_mul_f32_e32 v58, v54, v52
	v_mul_f32_e32 v59, v55, v53
	v_cvt_pk_bf16_f32 v54, v56, v57
	v_mad_i64_i32 v[56:57], s[16:17], v156, s91, v[116:117]
	v_cvt_pk_bf16_f32 v52, v60, v61
	v_cvt_pk_bf16_f32 v53, v62, v63
	v_cvt_pk_bf16_f32 v55, v58, v59
	v_lshl_add_u64 v[56:57], v[56:57], 0, v[118:119]
	global_store_dwordx4 v[56:57], v[52:55], off
	s_nop 1
	v_mul_f32_e32 v53, 0xbfb8aa3b, v155
	v_mul_f32_e32 v54, v48, v53
	v_mul_f32_e32 v55, v49, v53
	v_mul_f32_e32 v48, v50, v53
	v_mul_f32_e32 v49, v51, v53
	v_exp_f32_e32 v48, v48
	v_exp_f32_e32 v49, v49
	v_mul_f32_e32 v52, v155, v155
	v_mul_f32_e32 v46, v46, v52
	v_mul_f32_e32 v47, v47, v52
	v_add_f32_e32 v48, 1.0, v48
	v_add_f32_e32 v49, 1.0, v49
	v_rcp_f32_e32 v48, v48
	v_rcp_f32_e32 v49, v49
	v_mul_f32_e32 v36, v36, v52
	v_mul_f32_e32 v37, v37, v52
	v_exp_f32_e32 v54, v54
	v_exp_f32_e32 v55, v55
	v_mul_f32_e32 v46, v46, v48
	v_mul_f32_e32 v47, v47, v49
	v_mul_f32_e32 v48, v40, v53
	v_mul_f32_e32 v49, v41, v53
	v_exp_f32_e32 v48, v48
	v_exp_f32_e32 v49, v49
	v_add_f32_e32 v54, 1.0, v54
	v_add_f32_e32 v55, 1.0, v55
	v_add_f32_e32 v48, 1.0, v48
	v_add_f32_e32 v49, 1.0, v49
	v_rcp_f32_e32 v48, v48
	v_rcp_f32_e32 v49, v49
	v_rcp_f32_e32 v54, v54
	v_rcp_f32_e32 v55, v55
	v_mul_f32_e32 v44, v44, v52
	v_mul_f32_e32 v45, v45, v52
	v_mul_f32_e32 v40, v36, v48
	v_mul_f32_e32 v41, v37, v49
	v_mul_f32_e32 v36, v42, v53
	v_mul_f32_e32 v37, v43, v53
	v_exp_f32_e32 v36, v36
	v_exp_f32_e32 v37, v37
	v_mul_f32_e32 v38, v38, v52
	v_mul_f32_e32 v39, v39, v52
	v_mul_f32_e32 v44, v44, v54
	v_mul_f32_e32 v45, v45, v55
	v_add_f32_e32 v36, 1.0, v36
	v_add_f32_e32 v37, 1.0, v37
	v_rcp_f32_e32 v36, v36
	v_rcp_f32_e32 v37, v37
	s_nop 0
	v_mul_f32_e32 v42, v38, v36
	v_mul_f32_e32 v43, v39, v37
	v_cvt_pk_bf16_f32 v38, v40, v41
	v_mad_i64_i32 v[40:41], s[16:17], v154, s91, v[116:117]
	v_cvt_pk_bf16_f32 v36, v44, v45
	v_cvt_pk_bf16_f32 v37, v46, v47
	v_cvt_pk_bf16_f32 v39, v42, v43
	v_lshl_add_u64 v[40:41], v[40:41], 0, v[118:119]
	global_store_dwordx4 v[40:41], v[36:39], off
	s_nop 1
	v_mul_f32_e32 v37, 0xbfb8aa3b, v147
	v_mul_f32_e32 v38, v32, v37
	v_mul_f32_e32 v39, v33, v37
	v_mul_f32_e32 v32, v34, v37
	v_mul_f32_e32 v33, v35, v37
	v_exp_f32_e32 v32, v32
	v_exp_f32_e32 v33, v33
	v_mul_f32_e32 v36, v147, v147
	v_mul_f32_e32 v30, v30, v36
	v_mul_f32_e32 v31, v31, v36
	v_add_f32_e32 v32, 1.0, v32
	v_add_f32_e32 v33, 1.0, v33
	v_rcp_f32_e32 v32, v32
	v_rcp_f32_e32 v33, v33
	v_mul_f32_e32 v20, v20, v36
	v_mul_f32_e32 v21, v21, v36
	v_exp_f32_e32 v38, v38
	v_exp_f32_e32 v39, v39
	v_mul_f32_e32 v30, v30, v32
	v_mul_f32_e32 v31, v31, v33
	v_mul_f32_e32 v32, v24, v37
	v_mul_f32_e32 v33, v25, v37
	v_exp_f32_e32 v32, v32
	v_exp_f32_e32 v33, v33
	v_add_f32_e32 v38, 1.0, v38
	v_add_f32_e32 v39, 1.0, v39
	v_add_f32_e32 v32, 1.0, v32
	v_add_f32_e32 v33, 1.0, v33
	v_rcp_f32_e32 v32, v32
	v_rcp_f32_e32 v33, v33
	v_rcp_f32_e32 v38, v38
	v_rcp_f32_e32 v39, v39
	v_mul_f32_e32 v28, v28, v36
	v_mul_f32_e32 v29, v29, v36
	v_mul_f32_e32 v24, v20, v32
	v_mul_f32_e32 v25, v21, v33
	v_mul_f32_e32 v20, v26, v37
	v_mul_f32_e32 v21, v27, v37
	v_exp_f32_e32 v20, v20
	v_exp_f32_e32 v21, v21
	v_mul_f32_e32 v22, v22, v36
	v_mul_f32_e32 v23, v23, v36
	v_mul_f32_e32 v28, v28, v38
	v_mul_f32_e32 v29, v29, v39
	v_add_f32_e32 v20, 1.0, v20
	v_add_f32_e32 v21, 1.0, v21
	v_rcp_f32_e32 v20, v20
	v_rcp_f32_e32 v21, v21
	s_nop 0
	v_mul_f32_e32 v26, v22, v20
	v_mul_f32_e32 v27, v23, v21
	v_cvt_pk_bf16_f32 v22, v24, v25
	v_mad_i64_i32 v[24:25], s[16:17], v145, s91, v[116:117]
	v_cvt_pk_bf16_f32 v20, v28, v29
	v_cvt_pk_bf16_f32 v21, v30, v31
	v_cvt_pk_bf16_f32 v23, v26, v27
	v_lshl_add_u64 v[24:25], v[24:25], 0, v[118:119]
	global_store_dwordx4 v[24:25], v[20:23], off
	s_nop 1
	v_mul_f32_e32 v21, 0xbfb8aa3b, v143
	v_mul_f32_e32 v22, v16, v21
	v_mul_f32_e32 v23, v17, v21
	v_mul_f32_e32 v16, v18, v21
	v_mul_f32_e32 v17, v19, v21
	v_exp_f32_e32 v16, v16
	v_exp_f32_e32 v17, v17
	v_mul_f32_e32 v20, v143, v143
	v_mul_f32_e32 v14, v14, v20
	v_mul_f32_e32 v15, v15, v20
	v_add_f32_e32 v16, 1.0, v16
	v_add_f32_e32 v17, 1.0, v17
	v_rcp_f32_e32 v16, v16
	v_rcp_f32_e32 v17, v17
	v_mul_f32_e32 v4, v4, v20
	v_mul_f32_e32 v5, v5, v20
	v_exp_f32_e32 v22, v22
	v_exp_f32_e32 v23, v23
	v_mul_f32_e32 v14, v14, v16
	v_mul_f32_e32 v15, v15, v17
	v_mul_f32_e32 v16, v8, v21
	v_mul_f32_e32 v17, v9, v21
	v_exp_f32_e32 v16, v16
	v_exp_f32_e32 v17, v17
	v_add_f32_e32 v22, 1.0, v22
	v_add_f32_e32 v23, 1.0, v23
	v_add_f32_e32 v16, 1.0, v16
	v_add_f32_e32 v17, 1.0, v17
	v_rcp_f32_e32 v16, v16
	v_rcp_f32_e32 v17, v17
	v_rcp_f32_e32 v22, v22
	v_rcp_f32_e32 v23, v23
	v_mul_f32_e32 v12, v12, v20
	v_mul_f32_e32 v13, v13, v20
	v_mul_f32_e32 v8, v4, v16
	v_mul_f32_e32 v9, v5, v17
	v_mul_f32_e32 v4, v10, v21
	v_mul_f32_e32 v5, v11, v21
	v_exp_f32_e32 v4, v4
	v_exp_f32_e32 v5, v5
	v_mul_f32_e32 v6, v6, v20
	v_mul_f32_e32 v7, v7, v20
	v_mul_f32_e32 v12, v12, v22
	v_mul_f32_e32 v13, v13, v23
	v_add_f32_e32 v4, 1.0, v4
	v_add_f32_e32 v5, 1.0, v5
	v_rcp_f32_e32 v4, v4
	v_rcp_f32_e32 v5, v5
	s_nop 0
	v_mul_f32_e32 v10, v6, v4
	v_mul_f32_e32 v11, v7, v5
	v_cvt_pk_bf16_f32 v6, v8, v9
	v_mad_i64_i32 v[8:9], s[16:17], v141, s91, v[116:117]
	v_cvt_pk_bf16_f32 v4, v12, v13
	v_cvt_pk_bf16_f32 v5, v14, v15
	v_cvt_pk_bf16_f32 v7, v10, v11
	v_lshl_add_u64 v[8:9], v[8:9], 0, v[118:119]
	s_mov_b64 s[16:17], -1
	global_store_dwordx4 v[8:9], v[4:7], off
	s_cbranch_vccnz .LBB0_587
	s_andn2_b64 vcc, exec, s[0:1]
	s_cbranch_vccnz .LBB0_586
	s_barrier
	s_branch .LBB0_586

.LBB0_598:
	s_cmp_eq_u32 s26, 0
	s_cbranch_scc1 .LBB0_805
	s_abs_i32 s0, s27
	v_cvt_f32_u32_e32 v0, s0
	s_sub_i32 s1, 0, s0
	v_rcp_iflag_f32_e32 v0, v0
	s_nop 0
	v_mul_f32_e32 v0, 0x4f7ffffe, v0
	v_cvt_u32_f32_e32 v0, v0
	s_nop 0
	v_readfirstlane_b32 s4, v0
	s_mul_i32 s1, s1, s4
	s_mul_hi_u32 s1, s4, s1
	s_add_i32 s4, s4, s1
	s_mul_hi_u32 s1, s4, 0x580
	s_mul_i32 s1, s1, s0
	s_sub_i32 s1, 0x580, s1
	s_sub_i32 s4, s1, s0
	s_cmp_ge_u32 s1, s0
	s_cselect_b32 s1, s4, s1
	s_sub_i32 s4, s1, s0
	s_cmp_ge_u32 s1, s0
	s_cselect_b32 s0, s4, s1
	s_cmp_eq_u32 s0, 0
	s_cselect_b64 s[4:5], -1, 0
	s_cmp_lt_i32 s66, s0
	s_cselect_b64 s[6:7], -1, 0
	s_or_b64 s[4:5], s[4:5], s[6:7]
	s_and_b64 vcc, exec, s[4:5]
	s_cbranch_vccnz .LBB0_805
	s_sub_i32 s20, s66, s0
	s_sub_i32 s44, s27, s0
	s_cmp_lt_i32 s26, 2
	s_mov_b64 s[0:1], -1
	s_cbranch_scc1 .LBB0_774
	s_cmp_lt_i32 s26, 3
	s_cbranch_scc1 .LBB0_721
	s_cmp_lg_u32 s26, 3
	s_cbranch_scc0 .LBB0_609
	v_mov_b32_e32 v19, v173
	s_cmpk_gt_i32 s20, 0x2bf
	s_movk_i32 s22, 0x5800
	s_cbranch_scc1 .LBB0_608
	v_readlane_b32 s0, v254, 34
	v_readlane_b32 s1, v254, 35
	s_add_u32 s0, s0, 0x4200000
	s_addc_u32 s1, s1, 0
	v_readlane_b32 s4, v254, 32
	v_readlane_b32 s5, v254, 33
	s_add_u32 s4, s4, 0x3000
	s_addc_u32 s5, s5, 0
	v_readlane_b32 s6, v254, 48
	s_sext_i32_i16 s8, s20
	v_readlane_b32 s7, v254, 49
	s_add_u32 s6, s6, 0x2100000
	s_mulk_i32 s8, 0xba3
	s_addc_u32 s7, s7, 0
	s_lshr_b32 s9, s8, 31
	s_ashr_i32 s8, s8, 17
	s_add_i32 s9, s8, s9
	s_lshl_b32 s8, s9, 6
	s_mul_i32 s9, s9, 44
	s_sub_i32 s10, s20, s9
	s_sext_i32_i16 s11, s10
	s_lshl_b32 s9, s11, 7
	s_bfe_i32 s10, s10, 0x10000
	s_lshl_b32 s11, s11, 6
	v_lshlrev_b32_e32 v0, 2, v19
	s_and_b32 s10, s10, 0xb00
	s_and_b32 s11, s11, 0xffffff80
	v_and_b32_e32 v20, 64, v0
	s_add_i32 s10, s10, s11
	v_and_b32_e32 v18, 60, v0
	v_ashrrev_i32_e32 v21, 5, v19
	v_or_b32_e32 v0, s10, v20
	v_add_u32_e32 v8, s8, v21
	v_mov_b64_e32 v[16:17], s[0:1]
	v_ashrrev_i32_e32 v1, 31, v0
	v_mad_i64_i32 v[4:5], s[10:11], v8, s22, v[16:17]
	v_lshlrev_b64 v[26:27], 2, v[0:1]
	v_lshl_add_u64 v[0:1], v[4:5], 0, v[26:27]
	v_lshlrev_b32_e32 v2, 2, v18
	v_ashrrev_i32_e32 v9, 31, v8
	v_lshl_add_u64 v[0:1], v[0:1], 0, v[2:3]
	global_load_dwordx4 v[4:7], v[0:1], off
	v_lshl_add_u64 v[0:1], v[8:9], 2, s[4:5]
	global_load_dword v8, v[0:1], off
	s_lshl_b32 s12, s44, 7
	s_lshl_b32 s14, s44, 6
	v_lshlrev_b32_e32 v18, 2, v18
	s_mov_b32 s15, s20
	s_mov_b32 s16, s9
	s_waitcnt vmcnt(0)
	v_mul_f32_e32 v0, v6, v8
	v_mul_f32_e32 v1, v7, v8
	v_add_u32_e32 v6, 0x200, v19
	v_ashrrev_i32_e32 v22, 5, v6
	v_add_u32_e32 v6, s8, v22
	v_mul_f32_e32 v4, v4, v8
	v_mul_f32_e32 v5, v5, v8
	v_mad_i64_i32 v[8:9], s[10:11], v6, s22, v[16:17]
	v_ashrrev_i32_e32 v7, 31, v6
	v_lshl_add_u64 v[8:9], v[8:9], 0, v[26:27]
	v_lshl_add_u64 v[8:9], v[8:9], 0, v[2:3]
	v_lshl_add_u64 v[6:7], v[6:7], 2, s[4:5]
	global_load_dwordx4 v[8:11], v[8:9], off
	s_nop 0
	global_load_dword v12, v[6:7], off
	s_waitcnt vmcnt(0)
	v_mul_f32_e32 v6, v10, v12
	v_mul_f32_e32 v7, v11, v12
	v_add_u32_e32 v10, 0x400, v19
	v_ashrrev_i32_e32 v23, 5, v10
	v_add_u32_e32 v10, s8, v23
	v_mul_f32_e32 v8, v8, v12
	v_mul_f32_e32 v9, v9, v12
	v_mad_i64_i32 v[12:13], s[10:11], v10, s22, v[16:17]
	v_ashrrev_i32_e32 v11, 31, v10
	v_lshl_add_u64 v[12:13], v[12:13], 0, v[26:27]
	v_lshl_add_u64 v[12:13], v[12:13], 0, v[2:3]
	v_lshl_add_u64 v[10:11], v[10:11], 2, s[4:5]
	global_load_dwordx4 v[12:15], v[12:13], off
	s_nop 0
	global_load_dword v24, v[10:11], off
	s_waitcnt vmcnt(0)
	v_mul_f32_e32 v10, v14, v24
	v_mul_f32_e32 v11, v15, v24
	v_add_u32_e32 v14, 0x600, v19
	v_mul_f32_e32 v12, v12, v24
	v_mul_f32_e32 v13, v13, v24
	v_ashrrev_i32_e32 v24, 5, v14
	v_add_u32_e32 v14, s8, v24
	v_mad_i64_i32 v[16:17], s[10:11], v14, s22, v[16:17]
	v_ashrrev_i32_e32 v15, 31, v14
	v_lshl_add_u64 v[16:17], v[16:17], 0, v[26:27]
	v_lshl_add_u64 v[16:17], v[16:17], 0, v[2:3]
	v_lshl_add_u64 v[14:15], v[14:15], 2, s[4:5]
	global_load_dwordx4 v[26:29], v[16:17], off
	global_load_dword v2, v[14:15], off
	s_movk_i32 s10, 0x204
	v_mul_lo_u32 v31, v24, s10
	s_waitcnt vmcnt(0)
	v_mul_f32_e32 v14, v28, v2
	v_mul_f32_e32 v15, v29, v2
	v_mul_f32_e32 v16, v26, v2
	v_mul_f32_e32 v17, v27, v2
	v_lshlrev_b32_e32 v2, 4, v19
	v_and_b32_e32 v25, 0x1f0, v2
	v_and_b32_e32 v2, 48, v2
	v_add_u32_e32 v30, 0, v25
	v_ashrrev_i32_e32 v25, 2, v19
	v_mul_u32_u24_e32 v26, 0x204, v2
	v_and_b32_e32 v19, -4, v19
	v_add3_u32 v26, 0, v26, v19
	v_mul_lo_u32 v19, v21, s10
	v_mul_lo_u32 v28, v22, s10
	v_mul_lo_u32 v29, v23, s10
	s_add_i32 s10, s20, s44
	s_lshl_b32 s11, s10, 7
	s_lshl_b32 s13, s10, 6
	v_add_u32_e32 v27, v30, v19
	v_add_u32_e32 v28, v30, v28
	v_add_u32_e32 v29, v30, v29
	v_add_u32_e32 v30, v30, v31
	v_lshlrev_b32_e32 v2, 1, v2
	s_branch .LBB0_606

.LBB0_606:
	s_cmpk_gt_i32 s10, 0x2bf
	s_mov_b32 s17, s8
	ds_write2_b32 v27, v4, v5 offset1:1
	ds_write2_b32 v27, v0, v1 offset0:2 offset1:3
	ds_write2_b32 v28, v8, v9 offset1:1
	ds_write2_b32 v28, v6, v7 offset0:2 offset1:3
	ds_write2_b32 v29, v12, v13 offset1:1
	ds_write2_b32 v29, v10, v11 offset0:2 offset1:3
	ds_write2_b32 v30, v16, v17 offset1:1
	ds_write2_b32 v30, v14, v15 offset0:2 offset1:3
	s_cbranch_scc1 .LBB0_605
	s_mul_hi_i32 s16, s10, 0x2e8ba2e9
	s_lshr_b32 s17, s16, 31
	s_ashr_i32 s16, s16, 3
	s_add_i32 s18, s16, s17
	s_lshl_b32 s17, s18, 6
	s_mul_i32 s16, s18, 0xffffea00
	s_mulk_i32 s18, 0xf500
	s_bfe_i32 s19, s10, 0x10000
	s_add_i32 s18, s13, s18
	s_and_b32 s19, s19, 0xb00
	s_and_b32 s18, s18, 0xffffff80
	s_add_i32 s19, s19, s18
	v_or_b32_e32 v0, s19, v20
	v_add_u32_e32 v8, s17, v21
	v_mov_b64_e32 v[16:17], s[0:1]
	v_ashrrev_i32_e32 v1, 31, v0
	v_mad_i64_i32 v[4:5], s[18:19], v8, s22, v[16:17]
	v_lshlrev_b64 v[32:33], 2, v[0:1]
	v_lshl_add_u64 v[0:1], v[4:5], 0, v[32:33]
	v_mov_b32_e32 v19, v3
	v_ashrrev_i32_e32 v9, 31, v8
	v_lshl_add_u64 v[0:1], v[0:1], 0, v[18:19]
	global_load_dwordx4 v[4:7], v[0:1], off
	v_lshl_add_u64 v[0:1], v[8:9], 2, s[4:5]
	global_load_dword v8, v[0:1], off
	s_add_i32 s16, s11, s16
	s_waitcnt vmcnt(0)
	v_mul_f32_e32 v0, v6, v8
	v_mul_f32_e32 v1, v7, v8
	v_add_u32_e32 v6, s17, v22
	v_mul_f32_e32 v4, v4, v8
	v_mul_f32_e32 v5, v5, v8
	v_mad_i64_i32 v[8:9], s[18:19], v6, s22, v[16:17]
	v_ashrrev_i32_e32 v7, 31, v6
	v_lshl_add_u64 v[8:9], v[8:9], 0, v[32:33]
	v_lshl_add_u64 v[8:9], v[8:9], 0, v[18:19]
	v_lshl_add_u64 v[6:7], v[6:7], 2, s[4:5]
	global_load_dwordx4 v[8:11], v[8:9], off
	s_nop 0
	global_load_dword v12, v[6:7], off
	s_waitcnt vmcnt(0)
	v_mul_f32_e32 v6, v10, v12
	v_mul_f32_e32 v7, v11, v12
	v_add_u32_e32 v10, s17, v23
	v_mul_f32_e32 v8, v8, v12
	v_mul_f32_e32 v9, v9, v12
	v_mad_i64_i32 v[12:13], s[18:19], v10, s22, v[16:17]
	v_ashrrev_i32_e32 v11, 31, v10
	v_lshl_add_u64 v[12:13], v[12:13], 0, v[32:33]
	v_lshl_add_u64 v[12:13], v[12:13], 0, v[18:19]
	v_lshl_add_u64 v[10:11], v[10:11], 2, s[4:5]
	global_load_dwordx4 v[12:15], v[12:13], off
	s_nop 0
	global_load_dword v34, v[10:11], off
	s_waitcnt vmcnt(0)
	v_mul_f32_e32 v10, v14, v34
	v_mul_f32_e32 v11, v15, v34
	v_add_u32_e32 v14, s17, v24
	v_mad_i64_i32 v[16:17], s[18:19], v14, s22, v[16:17]
	v_ashrrev_i32_e32 v15, 31, v14
	v_lshl_add_u64 v[16:17], v[16:17], 0, v[32:33]
	v_lshl_add_u64 v[16:17], v[16:17], 0, v[18:19]
	v_lshl_add_u64 v[14:15], v[14:15], 2, s[4:5]
	v_mul_f32_e32 v12, v12, v34
	v_mul_f32_e32 v13, v13, v34
	global_load_dwordx4 v[32:35], v[16:17], off
	s_nop 0
	global_load_dword v16, v[14:15], off
	s_waitcnt vmcnt(0)
	v_mul_f32_e32 v14, v34, v16
	v_mul_f32_e32 v15, v35, v16
	v_mul_f32_e32 v17, v33, v16
	v_mul_f32_e32 v16, v32, v16
	s_branch .LBB0_605

.LBB0_626:
	s_or_b64 exec, exec, s[18:19]
	v_mov_b32_e32 v4, 0
	v_ashrrev_i32_e32 v26, 5, v22
	v_mov_b32_e32 v5, v4
	v_mov_b32_e32 v6, v4
	v_mov_b32_e32 v7, v4
	s_and_saveexec_b64 s[18:19], s[22:23]
	s_cbranch_execz .LBB0_631
	v_mov_b32_e32 v7, 0
	v_mov_b32_e32 v6, 0
	v_mov_b32_e32 v5, 0
	v_mov_b32_e32 v4, 0
	s_and_saveexec_b64 s[22:23], s[24:25]
	s_cbranch_execz .LBB0_630
	v_add_u32_e32 v10, s8, v26
	v_ashrrev_i32_e32 v11, 31, v10
	v_mul_lo_u32 v1, s14, v11
	v_mul_lo_u32 v2, s15, v10
	v_mad_u64_u32 v[4:5], s[24:25], s14, v10, 0
	v_add3_u32 v5, v5, v1, v2
	v_lshl_add_u64 v[4:5], v[4:5], 2, s[10:11]
	v_ashrrev_i32_e32 v9, 31, v8
	v_lshl_add_u64 v[4:5], v[8:9], 2, v[4:5]
	v_lshlrev_b32_e32 v2, 2, v24
	v_lshl_add_u64 v[4:5], v[4:5], 0, v[2:3]
	global_load_dwordx4 v[4:7], v[4:5], off
	s_cmp_eq_u64 s[12:13], 0
	s_cbranch_scc1 .LBB0_630
	v_lshl_add_u64 v[8:9], v[10:11], 2, s[12:13]
	global_load_dword v2, v[8:9], off
	s_waitcnt vmcnt(0)
	v_mul_f32_e32 v6, v6, v2
	v_mul_f32_e32 v7, v7, v2
	v_mul_f32_e32 v4, v4, v2
	v_mul_f32_e32 v5, v5, v2

.LBB0_637:
	s_or_b64 exec, exec, s[18:19]
	v_add_u32_e32 v1, 0x200, v22
	v_mov_b32_e32 v8, 0
	v_ashrrev_i32_e32 v27, 5, v1
	v_mov_b32_e32 v9, v8
	v_mov_b32_e32 v10, v8
	v_mov_b32_e32 v11, v8
	s_and_saveexec_b64 s[18:19], s[22:23]
	s_cbranch_execz .LBB0_642
	v_mov_b32_e32 v11, 0
	v_mov_b32_e32 v10, 0
	v_mov_b32_e32 v9, 0
	v_mov_b32_e32 v8, 0
	s_and_saveexec_b64 s[22:23], s[24:25]
	s_cbranch_execz .LBB0_641
	v_add_u32_e32 v14, s8, v27
	v_ashrrev_i32_e32 v15, 31, v14
	v_mul_lo_u32 v1, s14, v15
	v_mul_lo_u32 v2, s15, v14
	v_mad_u64_u32 v[8:9], s[24:25], s14, v14, 0
	v_add3_u32 v9, v9, v1, v2
	v_lshl_add_u64 v[8:9], v[8:9], 2, s[10:11]
	v_ashrrev_i32_e32 v13, 31, v12
	v_lshl_add_u64 v[8:9], v[12:13], 2, v[8:9]
	v_lshlrev_b32_e32 v2, 2, v24
	v_lshl_add_u64 v[8:9], v[8:9], 0, v[2:3]
	global_load_dwordx4 v[8:11], v[8:9], off
	s_cmp_eq_u64 s[12:13], 0
	s_cbranch_scc1 .LBB0_641
	v_lshl_add_u64 v[12:13], v[14:15], 2, s[12:13]
	global_load_dword v2, v[12:13], off
	s_waitcnt vmcnt(0)
	v_mul_f32_e32 v10, v10, v2
	v_mul_f32_e32 v11, v11, v2
	v_mul_f32_e32 v8, v8, v2
	v_mul_f32_e32 v9, v9, v2

.LBB0_648:
	s_or_b64 exec, exec, s[18:19]
	v_add_u32_e32 v1, 0x400, v22
	v_mov_b32_e32 v12, 0
	v_ashrrev_i32_e32 v28, 5, v1
	v_mov_b32_e32 v13, v12
	v_mov_b32_e32 v14, v12
	v_mov_b32_e32 v15, v12
	s_and_saveexec_b64 s[18:19], s[22:23]
	s_cbranch_execz .LBB0_653
	v_mov_b32_e32 v15, 0
	v_mov_b32_e32 v14, 0
	v_mov_b32_e32 v13, 0
	v_mov_b32_e32 v12, 0
	s_and_saveexec_b64 s[22:23], s[24:25]
	s_cbranch_execz .LBB0_652
	v_add_u32_e32 v18, s8, v28
	v_ashrrev_i32_e32 v19, 31, v18
	v_mul_lo_u32 v1, s14, v19
	v_mul_lo_u32 v2, s15, v18
	v_mad_u64_u32 v[12:13], s[24:25], s14, v18, 0
	v_add3_u32 v13, v13, v1, v2
	v_lshl_add_u64 v[12:13], v[12:13], 2, s[10:11]
	v_ashrrev_i32_e32 v17, 31, v16
	v_lshl_add_u64 v[12:13], v[16:17], 2, v[12:13]
	v_lshlrev_b32_e32 v2, 2, v24
	v_lshl_add_u64 v[12:13], v[12:13], 0, v[2:3]
	global_load_dwordx4 v[12:15], v[12:13], off
	s_cmp_eq_u64 s[12:13], 0
	s_cbranch_scc1 .LBB0_652
	v_lshl_add_u64 v[16:17], v[18:19], 2, s[12:13]
	global_load_dword v2, v[16:17], off
	s_waitcnt vmcnt(0)
	v_mul_f32_e32 v14, v14, v2
	v_mul_f32_e32 v15, v15, v2
	v_mul_f32_e32 v12, v12, v2
	v_mul_f32_e32 v13, v13, v2

.LBB0_659:
	s_or_b64 exec, exec, s[18:19]
	v_add_u32_e32 v1, 0x600, v22
	v_ashrrev_i32_e32 v29, 5, v1
	v_mov_b32_e32 v16, 0
	v_mov_b32_e32 v17, 0
	v_mov_b32_e32 v18, 0
	v_mov_b32_e32 v19, 0
	s_and_saveexec_b64 s[16:17], s[24:25]
	s_cbranch_execz .LBB0_664
	v_mov_b32_e32 v19, 0
	v_mov_b32_e32 v18, 0
	v_mov_b32_e32 v17, 0
	v_mov_b32_e32 v16, 0
	s_and_saveexec_b64 s[18:19], s[22:23]
	s_cbranch_execz .LBB0_663
	v_add_u32_e32 v20, s8, v29
	v_ashrrev_i32_e32 v21, 31, v20
	v_mul_lo_u32 v1, s14, v21
	v_mul_lo_u32 v2, s15, v20
	v_mad_u64_u32 v[16:17], s[14:15], s14, v20, 0
	v_add3_u32 v17, v17, v1, v2
	v_lshl_add_u64 v[16:17], v[16:17], 2, s[10:11]
	v_ashrrev_i32_e32 v1, 31, v0
	v_lshl_add_u64 v[0:1], v[0:1], 2, v[16:17]
	v_lshlrev_b32_e32 v2, 2, v24
	v_lshl_add_u64 v[0:1], v[0:1], 0, v[2:3]
	global_load_dwordx4 v[16:19], v[0:1], off
	s_cmp_eq_u64 s[12:13], 0
	s_cbranch_scc1 .LBB0_663
	v_lshl_add_u64 v[0:1], v[20:21], 2, s[12:13]
	global_load_dword v0, v[0:1], off
	s_waitcnt vmcnt(0)
	v_mul_f32_e32 v18, v18, v0
	v_mul_f32_e32 v19, v19, v0
	v_mul_f32_e32 v16, v16, v0
	v_mul_f32_e32 v17, v17, v0

.LBB0_682:
	s_or_b64 exec, exec, s[36:37]
	v_mov_b32_e32 v4, 0
	v_mov_b32_e32 v5, 0
	v_mov_b32_e32 v6, 0
	v_mov_b32_e32 v7, 0
	s_and_saveexec_b64 s[36:37], s[38:39]
	s_cbranch_execz .LBB0_687
	v_mov_b32_e32 v7, 0
	v_mov_b32_e32 v6, 0
	v_mov_b32_e32 v5, 0
	v_mov_b32_e32 v4, 0
	s_and_saveexec_b64 s[38:39], s[40:41]
	s_cbranch_execz .LBB0_686
	v_add_u32_e32 v10, s54, v26
	v_ashrrev_i32_e32 v11, 31, v10
	v_mul_lo_u32 v1, s24, v11
	v_mul_lo_u32 v2, s25, v10
	v_mad_u64_u32 v[4:5], s[40:41], s24, v10, 0
	v_add3_u32 v5, v5, v1, v2
	v_lshl_add_u64 v[4:5], v[4:5], 2, s[28:29]
	v_ashrrev_i32_e32 v9, 31, v8
	v_lshl_add_u64 v[4:5], v[8:9], 2, v[4:5]
	v_lshlrev_b32_e32 v2, 2, v24
	v_lshl_add_u64 v[4:5], v[4:5], 0, v[2:3]
	global_load_dwordx4 v[4:7], v[4:5], off
	s_cmp_eq_u64 s[26:27], 0
	s_cbranch_scc1 .LBB0_686
	v_lshl_add_u64 v[8:9], v[10:11], 2, s[26:27]
	global_load_dword v2, v[8:9], off
	s_waitcnt vmcnt(0)
	v_mul_f32_e32 v6, v6, v2
	v_mul_f32_e32 v7, v7, v2
	v_mul_f32_e32 v4, v4, v2
	v_mul_f32_e32 v5, v5, v2

.LBB0_693:
	s_or_b64 exec, exec, s[36:37]
	v_mov_b32_e32 v8, 0
	v_mov_b32_e32 v9, 0
	v_mov_b32_e32 v10, 0
	v_mov_b32_e32 v11, 0
	s_and_saveexec_b64 s[36:37], s[38:39]
	s_cbranch_execz .LBB0_698
	v_mov_b32_e32 v11, 0
	v_mov_b32_e32 v10, 0
	v_mov_b32_e32 v9, 0
	v_mov_b32_e32 v8, 0
	s_and_saveexec_b64 s[38:39], s[40:41]
	s_cbranch_execz .LBB0_697
	v_add_u32_e32 v14, s54, v27
	v_ashrrev_i32_e32 v15, 31, v14
	v_mul_lo_u32 v1, s24, v15
	v_mul_lo_u32 v2, s25, v14
	v_mad_u64_u32 v[8:9], s[40:41], s24, v14, 0
	v_add3_u32 v9, v9, v1, v2
	v_lshl_add_u64 v[8:9], v[8:9], 2, s[28:29]
	v_ashrrev_i32_e32 v13, 31, v12
	v_lshl_add_u64 v[8:9], v[12:13], 2, v[8:9]
	v_lshlrev_b32_e32 v2, 2, v24
	v_lshl_add_u64 v[8:9], v[8:9], 0, v[2:3]
	global_load_dwordx4 v[8:11], v[8:9], off
	s_cmp_eq_u64 s[26:27], 0
	s_cbranch_scc1 .LBB0_697
	v_lshl_add_u64 v[12:13], v[14:15], 2, s[26:27]
	global_load_dword v2, v[12:13], off
	s_waitcnt vmcnt(0)
	v_mul_f32_e32 v10, v10, v2
	v_mul_f32_e32 v11, v11, v2
	v_mul_f32_e32 v8, v8, v2
	v_mul_f32_e32 v9, v9, v2

.LBB0_704:
	s_or_b64 exec, exec, s[36:37]
	v_mov_b32_e32 v12, 0
	v_mov_b32_e32 v13, 0
	v_mov_b32_e32 v14, 0
	v_mov_b32_e32 v15, 0
	s_and_saveexec_b64 s[36:37], s[38:39]
	s_cbranch_execz .LBB0_709
	v_mov_b32_e32 v15, 0
	v_mov_b32_e32 v14, 0
	v_mov_b32_e32 v13, 0
	v_mov_b32_e32 v12, 0
	s_and_saveexec_b64 s[38:39], s[40:41]
	s_cbranch_execz .LBB0_708
	v_add_u32_e32 v18, s54, v28
	v_ashrrev_i32_e32 v19, 31, v18
	v_mul_lo_u32 v1, s24, v19
	v_mul_lo_u32 v2, s25, v18
	v_mad_u64_u32 v[12:13], s[40:41], s24, v18, 0
	v_add3_u32 v13, v13, v1, v2
	v_lshl_add_u64 v[12:13], v[12:13], 2, s[28:29]
	v_ashrrev_i32_e32 v17, 31, v16
	v_lshl_add_u64 v[12:13], v[16:17], 2, v[12:13]
	v_lshlrev_b32_e32 v2, 2, v24
	v_lshl_add_u64 v[12:13], v[12:13], 0, v[2:3]
	global_load_dwordx4 v[12:15], v[12:13], off
	s_cmp_eq_u64 s[26:27], 0
	s_cbranch_scc1 .LBB0_708
	v_lshl_add_u64 v[16:17], v[18:19], 2, s[26:27]
	global_load_dword v2, v[16:17], off
	s_waitcnt vmcnt(0)
	v_mul_f32_e32 v14, v14, v2
	v_mul_f32_e32 v15, v15, v2
	v_mul_f32_e32 v12, v12, v2
	v_mul_f32_e32 v13, v13, v2

.LBB0_715:
	s_or_b64 exec, exec, s[36:37]
	v_mov_b32_e32 v16, 0
	v_mov_b32_e32 v17, 0
	v_mov_b32_e32 v18, 0
	v_mov_b32_e32 v19, 0
	s_and_saveexec_b64 s[30:31], s[40:41]
	s_cbranch_execz .LBB0_666
	v_mov_b32_e32 v19, 0
	v_mov_b32_e32 v18, 0
	v_mov_b32_e32 v17, 0
	v_mov_b32_e32 v16, 0
	s_and_saveexec_b64 s[36:37], s[38:39]
	s_cbranch_execz .LBB0_665
	v_add_u32_e32 v22, s54, v29
	v_ashrrev_i32_e32 v23, 31, v22
	v_mul_lo_u32 v1, s24, v23
	v_mul_lo_u32 v2, s25, v22
	v_mad_u64_u32 v[16:17], s[24:25], s24, v22, 0
	v_add3_u32 v17, v17, v1, v2
	v_lshl_add_u64 v[16:17], v[16:17], 2, s[28:29]
	v_ashrrev_i32_e32 v21, 31, v20
	v_lshl_add_u64 v[16:17], v[20:21], 2, v[16:17]
	v_lshlrev_b32_e32 v2, 2, v24
	v_lshl_add_u64 v[16:17], v[16:17], 0, v[2:3]
	global_load_dwordx4 v[16:19], v[16:17], off
	s_cmp_eq_u64 s[26:27], 0
	s_cbranch_scc1 .LBB0_665
	v_lshl_add_u64 v[20:21], v[22:23], 2, s[26:27]
	global_load_dword v2, v[20:21], off
	s_waitcnt vmcnt(0)
	v_mul_f32_e32 v18, v18, v2
	v_mul_f32_e32 v19, v19, v2
	v_mul_f32_e32 v16, v16, v2
	v_mul_f32_e32 v17, v17, v2
	s_branch .LBB0_665
